# speedup vs baseline: 1.0070x; 1.0070x over previous
; #define WAIT_V(n) asm volatile("s_waitcnt vmcnt(%0)" ::"n"(n) : "memory")
; #define WAIT_L(n) asm volatile("s_waitcnt lgkmcnt(%0)" ::"n"(n) : "memory")
; #define SBAR() __builtin_amdgcn_sched_barrier(0)
; #define STAGE(P, base, kt) do { _Pragma("unroll") for (int _i = 0; _i < 2; ++_i)                                        \
;       __builtin_amdgcn_global_load_lds((const unsigned*)((base) + (size_t)(sOff[_i] + (unsigned)(kt) * (BK * 2))),        \
;                                        (unsigned*)((P) + wid * 1024 + _i * 8192), 16, 0, 0); } while (0)
; #define LDA(dst, b, h) _Pragma("unroll") for (int m = 0; m < 4; ++m) _Pragma("unroll") for (int k = 0; k < 2; ++k) \
;       dst[m][k] = *(const bf16x8*)(SA(b, h) + aoff + (m * 2048 + k * 1024))
; #define LDB(dst, b, h) _Pragma("unroll") for (int n = 0; n < 2; ++n) _Pragma("unroll") for (int k = 0; k < 2; ++k) \
;       dst[n][k] = *(const bf16x8*)(SB(b, h) + boff + (n * 256 + k * 1024))
; #define BAR __builtin_amdgcn_s_barrier()
; template <int EPI, int N, int K>
; __device__ __forceinline__ void phase_gemm(const Params& p, const u16* __restrict__ A, const u16* __restrict__ Bt, int nM, char* shm,
;                            u16* __restrict__ outp, float* __restrict__ rowss) {
;     ...
;   for (;;) {
;     const char* A1 = A0 + (size_t)128 * K * 2;
;     const char* B1p = B0p + (size_t)128 * K * 2;
;     f32x4 acc[2][2][4][2] = {};
;     bf16x8 At[4][2], B0[2][2], B1[2][2];
;     if (wr == 1) BAR;
;     WAIT_V(0); BAR;
;     BAR;
;     for (int t = 0; t < nt - 2; t += 2) {
;       LDB(B0, 0, 0); SBAR(); LDA(At, 0, 0); STAGE(SA(1, 1), A1, t + 1);
;       WAIT_L(8); BAR; WAIT_L(0); MMA(0, 0, At, B0); BAR; SBAR();
;       LDB(B1, 0, 1); STAGE(SB(0, 0), B0p, t + 2);
;       BAR; WAIT_L(0); MMA(0, 1, At, B1); BAR;
;       LDA(At, 0, 1); STAGE(SA(0, 0), A0, t + 2);
;       BAR; WAIT_L(0); MMA(1, 0, At, B0); BAR; SBAR();
;       STAGE(SB(0, 1), B1p, t + 2);
;       WAIT_V(6); BAR; MMA(1, 1, At, B1); BAR;
.LBB0_93:
	s_add_u32 s6, s14, 0xb0000
	s_addc_u32 s7, s15, 0
	s_waitcnt vmcnt(0)
	s_add_u32 s22, s12, 0xb0000
	s_addc_u32 s23, s13, 0
	s_mov_b32 s61, -2
	v_mov_b32_e32 v96, v150
	v_mov_b32_e32 v142, v149
	s_waitcnt lgkmcnt(0)
	s_barrier
	s_barrier
	v_or_b32_e32 v143, 0x10000, v146
	v_add_u32_e32 v145, 0x10100, v146
	v_add_u32_e32 v144, 0x10400, v146
	ds_read_b128 v[156:159], v143
	ds_read_b128 v[160:163], v144
	v_add_u32_e32 v151, 0x10500, v146
	ds_read_b128 v[164:167], v145
	ds_read_b128 v[168:171], v151
	v_add_u32_e32 v240, v148, v96
	s_mov_b32 m0, s56
	v_add_u32_e32 v152, 0x80, v240
	v_add_u32_e32 v241, v148, v142
	ds_read_b128 v[172:175], v147
	ds_read_b128 v[176:179], v147 offset:1024
	ds_read_b128 v[180:183], v147 offset:2048
	ds_read_b128 v[196:199], v147 offset:3072
	ds_read_b128 v[200:203], v147 offset:4096
	ds_read_b128 v[204:207], v147 offset:5120
	ds_read_b128 v[208:211], v147 offset:6144
	ds_read_b128 v[212:215], v147 offset:7168
	global_load_lds_dwordx4 v152, s[6:7]
	v_add_u32_e32 v152, 0x80, v241
	s_mov_b32 m0, s57
	s_nop 0
	global_load_lds_dwordx4 v152, s[6:7]
	s_waitcnt lgkmcnt(8)
	s_barrier
	s_waitcnt lgkmcnt(0)
	s_setprio 1
	s_waitcnt lgkmcnt(0)
	v_mfma_f32_16x16x32_bf16 v[126:129], v[156:159], v[172:175], 0
	v_mfma_f32_16x16x32_bf16 v[122:125], v[164:167], v[172:175], 0
	v_mfma_f32_16x16x32_bf16 v[118:121], v[156:159], v[180:183], 0
	v_mfma_f32_16x16x32_bf16 v[114:117], v[164:167], v[180:183], 0
	v_mfma_f32_16x16x32_bf16 v[110:113], v[156:159], v[200:203], 0
	v_mfma_f32_16x16x32_bf16 v[106:109], v[164:167], v[200:203], 0
	v_mfma_f32_16x16x32_bf16 v[102:105], v[156:159], v[208:211], 0
	v_mfma_f32_16x16x32_bf16 v[98:101], v[164:167], v[208:211], 0
	v_mfma_f32_16x16x32_bf16 v[126:129], v[160:163], v[176:179], v[126:129]
	v_mfma_f32_16x16x32_bf16 v[122:125], v[168:171], v[176:179], v[122:125]
	v_mfma_f32_16x16x32_bf16 v[118:121], v[160:163], v[196:199], v[118:121]
	v_mfma_f32_16x16x32_bf16 v[114:117], v[168:171], v[196:199], v[114:117]
	v_mfma_f32_16x16x32_bf16 v[110:113], v[160:163], v[204:207], v[110:113]
	v_mfma_f32_16x16x32_bf16 v[106:109], v[168:171], v[204:207], v[106:109]
	v_mfma_f32_16x16x32_bf16 v[102:105], v[160:163], v[212:215], v[102:105]
	v_mfma_f32_16x16x32_bf16 v[98:101], v[168:171], v[212:215], v[98:101]
	s_setprio 0
	s_barrier
	s_mov_b32 m0, s26
	v_or_b32_e32 v152, 0x14000, v146
	v_add_u32_e32 v154, 0x14100, v146
	v_add_u32_e32 v232, 0x100, v240
	v_add_u32_e32 v153, 0x14400, v146
	ds_read_b128 v[216:219], v152
	ds_read_b128 v[220:223], v153
	v_add_u32_e32 v155, 0x14500, v146
	ds_read_b128 v[224:227], v154
	ds_read_b128 v[228:231], v155
	global_load_lds_dwordx4 v232, s[12:13]
	v_add_u32_e32 v233, 0x100, v241
	s_mov_b32 m0, s27
	s_nop 0
	global_load_lds_dwordx4 v233, s[12:13]
	s_barrier
	s_waitcnt lgkmcnt(0)
	s_setprio 1
	s_waitcnt lgkmcnt(0)
	v_mfma_f32_16x16x32_bf16 v[92:95], v[216:219], v[172:175], 0
	v_mfma_f32_16x16x32_bf16 v[88:91], v[224:227], v[172:175], 0
	v_mfma_f32_16x16x32_bf16 v[84:87], v[216:219], v[180:183], 0
	v_mfma_f32_16x16x32_bf16 v[80:83], v[224:227], v[180:183], 0
	v_mfma_f32_16x16x32_bf16 v[76:79], v[216:219], v[200:203], 0
	v_mfma_f32_16x16x32_bf16 v[72:75], v[224:227], v[200:203], 0
	v_mfma_f32_16x16x32_bf16 v[68:71], v[216:219], v[208:211], 0
	v_mfma_f32_16x16x32_bf16 v[64:67], v[224:227], v[208:211], 0
	v_mfma_f32_16x16x32_bf16 v[92:95], v[220:223], v[176:179], v[92:95]
	v_mfma_f32_16x16x32_bf16 v[88:91], v[228:231], v[176:179], v[88:91]
	v_mfma_f32_16x16x32_bf16 v[84:87], v[220:223], v[196:199], v[84:87]
	v_mfma_f32_16x16x32_bf16 v[80:83], v[228:231], v[196:199], v[80:83]
	v_mfma_f32_16x16x32_bf16 v[76:79], v[220:223], v[204:207], v[76:79]
	v_mfma_f32_16x16x32_bf16 v[72:75], v[228:231], v[204:207], v[72:75]
	v_mfma_f32_16x16x32_bf16 v[68:71], v[220:223], v[212:215], v[68:71]
	v_mfma_f32_16x16x32_bf16 v[64:67], v[228:231], v[212:215], v[64:67]
	s_setprio 0
	s_mov_b32 m0, s5
	s_barrier
	ds_read_b128 v[172:175], v147 offset:16384
	ds_read_b128 v[176:179], v147 offset:17408
	ds_read_b128 v[180:183], v147 offset:18432
	ds_read_b128 v[196:199], v147 offset:19456
	ds_read_b128 v[200:203], v147 offset:20480
	ds_read_b128 v[204:207], v147 offset:21504
	ds_read_b128 v[208:211], v147 offset:22528
	ds_read_b128 v[212:215], v147 offset:23552
	global_load_lds_dwordx4 v232, s[14:15]
	s_mov_b32 m0, s24
	s_nop 0
	global_load_lds_dwordx4 v233, s[14:15]
	s_barrier
	s_waitcnt lgkmcnt(0)
	s_setprio 1
	s_waitcnt lgkmcnt(0)
	v_mfma_f32_16x16x32_bf16 v[60:63], v[156:159], v[172:175], 0
	v_mfma_f32_16x16x32_bf16 v[56:59], v[164:167], v[172:175], 0
	v_mfma_f32_16x16x32_bf16 v[52:55], v[156:159], v[180:183], 0
	v_mfma_f32_16x16x32_bf16 v[48:51], v[164:167], v[180:183], 0
	v_mfma_f32_16x16x32_bf16 v[44:47], v[156:159], v[200:203], 0
	v_mfma_f32_16x16x32_bf16 v[40:43], v[164:167], v[200:203], 0
	v_mfma_f32_16x16x32_bf16 v[36:39], v[156:159], v[208:211], 0
	v_mfma_f32_16x16x32_bf16 v[32:35], v[164:167], v[208:211], 0
	v_mfma_f32_16x16x32_bf16 v[60:63], v[160:163], v[176:179], v[60:63]
	v_mfma_f32_16x16x32_bf16 v[56:59], v[168:171], v[176:179], v[56:59]
	v_mfma_f32_16x16x32_bf16 v[52:55], v[160:163], v[196:199], v[52:55]
	v_mfma_f32_16x16x32_bf16 v[48:51], v[168:171], v[196:199], v[48:51]
	v_mfma_f32_16x16x32_bf16 v[44:47], v[160:163], v[204:207], v[44:47]
	v_mfma_f32_16x16x32_bf16 v[40:43], v[168:171], v[204:207], v[40:43]
	v_mfma_f32_16x16x32_bf16 v[36:39], v[160:163], v[212:215], v[36:39]
	v_mfma_f32_16x16x32_bf16 v[32:35], v[168:171], v[212:215], v[32:35]
	s_setprio 0
	s_barrier
	s_mov_b32 m0, s28
	s_nop 0
	global_load_lds_dwordx4 v232, s[22:23]
	s_mov_b32 m0, s29
	s_nop 0
	global_load_lds_dwordx4 v233, s[22:23]
	s_waitcnt vmcnt(6)
	s_barrier
; #define WAIT_V(n) asm volatile("s_waitcnt vmcnt(%0)" ::"n"(n) : "memory")
; #define WAIT_L(n) asm volatile("s_waitcnt lgkmcnt(%0)" ::"n"(n) : "memory")
; #define SBAR() __builtin_amdgcn_sched_barrier(0)
; #define STAGE(P, base, kt) do { _Pragma("unroll") for (int _i = 0; _i < 2; ++_i)                                        \
;       __builtin_amdgcn_global_load_lds((const unsigned*)((base) + (size_t)(sOff[_i] + (unsigned)(kt) * (BK * 2))),        \
;                                        (unsigned*)((P) + wid * 1024 + _i * 8192), 16, 0, 0); } while (0)
; #define LDA(dst, b, h) _Pragma("unroll") for (int m = 0; m < 4; ++m) _Pragma("unroll") for (int k = 0; k < 2; ++k) \
;       dst[m][k] = *(const bf16x8*)(SA(b, h) + aoff + (m * 2048 + k * 1024))
; #define LDB(dst, b, h) _Pragma("unroll") for (int n = 0; n < 2; ++n) _Pragma("unroll") for (int k = 0; k < 2; ++k) \
;       dst[n][k] = *(const bf16x8*)(SB(b, h) + boff + (n * 256 + k * 1024))
; #define BAR __builtin_amdgcn_s_barrier()
; template <int EPI, int N, int K>
; __device__ __forceinline__ void phase_gemm(const Params& p, const u16* __restrict__ A, const u16* __restrict__ Bt, int nM, char* shm,
;                            u16* __restrict__ outp, float* __restrict__ rowss) {
;     ...
;       WAIT_V(6); BAR; MMA(1, 1, At, B1); BAR;
;       LDB(B0, 1, 0); SBAR(); LDA(At, 1, 0); STAGE(SA(0, 1), A1, t + 2);
;       WAIT_L(8); BAR; WAIT_L(0); MMA(0, 0, At, B0); BAR; SBAR();
;       LDB(B1, 1, 1); STAGE(SB(1, 0), B0p, t + 3);
;       BAR; WAIT_L(0); MMA(0, 1, At, B1); BAR;
	s_setprio 1
	v_mfma_f32_16x16x32_bf16 v[28:31], v[216:219], v[172:175], 0
	v_mfma_f32_16x16x32_bf16 v[24:27], v[224:227], v[172:175], 0
	v_mfma_f32_16x16x32_bf16 v[20:23], v[216:219], v[180:183], 0
	v_mfma_f32_16x16x32_bf16 v[16:19], v[224:227], v[180:183], 0
	v_mfma_f32_16x16x32_bf16 v[12:15], v[216:219], v[200:203], 0
	v_mfma_f32_16x16x32_bf16 v[8:11], v[224:227], v[200:203], 0
	v_mfma_f32_16x16x32_bf16 v[4:7], v[216:219], v[208:211], 0
	v_mfma_f32_16x16x32_bf16 v[0:3], v[224:227], v[208:211], 0
	v_mfma_f32_16x16x32_bf16 v[28:31], v[220:223], v[176:179], v[28:31]
	v_mfma_f32_16x16x32_bf16 v[24:27], v[228:231], v[176:179], v[24:27]
	v_mfma_f32_16x16x32_bf16 v[20:23], v[220:223], v[196:199], v[20:23]
	v_mfma_f32_16x16x32_bf16 v[16:19], v[228:231], v[196:199], v[16:19]
	v_mfma_f32_16x16x32_bf16 v[12:15], v[220:223], v[204:207], v[12:15]
	v_mfma_f32_16x16x32_bf16 v[8:11], v[228:231], v[204:207], v[8:11]
	v_mfma_f32_16x16x32_bf16 v[4:7], v[220:223], v[212:215], v[4:7]
	v_mfma_f32_16x16x32_bf16 v[0:3], v[228:231], v[212:215], v[0:3]
	s_setprio 0
	v_or_b32_e32 v156, 0x18000, v146
	v_add_u32_e32 v158, 0x18100, v146
	s_barrier
	v_add_u32_e32 v157, 0x18400, v146
	ds_read_b128 v[164:167], v156
	ds_read_b128 v[168:171], v157
	v_add_u32_e32 v159, 0x18500, v146
	ds_read_b128 v[172:175], v158
	ds_read_b128 v[176:179], v159
	s_mov_b32 m0, s30
	ds_read_b128 v[180:183], v147 offset:32768
	ds_read_b128 v[196:199], v147 offset:33792
	ds_read_b128 v[200:203], v147 offset:34816
	ds_read_b128 v[204:207], v147 offset:35840
	ds_read_b128 v[208:211], v147 offset:36864
	ds_read_b128 v[212:215], v147 offset:37888
	ds_read_b128 v[216:219], v147 offset:38912
	ds_read_b128 v[220:223], v147 offset:39936
	global_load_lds_dwordx4 v232, s[6:7]
	s_mov_b32 m0, s31
	s_nop 0
	global_load_lds_dwordx4 v233, s[6:7]
	s_waitcnt lgkmcnt(8)
	s_barrier
	s_waitcnt lgkmcnt(0)
	s_setprio 1
	s_waitcnt lgkmcnt(0)
	v_mfma_f32_16x16x32_bf16 v[126:129], v[164:167], v[180:183], v[126:129]
	v_mfma_f32_16x16x32_bf16 v[122:125], v[172:175], v[180:183], v[122:125]
	v_mfma_f32_16x16x32_bf16 v[118:121], v[164:167], v[200:203], v[118:121]
	v_mfma_f32_16x16x32_bf16 v[114:117], v[172:175], v[200:203], v[114:117]
	v_mfma_f32_16x16x32_bf16 v[110:113], v[164:167], v[208:211], v[110:113]
	v_mfma_f32_16x16x32_bf16 v[106:109], v[172:175], v[208:211], v[106:109]
	v_mfma_f32_16x16x32_bf16 v[102:105], v[164:167], v[216:219], v[102:105]
	v_mfma_f32_16x16x32_bf16 v[98:101], v[172:175], v[216:219], v[98:101]
	v_mfma_f32_16x16x32_bf16 v[126:129], v[168:171], v[196:199], v[126:129]
	v_mfma_f32_16x16x32_bf16 v[122:125], v[176:179], v[196:199], v[122:125]
	v_mfma_f32_16x16x32_bf16 v[118:121], v[168:171], v[204:207], v[118:121]
	v_mfma_f32_16x16x32_bf16 v[114:117], v[176:179], v[204:207], v[114:117]
	v_mfma_f32_16x16x32_bf16 v[110:113], v[168:171], v[212:215], v[110:113]
	v_mfma_f32_16x16x32_bf16 v[106:109], v[176:179], v[212:215], v[106:109]
	v_mfma_f32_16x16x32_bf16 v[102:105], v[168:171], v[220:223], v[102:105]
	v_mfma_f32_16x16x32_bf16 v[98:101], v[176:179], v[220:223], v[98:101]
	s_setprio 0
	s_barrier
	s_mov_b32 m0, s33
	v_or_b32_e32 v160, 0x1c000, v146
	v_add_u32_e32 v162, 0x1c100, v146
	v_add_u32_e32 v240, 0x180, v240
	v_add_u32_e32 v161, 0x1c400, v146
	ds_read_b128 v[224:227], v160
	ds_read_b128 v[228:231], v161
	v_add_u32_e32 v163, 0x1c500, v146
	ds_read_b128 v[232:235], v162
	ds_read_b128 v[236:239], v163
	global_load_lds_dwordx4 v240, s[12:13]
	v_add_u32_e32 v241, 0x180, v241
	s_mov_b32 m0, s35
	s_nop 0
	global_load_lds_dwordx4 v241, s[12:13]
	s_barrier
; #define WAIT_V(n) asm volatile("s_waitcnt vmcnt(%0)" ::"n"(n) : "memory")
; #define WAIT_L(n) asm volatile("s_waitcnt lgkmcnt(%0)" ::"n"(n) : "memory")
; #define SBAR() __builtin_amdgcn_sched_barrier(0)
; #define STAGE(P, base, kt) do { _Pragma("unroll") for (int _i = 0; _i < 2; ++_i)                                        \
;       __builtin_amdgcn_global_load_lds((const unsigned*)((base) + (size_t)(sOff[_i] + (unsigned)(kt) * (BK * 2))),        \
;                                        (unsigned*)((P) + wid * 1024 + _i * 8192), 16, 0, 0); } while (0)
; #define LDA(dst, b, h) _Pragma("unroll") for (int m = 0; m < 4; ++m) _Pragma("unroll") for (int k = 0; k < 2; ++k) \
;       dst[m][k] = *(const bf16x8*)(SA(b, h) + aoff + (m * 2048 + k * 1024))
; #define BAR __builtin_amdgcn_s_barrier()
; template <int EPI, int N, int K>
; __device__ __forceinline__ void phase_gemm(const Params& p, const u16* __restrict__ A, const u16* __restrict__ Bt, int nM, char* shm,
;                            u16* __restrict__ outp, float* __restrict__ rowss) {
;     ...
;       BAR; WAIT_L(0); MMA(0, 1, At, B1); BAR;
;       LDA(At, 1, 1); STAGE(SA(1, 0), A0, t + 3);
;       BAR; WAIT_L(0); MMA(1, 0, At, B0); BAR; SBAR();
;       STAGE(SB(1, 1), B1p, t + 3);
;       WAIT_V(6); BAR; MMA(1, 1, At, B1); BAR;
;     }
	s_waitcnt lgkmcnt(0)
	s_setprio 1
	s_waitcnt lgkmcnt(0)
	v_mfma_f32_16x16x32_bf16 v[92:95], v[224:227], v[180:183], v[92:95]
	v_mfma_f32_16x16x32_bf16 v[88:91], v[232:235], v[180:183], v[88:91]
	v_mfma_f32_16x16x32_bf16 v[84:87], v[224:227], v[200:203], v[84:87]
	v_mfma_f32_16x16x32_bf16 v[80:83], v[232:235], v[200:203], v[80:83]
	v_mfma_f32_16x16x32_bf16 v[76:79], v[224:227], v[208:211], v[76:79]
	v_mfma_f32_16x16x32_bf16 v[72:75], v[232:235], v[208:211], v[72:75]
	v_mfma_f32_16x16x32_bf16 v[68:71], v[224:227], v[216:219], v[68:71]
	v_mfma_f32_16x16x32_bf16 v[64:67], v[232:235], v[216:219], v[64:67]
	v_mfma_f32_16x16x32_bf16 v[92:95], v[228:231], v[196:199], v[92:95]
	v_mfma_f32_16x16x32_bf16 v[88:91], v[236:239], v[196:199], v[88:91]
	v_mfma_f32_16x16x32_bf16 v[84:87], v[228:231], v[204:207], v[84:87]
	v_mfma_f32_16x16x32_bf16 v[80:83], v[236:239], v[204:207], v[80:83]
	v_mfma_f32_16x16x32_bf16 v[76:79], v[228:231], v[212:215], v[76:79]
	v_mfma_f32_16x16x32_bf16 v[72:75], v[236:239], v[212:215], v[72:75]
	v_mfma_f32_16x16x32_bf16 v[68:71], v[228:231], v[220:223], v[68:71]
	v_mfma_f32_16x16x32_bf16 v[64:67], v[236:239], v[220:223], v[64:67]
	s_setprio 0
	s_mov_b32 m0, s93
	s_barrier
	ds_read_b128 v[180:183], v147 offset:49152
	ds_read_b128 v[196:199], v147 offset:50176
	ds_read_b128 v[200:203], v147 offset:51200
	ds_read_b128 v[204:207], v147 offset:52224
	ds_read_b128 v[208:211], v147 offset:53248
	ds_read_b128 v[212:215], v147 offset:54272
	ds_read_b128 v[216:219], v147 offset:55296
	ds_read_b128 v[220:223], v147 offset:56320
	global_load_lds_dwordx4 v240, s[14:15]
	s_mov_b32 m0, s96
	s_nop 0
	global_load_lds_dwordx4 v241, s[14:15]
	s_barrier
	s_waitcnt lgkmcnt(0)
	s_setprio 1
	s_waitcnt lgkmcnt(0)
	v_mfma_f32_16x16x32_bf16 v[60:63], v[164:167], v[180:183], v[60:63]
	v_mfma_f32_16x16x32_bf16 v[56:59], v[172:175], v[180:183], v[56:59]
	v_mfma_f32_16x16x32_bf16 v[52:55], v[164:167], v[200:203], v[52:55]
	v_mfma_f32_16x16x32_bf16 v[48:51], v[172:175], v[200:203], v[48:51]
	v_mfma_f32_16x16x32_bf16 v[44:47], v[164:167], v[208:211], v[44:47]
	v_mfma_f32_16x16x32_bf16 v[40:43], v[172:175], v[208:211], v[40:43]
	v_mfma_f32_16x16x32_bf16 v[36:39], v[164:167], v[216:219], v[36:39]
	v_mfma_f32_16x16x32_bf16 v[32:35], v[172:175], v[216:219], v[32:35]
	v_mfma_f32_16x16x32_bf16 v[60:63], v[168:171], v[196:199], v[60:63]
	v_mfma_f32_16x16x32_bf16 v[56:59], v[176:179], v[196:199], v[56:59]
	v_mfma_f32_16x16x32_bf16 v[52:55], v[168:171], v[204:207], v[52:55]
	v_mfma_f32_16x16x32_bf16 v[48:51], v[176:179], v[204:207], v[48:51]
	v_mfma_f32_16x16x32_bf16 v[44:47], v[168:171], v[212:215], v[44:47]
	v_mfma_f32_16x16x32_bf16 v[40:43], v[176:179], v[212:215], v[40:43]
	v_mfma_f32_16x16x32_bf16 v[36:39], v[168:171], v[220:223], v[36:39]
	v_mfma_f32_16x16x32_bf16 v[32:35], v[176:179], v[220:223], v[32:35]
	s_setprio 0
	s_barrier
	s_mov_b32 m0, s52
	s_nop 0
	global_load_lds_dwordx4 v240, s[22:23]
	s_mov_b32 m0, s53
	s_nop 0
	global_load_lds_dwordx4 v241, s[22:23]
	s_waitcnt vmcnt(6)
	s_barrier
	s_setprio 1
	v_mfma_f32_16x16x32_bf16 v[28:31], v[224:227], v[180:183], v[28:31]
	v_mfma_f32_16x16x32_bf16 v[24:27], v[232:235], v[180:183], v[24:27]
	v_mfma_f32_16x16x32_bf16 v[20:23], v[224:227], v[200:203], v[20:23]
	v_mfma_f32_16x16x32_bf16 v[16:19], v[232:235], v[200:203], v[16:19]
	v_mfma_f32_16x16x32_bf16 v[12:15], v[224:227], v[208:211], v[12:15]
	v_mfma_f32_16x16x32_bf16 v[8:11], v[232:235], v[208:211], v[8:11]
	v_mfma_f32_16x16x32_bf16 v[4:7], v[224:227], v[216:219], v[4:7]
	v_mfma_f32_16x16x32_bf16 v[0:3], v[232:235], v[216:219], v[0:3]
	v_mfma_f32_16x16x32_bf16 v[28:31], v[228:231], v[196:199], v[28:31]
	v_mfma_f32_16x16x32_bf16 v[24:27], v[236:239], v[196:199], v[24:27]
	v_mfma_f32_16x16x32_bf16 v[20:23], v[228:231], v[204:207], v[20:23]
	v_mfma_f32_16x16x32_bf16 v[16:19], v[236:239], v[204:207], v[16:19]
	v_mfma_f32_16x16x32_bf16 v[12:15], v[228:231], v[212:215], v[12:15]
	v_mfma_f32_16x16x32_bf16 v[8:11], v[236:239], v[212:215], v[8:11]
	v_mfma_f32_16x16x32_bf16 v[4:7], v[228:231], v[220:223], v[4:7]
	v_mfma_f32_16x16x32_bf16 v[0:3], v[236:239], v[220:223], v[0:3]
	s_setprio 0
	s_add_i32 s61, s61, 2
	v_add_u32_e32 v142, 0x100, v142
	s_cmp_lt_u32 s61, 40
	v_add_u32_e32 v96, 0x100, v96
	s_barrier

; #define WAIT_V(n) asm volatile("s_waitcnt vmcnt(%0)" ::"n"(n) : "memory")
; #define WAIT_L(n) asm volatile("s_waitcnt lgkmcnt(%0)" ::"n"(n) : "memory")
; #define SBAR() __builtin_amdgcn_sched_barrier(0)
; #define STAGE(P, base, kt) do { _Pragma("unroll") for (int _i = 0; _i < 2; ++_i)                                        \
;       __builtin_amdgcn_global_load_lds((const unsigned*)((base) + (size_t)(sOff[_i] + (unsigned)(kt) * (BK * 2))),        \
;                                        (unsigned*)((P) + wid * 1024 + _i * 8192), 16, 0, 0); } while (0)
; #define LDA(dst, b, h) _Pragma("unroll") for (int m = 0; m < 4; ++m) _Pragma("unroll") for (int k = 0; k < 2; ++k) \
;       dst[m][k] = *(const bf16x8*)(SA(b, h) + aoff + (m * 2048 + k * 1024))
; #define LDB(dst, b, h) _Pragma("unroll") for (int n = 0; n < 2; ++n) _Pragma("unroll") for (int k = 0; k < 2; ++k) \
;       dst[n][k] = *(const bf16x8*)(SB(b, h) + boff + (n * 256 + k * 1024))
; #define BAR __builtin_amdgcn_s_barrier()
; template <int EPI, int N, int K>
; __device__ __forceinline__ void phase_gemm(const Params& p, const u16* __restrict__ A, const u16* __restrict__ Bt, int nM, char* shm,
;                            u16* __restrict__ outp, float* __restrict__ rowss) {
;     ...
;   for (;;) {
;     const char* A1 = A0 + (size_t)128 * K * 2;
;     const char* B1p = B0p + (size_t)128 * K * 2;
;     f32x4 acc[2][2][4][2] = {};
;     bf16x8 At[4][2], B0[2][2], B1[2][2];
;     if (wr == 1) BAR;
;     WAIT_V(0); BAR;
;     BAR;
;     for (int t = 0; t < nt - 2; t += 2) {
;       LDB(B0, 0, 0); SBAR(); LDA(At, 0, 0); STAGE(SA(1, 1), A1, t + 1);
;       WAIT_L(8); BAR; WAIT_L(0); MMA(0, 0, At, B0); BAR; SBAR();
;       LDB(B1, 0, 1); STAGE(SB(0, 0), B0p, t + 2);
;       BAR; WAIT_L(0); MMA(0, 1, At, B1); BAR;
;       LDA(At, 0, 1); STAGE(SA(0, 0), A0, t + 2);
;       BAR; WAIT_L(0); MMA(1, 0, At, B0); BAR; SBAR();
;       STAGE(SB(0, 1), B1p, t + 2);
;       WAIT_V(6); BAR; MMA(1, 1, At, B1); BAR;
.LBB0_129:
	s_add_u32 s16, s10, 0x40000
	s_addc_u32 s17, s11, 0
	s_waitcnt vmcnt(0)
	s_add_u32 s18, s8, 0x40000
	s_addc_u32 s19, s9, 0
	s_mov_b32 s53, -2
	v_mov_b32_e32 v140, v146
	v_mov_b32_e32 v141, v145
	s_barrier
	s_barrier
	v_or_b32_e32 v147, 0x10000, v143
	v_add_u32_e32 v149, 0x10100, v143
	v_add_u32_e32 v148, 0x10400, v143
	ds_read_b128 v[156:159], v147
	ds_read_b128 v[160:163], v148
	v_add_u32_e32 v150, 0x10500, v143
	ds_read_b128 v[164:167], v149
	ds_read_b128 v[168:171], v150
	v_add_u32_e32 v240, v142, v140
	s_add_i32 s55, s5, 0xc000
	v_add_u32_e32 v151, 0x80, v240
	s_mov_b32 m0, s55
	v_add_u32_e32 v241, v142, v141
	s_add_i32 s54, s5, 0xe000
	ds_read_b128 v[172:175], v144
	ds_read_b128 v[176:179], v144 offset:1024
	ds_read_b128 v[180:183], v144 offset:2048
	ds_read_b128 v[196:199], v144 offset:3072
	ds_read_b128 v[200:203], v144 offset:4096
	ds_read_b128 v[204:207], v144 offset:5120
	ds_read_b128 v[208:211], v144 offset:6144
	ds_read_b128 v[212:215], v144 offset:7168
	global_load_lds_dwordx4 v151, s[16:17]
	v_add_u32_e32 v151, 0x80, v241
	s_mov_b32 m0, s54
	s_nop 0
	global_load_lds_dwordx4 v151, s[16:17]
	s_waitcnt lgkmcnt(8)
	s_barrier
	s_waitcnt lgkmcnt(0)
	s_setprio 1
	s_waitcnt lgkmcnt(0)
	v_mfma_f32_16x16x32_bf16 v[126:129], v[156:159], v[172:175], 0
	v_mfma_f32_16x16x32_bf16 v[122:125], v[164:167], v[172:175], 0
	v_mfma_f32_16x16x32_bf16 v[118:121], v[156:159], v[180:183], 0
	v_mfma_f32_16x16x32_bf16 v[114:117], v[164:167], v[180:183], 0
	v_mfma_f32_16x16x32_bf16 v[110:113], v[156:159], v[200:203], 0
	v_mfma_f32_16x16x32_bf16 v[106:109], v[164:167], v[200:203], 0
	v_mfma_f32_16x16x32_bf16 v[102:105], v[156:159], v[208:211], 0
	v_mfma_f32_16x16x32_bf16 v[98:101], v[164:167], v[208:211], 0
	v_mfma_f32_16x16x32_bf16 v[126:129], v[160:163], v[176:179], v[126:129]
	v_mfma_f32_16x16x32_bf16 v[122:125], v[168:171], v[176:179], v[122:125]
	v_mfma_f32_16x16x32_bf16 v[118:121], v[160:163], v[196:199], v[118:121]
	v_mfma_f32_16x16x32_bf16 v[114:117], v[168:171], v[196:199], v[114:117]
	v_mfma_f32_16x16x32_bf16 v[110:113], v[160:163], v[204:207], v[110:113]
	v_mfma_f32_16x16x32_bf16 v[106:109], v[168:171], v[204:207], v[106:109]
	v_mfma_f32_16x16x32_bf16 v[102:105], v[160:163], v[212:215], v[102:105]
	v_mfma_f32_16x16x32_bf16 v[98:101], v[168:171], v[212:215], v[98:101]
	s_setprio 0
	s_barrier
	s_mov_b32 m0, s23
	v_or_b32_e32 v151, 0x14000, v143
	v_add_u32_e32 v153, 0x14100, v143
	v_add_u32_e32 v232, 0x100, v240
	v_add_u32_e32 v152, 0x14400, v143
	ds_read_b128 v[216:219], v151
	ds_read_b128 v[220:223], v152
	v_add_u32_e32 v154, 0x14500, v143
	ds_read_b128 v[224:227], v153
	ds_read_b128 v[228:231], v154
	global_load_lds_dwordx4 v232, s[8:9]
	v_add_u32_e32 v233, 0x100, v241
	s_mov_b32 m0, s94
	s_nop 0
	global_load_lds_dwordx4 v233, s[8:9]
	s_barrier
	s_waitcnt lgkmcnt(0)
	s_setprio 1
	s_waitcnt lgkmcnt(0)
	v_mfma_f32_16x16x32_bf16 v[92:95], v[216:219], v[172:175], 0
	v_mfma_f32_16x16x32_bf16 v[88:91], v[224:227], v[172:175], 0
	v_mfma_f32_16x16x32_bf16 v[84:87], v[216:219], v[180:183], 0
	v_mfma_f32_16x16x32_bf16 v[80:83], v[224:227], v[180:183], 0
	v_mfma_f32_16x16x32_bf16 v[76:79], v[216:219], v[200:203], 0
	v_mfma_f32_16x16x32_bf16 v[72:75], v[224:227], v[200:203], 0
	v_mfma_f32_16x16x32_bf16 v[68:71], v[216:219], v[208:211], 0
	v_mfma_f32_16x16x32_bf16 v[64:67], v[224:227], v[208:211], 0
	v_mfma_f32_16x16x32_bf16 v[92:95], v[220:223], v[176:179], v[92:95]
	v_mfma_f32_16x16x32_bf16 v[88:91], v[228:231], v[176:179], v[88:91]
	v_mfma_f32_16x16x32_bf16 v[84:87], v[220:223], v[196:199], v[84:87]
	v_mfma_f32_16x16x32_bf16 v[80:83], v[228:231], v[196:199], v[80:83]
	v_mfma_f32_16x16x32_bf16 v[76:79], v[220:223], v[204:207], v[76:79]
	v_mfma_f32_16x16x32_bf16 v[72:75], v[228:231], v[204:207], v[72:75]
	v_mfma_f32_16x16x32_bf16 v[68:71], v[220:223], v[212:215], v[68:71]
	v_mfma_f32_16x16x32_bf16 v[64:67], v[228:231], v[212:215], v[64:67]
	s_setprio 0
	s_mov_b32 m0, s5
	s_barrier
	ds_read_b128 v[172:175], v144 offset:16384
	ds_read_b128 v[176:179], v144 offset:17408
	ds_read_b128 v[180:183], v144 offset:18432
	ds_read_b128 v[196:199], v144 offset:19456
	ds_read_b128 v[200:203], v144 offset:20480
	ds_read_b128 v[204:207], v144 offset:21504
	ds_read_b128 v[208:211], v144 offset:22528
	ds_read_b128 v[212:215], v144 offset:23552
	global_load_lds_dwordx4 v232, s[10:11]
	s_mov_b32 m0, s22
	s_nop 0
	global_load_lds_dwordx4 v233, s[10:11]
	s_barrier
	s_waitcnt lgkmcnt(0)
	s_setprio 1
	s_waitcnt lgkmcnt(0)
	v_mfma_f32_16x16x32_bf16 v[60:63], v[156:159], v[172:175], 0
	v_mfma_f32_16x16x32_bf16 v[56:59], v[164:167], v[172:175], 0
	v_mfma_f32_16x16x32_bf16 v[52:55], v[156:159], v[180:183], 0
	v_mfma_f32_16x16x32_bf16 v[48:51], v[164:167], v[180:183], 0
	v_mfma_f32_16x16x32_bf16 v[44:47], v[156:159], v[200:203], 0
	v_mfma_f32_16x16x32_bf16 v[40:43], v[164:167], v[200:203], 0
	v_mfma_f32_16x16x32_bf16 v[36:39], v[156:159], v[208:211], 0
	v_mfma_f32_16x16x32_bf16 v[32:35], v[164:167], v[208:211], 0
	v_mfma_f32_16x16x32_bf16 v[60:63], v[160:163], v[176:179], v[60:63]
	v_mfma_f32_16x16x32_bf16 v[56:59], v[168:171], v[176:179], v[56:59]
	v_mfma_f32_16x16x32_bf16 v[52:55], v[160:163], v[196:199], v[52:55]
	v_mfma_f32_16x16x32_bf16 v[48:51], v[168:171], v[196:199], v[48:51]
	v_mfma_f32_16x16x32_bf16 v[44:47], v[160:163], v[204:207], v[44:47]
	v_mfma_f32_16x16x32_bf16 v[40:43], v[168:171], v[204:207], v[40:43]
	v_mfma_f32_16x16x32_bf16 v[36:39], v[160:163], v[212:215], v[36:39]
	v_mfma_f32_16x16x32_bf16 v[32:35], v[168:171], v[212:215], v[32:35]
	s_setprio 0
	s_barrier
	s_mov_b32 m0, s95
	s_nop 0
	global_load_lds_dwordx4 v232, s[18:19]
	s_mov_b32 m0, s96
	s_nop 0
	global_load_lds_dwordx4 v233, s[18:19]
	s_waitcnt vmcnt(6)
	s_barrier
; #define WAIT_V(n) asm volatile("s_waitcnt vmcnt(%0)" ::"n"(n) : "memory")
; #define WAIT_L(n) asm volatile("s_waitcnt lgkmcnt(%0)" ::"n"(n) : "memory")
; #define SBAR() __builtin_amdgcn_sched_barrier(0)
; #define STAGE(P, base, kt) do { _Pragma("unroll") for (int _i = 0; _i < 2; ++_i)                                        \
;       __builtin_amdgcn_global_load_lds((const unsigned*)((base) + (size_t)(sOff[_i] + (unsigned)(kt) * (BK * 2))),        \
;                                        (unsigned*)((P) + wid * 1024 + _i * 8192), 16, 0, 0); } while (0)
; #define LDA(dst, b, h) _Pragma("unroll") for (int m = 0; m < 4; ++m) _Pragma("unroll") for (int k = 0; k < 2; ++k) \
;       dst[m][k] = *(const bf16x8*)(SA(b, h) + aoff + (m * 2048 + k * 1024))
; #define LDB(dst, b, h) _Pragma("unroll") for (int n = 0; n < 2; ++n) _Pragma("unroll") for (int k = 0; k < 2; ++k) \
;       dst[n][k] = *(const bf16x8*)(SB(b, h) + boff + (n * 256 + k * 1024))
; #define BAR __builtin_amdgcn_s_barrier()
; template <int EPI, int N, int K>
; __device__ __forceinline__ void phase_gemm(const Params& p, const u16* __restrict__ A, const u16* __restrict__ Bt, int nM, char* shm,
;                            u16* __restrict__ outp, float* __restrict__ rowss) {
;     ...
;       WAIT_V(6); BAR; MMA(1, 1, At, B1); BAR;
;       LDB(B0, 1, 0); SBAR(); LDA(At, 1, 0); STAGE(SA(0, 1), A1, t + 2);
;       WAIT_L(8); BAR; WAIT_L(0); MMA(0, 0, At, B0); BAR; SBAR();
;       LDB(B1, 1, 1); STAGE(SB(1, 0), B0p, t + 3);
;       BAR; WAIT_L(0); MMA(0, 1, At, B1); BAR;
	s_setprio 1
	v_mfma_f32_16x16x32_bf16 v[28:31], v[216:219], v[172:175], 0
	v_mfma_f32_16x16x32_bf16 v[24:27], v[224:227], v[172:175], 0
	v_mfma_f32_16x16x32_bf16 v[20:23], v[216:219], v[180:183], 0
	v_mfma_f32_16x16x32_bf16 v[16:19], v[224:227], v[180:183], 0
	v_mfma_f32_16x16x32_bf16 v[12:15], v[216:219], v[200:203], 0
	v_mfma_f32_16x16x32_bf16 v[8:11], v[224:227], v[200:203], 0
	v_mfma_f32_16x16x32_bf16 v[4:7], v[216:219], v[208:211], 0
	v_mfma_f32_16x16x32_bf16 v[0:3], v[224:227], v[208:211], 0
	v_mfma_f32_16x16x32_bf16 v[28:31], v[220:223], v[176:179], v[28:31]
	v_mfma_f32_16x16x32_bf16 v[24:27], v[228:231], v[176:179], v[24:27]
	v_mfma_f32_16x16x32_bf16 v[20:23], v[220:223], v[196:199], v[20:23]
	v_mfma_f32_16x16x32_bf16 v[16:19], v[228:231], v[196:199], v[16:19]
	v_mfma_f32_16x16x32_bf16 v[12:15], v[220:223], v[204:207], v[12:15]
	v_mfma_f32_16x16x32_bf16 v[8:11], v[228:231], v[204:207], v[8:11]
	v_mfma_f32_16x16x32_bf16 v[4:7], v[220:223], v[212:215], v[4:7]
	v_mfma_f32_16x16x32_bf16 v[0:3], v[228:231], v[212:215], v[0:3]
	s_setprio 0
	v_or_b32_e32 v155, 0x18000, v143
	v_add_u32_e32 v157, 0x18100, v143
	s_barrier
	v_add_u32_e32 v156, 0x18400, v143
	ds_read_b128 v[164:167], v155
	ds_read_b128 v[168:171], v156
	v_add_u32_e32 v158, 0x18500, v143
	ds_read_b128 v[172:175], v157
	ds_read_b128 v[176:179], v158
	s_mov_b32 m0, s97
	ds_read_b128 v[180:183], v144 offset:32768
	ds_read_b128 v[196:199], v144 offset:33792
	ds_read_b128 v[200:203], v144 offset:34816
	ds_read_b128 v[204:207], v144 offset:35840
	ds_read_b128 v[208:211], v144 offset:36864
	ds_read_b128 v[212:215], v144 offset:37888
	ds_read_b128 v[216:219], v144 offset:38912
	ds_read_b128 v[220:223], v144 offset:39936
	global_load_lds_dwordx4 v232, s[16:17]
	s_mov_b32 m0, s33
	s_nop 0
	global_load_lds_dwordx4 v233, s[16:17]
	s_waitcnt lgkmcnt(8)
	s_barrier
	s_waitcnt lgkmcnt(0)
	s_setprio 1
	s_waitcnt lgkmcnt(0)
	v_mfma_f32_16x16x32_bf16 v[126:129], v[164:167], v[180:183], v[126:129]
	v_mfma_f32_16x16x32_bf16 v[122:125], v[172:175], v[180:183], v[122:125]
	v_mfma_f32_16x16x32_bf16 v[118:121], v[164:167], v[200:203], v[118:121]
	v_mfma_f32_16x16x32_bf16 v[114:117], v[172:175], v[200:203], v[114:117]
	v_mfma_f32_16x16x32_bf16 v[110:113], v[164:167], v[208:211], v[110:113]
	v_mfma_f32_16x16x32_bf16 v[106:109], v[172:175], v[208:211], v[106:109]
	v_mfma_f32_16x16x32_bf16 v[102:105], v[164:167], v[216:219], v[102:105]
	v_mfma_f32_16x16x32_bf16 v[98:101], v[172:175], v[216:219], v[98:101]
	v_mfma_f32_16x16x32_bf16 v[126:129], v[168:171], v[196:199], v[126:129]
	v_mfma_f32_16x16x32_bf16 v[122:125], v[176:179], v[196:199], v[122:125]
	v_mfma_f32_16x16x32_bf16 v[118:121], v[168:171], v[204:207], v[118:121]
	v_mfma_f32_16x16x32_bf16 v[114:117], v[176:179], v[204:207], v[114:117]
	v_mfma_f32_16x16x32_bf16 v[110:113], v[168:171], v[212:215], v[110:113]
	v_mfma_f32_16x16x32_bf16 v[106:109], v[176:179], v[212:215], v[106:109]
	v_mfma_f32_16x16x32_bf16 v[102:105], v[168:171], v[220:223], v[102:105]
	v_mfma_f32_16x16x32_bf16 v[98:101], v[176:179], v[220:223], v[98:101]
	s_setprio 0
	s_barrier
	s_mov_b32 m0, s35
	v_or_b32_e32 v159, 0x1c000, v143
	v_add_u32_e32 v161, 0x1c100, v143
	v_add_u32_e32 v163, 0x180, v240
	v_add_u32_e32 v160, 0x1c400, v143
	ds_read_b128 v[224:227], v159
	ds_read_b128 v[228:231], v160
	v_add_u32_e32 v162, 0x1c500, v143
	ds_read_b128 v[232:235], v161
	ds_read_b128 v[236:239], v162
	global_load_lds_dwordx4 v163, s[8:9]
	v_add_u32_e32 v240, 0x180, v241
	s_mov_b32 m0, s93
	s_nop 0
	global_load_lds_dwordx4 v240, s[8:9]
	s_barrier
; #define WAIT_V(n) asm volatile("s_waitcnt vmcnt(%0)" ::"n"(n) : "memory")
; #define WAIT_L(n) asm volatile("s_waitcnt lgkmcnt(%0)" ::"n"(n) : "memory")
; #define SBAR() __builtin_amdgcn_sched_barrier(0)
; #define STAGE(P, base, kt) do { _Pragma("unroll") for (int _i = 0; _i < 2; ++_i)                                        \
;       __builtin_amdgcn_global_load_lds((const unsigned*)((base) + (size_t)(sOff[_i] + (unsigned)(kt) * (BK * 2))),        \
;                                        (unsigned*)((P) + wid * 1024 + _i * 8192), 16, 0, 0); } while (0)
; #define LDA(dst, b, h) _Pragma("unroll") for (int m = 0; m < 4; ++m) _Pragma("unroll") for (int k = 0; k < 2; ++k) \
;       dst[m][k] = *(const bf16x8*)(SA(b, h) + aoff + (m * 2048 + k * 1024))
; #define BAR __builtin_amdgcn_s_barrier()
; template <int EPI, int N, int K>
; __device__ __forceinline__ void phase_gemm(const Params& p, const u16* __restrict__ A, const u16* __restrict__ Bt, int nM, char* shm,
;                            u16* __restrict__ outp, float* __restrict__ rowss) {
;     ...
;       BAR; WAIT_L(0); MMA(0, 1, At, B1); BAR;
;       LDA(At, 1, 1); STAGE(SA(1, 0), A0, t + 3);
;       BAR; WAIT_L(0); MMA(1, 0, At, B0); BAR; SBAR();
;       STAGE(SB(1, 1), B1p, t + 3);
;       WAIT_V(6); BAR; MMA(1, 1, At, B1); BAR;
;     }
	s_waitcnt lgkmcnt(0)
	s_setprio 1
	s_waitcnt lgkmcnt(0)
	v_mfma_f32_16x16x32_bf16 v[92:95], v[224:227], v[180:183], v[92:95]
	v_mfma_f32_16x16x32_bf16 v[88:91], v[232:235], v[180:183], v[88:91]
	v_mfma_f32_16x16x32_bf16 v[84:87], v[224:227], v[200:203], v[84:87]
	v_mfma_f32_16x16x32_bf16 v[80:83], v[232:235], v[200:203], v[80:83]
	v_mfma_f32_16x16x32_bf16 v[76:79], v[224:227], v[208:211], v[76:79]
	v_mfma_f32_16x16x32_bf16 v[72:75], v[232:235], v[208:211], v[72:75]
	v_mfma_f32_16x16x32_bf16 v[68:71], v[224:227], v[216:219], v[68:71]
	v_mfma_f32_16x16x32_bf16 v[64:67], v[232:235], v[216:219], v[64:67]
	v_mfma_f32_16x16x32_bf16 v[92:95], v[228:231], v[196:199], v[92:95]
	v_mfma_f32_16x16x32_bf16 v[88:91], v[236:239], v[196:199], v[88:91]
	v_mfma_f32_16x16x32_bf16 v[84:87], v[228:231], v[204:207], v[84:87]
	v_mfma_f32_16x16x32_bf16 v[80:83], v[236:239], v[204:207], v[80:83]
	v_mfma_f32_16x16x32_bf16 v[76:79], v[228:231], v[212:215], v[76:79]
	v_mfma_f32_16x16x32_bf16 v[72:75], v[236:239], v[212:215], v[72:75]
	v_mfma_f32_16x16x32_bf16 v[68:71], v[228:231], v[220:223], v[68:71]
	v_mfma_f32_16x16x32_bf16 v[64:67], v[236:239], v[220:223], v[64:67]
	s_setprio 0
	s_mov_b32 m0, s24
	s_barrier
	ds_read_b128 v[180:183], v144 offset:49152
	ds_read_b128 v[196:199], v144 offset:50176
	ds_read_b128 v[200:203], v144 offset:51200
	ds_read_b128 v[204:207], v144 offset:52224
	ds_read_b128 v[208:211], v144 offset:53248
	ds_read_b128 v[212:215], v144 offset:54272
	ds_read_b128 v[216:219], v144 offset:55296
	ds_read_b128 v[220:223], v144 offset:56320
	global_load_lds_dwordx4 v163, s[10:11]
	s_mov_b32 m0, s25
	s_nop 0
	global_load_lds_dwordx4 v240, s[10:11]
	s_barrier
	s_waitcnt lgkmcnt(0)
	s_setprio 1
	s_waitcnt lgkmcnt(0)
	v_mfma_f32_16x16x32_bf16 v[60:63], v[164:167], v[180:183], v[60:63]
	v_mfma_f32_16x16x32_bf16 v[56:59], v[172:175], v[180:183], v[56:59]
	v_mfma_f32_16x16x32_bf16 v[52:55], v[164:167], v[200:203], v[52:55]
	v_mfma_f32_16x16x32_bf16 v[48:51], v[172:175], v[200:203], v[48:51]
	v_mfma_f32_16x16x32_bf16 v[44:47], v[164:167], v[208:211], v[44:47]
	v_mfma_f32_16x16x32_bf16 v[40:43], v[172:175], v[208:211], v[40:43]
	v_mfma_f32_16x16x32_bf16 v[36:39], v[164:167], v[216:219], v[36:39]
	v_mfma_f32_16x16x32_bf16 v[32:35], v[172:175], v[216:219], v[32:35]
	v_mfma_f32_16x16x32_bf16 v[60:63], v[168:171], v[196:199], v[60:63]
	v_mfma_f32_16x16x32_bf16 v[56:59], v[176:179], v[196:199], v[56:59]
	v_mfma_f32_16x16x32_bf16 v[52:55], v[168:171], v[204:207], v[52:55]
	v_mfma_f32_16x16x32_bf16 v[48:51], v[176:179], v[204:207], v[48:51]
	v_mfma_f32_16x16x32_bf16 v[44:47], v[168:171], v[212:215], v[44:47]
	v_mfma_f32_16x16x32_bf16 v[40:43], v[176:179], v[212:215], v[40:43]
	v_mfma_f32_16x16x32_bf16 v[36:39], v[168:171], v[220:223], v[36:39]
	v_mfma_f32_16x16x32_bf16 v[32:35], v[176:179], v[220:223], v[32:35]
	s_setprio 0
	s_barrier
	s_mov_b32 m0, s26
	s_nop 0
	global_load_lds_dwordx4 v163, s[18:19]
	s_mov_b32 m0, s27
	s_nop 0
	global_load_lds_dwordx4 v240, s[18:19]
	s_waitcnt vmcnt(6)
	s_barrier
	s_setprio 1
	v_mfma_f32_16x16x32_bf16 v[28:31], v[224:227], v[180:183], v[28:31]
	v_mfma_f32_16x16x32_bf16 v[24:27], v[232:235], v[180:183], v[24:27]
	v_mfma_f32_16x16x32_bf16 v[20:23], v[224:227], v[200:203], v[20:23]
	v_mfma_f32_16x16x32_bf16 v[16:19], v[232:235], v[200:203], v[16:19]
	v_mfma_f32_16x16x32_bf16 v[12:15], v[224:227], v[208:211], v[12:15]
	v_mfma_f32_16x16x32_bf16 v[8:11], v[232:235], v[208:211], v[8:11]
	v_mfma_f32_16x16x32_bf16 v[4:7], v[224:227], v[216:219], v[4:7]
	v_mfma_f32_16x16x32_bf16 v[0:3], v[232:235], v[216:219], v[0:3]
	v_mfma_f32_16x16x32_bf16 v[28:31], v[228:231], v[196:199], v[28:31]
	v_mfma_f32_16x16x32_bf16 v[24:27], v[236:239], v[196:199], v[24:27]
	v_mfma_f32_16x16x32_bf16 v[20:23], v[228:231], v[204:207], v[20:23]
	v_mfma_f32_16x16x32_bf16 v[16:19], v[236:239], v[204:207], v[16:19]
	v_mfma_f32_16x16x32_bf16 v[12:15], v[228:231], v[212:215], v[12:15]
	v_mfma_f32_16x16x32_bf16 v[8:11], v[236:239], v[212:215], v[8:11]
	v_mfma_f32_16x16x32_bf16 v[4:7], v[228:231], v[220:223], v[4:7]
	v_mfma_f32_16x16x32_bf16 v[0:3], v[236:239], v[220:223], v[0:3]
	s_setprio 0
	s_add_i32 s53, s53, 2
	v_add_u32_e32 v141, 0x100, v141
	s_cmp_lt_u32 s53, 12
	v_add_u32_e32 v140, 0x100, v140
	s_barrier

; #define WAIT_V(n) asm volatile("s_waitcnt vmcnt(%0)" ::"n"(n) : "memory")
; #define WAIT_L(n) asm volatile("s_waitcnt lgkmcnt(%0)" ::"n"(n) : "memory")
; #define SBAR() __builtin_amdgcn_sched_barrier(0)
; #define STAGE(P, base, kt) do { _Pragma("unroll") for (int _i = 0; _i < 2; ++_i)                                        \
;       __builtin_amdgcn_global_load_lds((const unsigned*)((base) + (size_t)(sOff[_i] + (unsigned)(kt) * (BK * 2))),        \
;                                        (unsigned*)((P) + wid * 1024 + _i * 8192), 16, 0, 0); } while (0)
; #define LDA(dst, b, h) _Pragma("unroll") for (int m = 0; m < 4; ++m) _Pragma("unroll") for (int k = 0; k < 2; ++k) \
;       dst[m][k] = *(const bf16x8*)(SA(b, h) + aoff + (m * 2048 + k * 1024))
; #define LDB(dst, b, h) _Pragma("unroll") for (int n = 0; n < 2; ++n) _Pragma("unroll") for (int k = 0; k < 2; ++k) \
;       dst[n][k] = *(const bf16x8*)(SB(b, h) + boff + (n * 256 + k * 1024))
; #define BAR __builtin_amdgcn_s_barrier()
; template <int EPI, int N, int K>
; __device__ __forceinline__ void phase_gemm(const Params& p, const u16* __restrict__ A, const u16* __restrict__ Bt, int nM, char* shm,
;                            u16* __restrict__ outp, float* __restrict__ rowss) {
;     ...
;   for (;;) {
;     const char* A1 = A0 + (size_t)128 * K * 2;
;     const char* B1p = B0p + (size_t)128 * K * 2;
;     f32x4 acc[2][2][4][2] = {};
;     bf16x8 At[4][2], B0[2][2], B1[2][2];
;     if (wr == 1) BAR;
;     WAIT_V(0); BAR;
;     BAR;
;     for (int t = 0; t < nt - 2; t += 2) {
;       LDB(B0, 0, 0); SBAR(); LDA(At, 0, 0); STAGE(SA(1, 1), A1, t + 1);
;       WAIT_L(8); BAR; WAIT_L(0); MMA(0, 0, At, B0); BAR; SBAR();
;       LDB(B1, 0, 1); STAGE(SB(0, 0), B0p, t + 2);
;       BAR; WAIT_L(0); MMA(0, 1, At, B1); BAR;
;       LDA(At, 0, 1); STAGE(SA(0, 0), A0, t + 2);
;       BAR; WAIT_L(0); MMA(1, 0, At, B0); BAR; SBAR();
;       STAGE(SB(0, 1), B1p, t + 2);
;       WAIT_V(6); BAR; MMA(1, 1, At, B1); BAR;
.LBB0_197:
	s_add_u32 s6, s14, 0x40000
	s_addc_u32 s7, s15, 0
	s_waitcnt vmcnt(0)
	s_add_u32 s22, s12, 0x40000
	s_addc_u32 s23, s13, 0
	s_mov_b32 s59, -2
	v_mov_b32_e32 v96, v150
	v_mov_b32_e32 v142, v149
	s_waitcnt lgkmcnt(0)
	s_barrier
	s_barrier
	v_or_b32_e32 v143, 0x10000, v147
	v_add_u32_e32 v145, 0x10100, v147
	v_add_u32_e32 v144, 0x10400, v147
	ds_read_b128 v[156:159], v143
	ds_read_b128 v[160:163], v144
	v_add_u32_e32 v151, 0x10500, v147
	ds_read_b128 v[164:167], v145
	ds_read_b128 v[168:171], v151
	v_add_u32_e32 v240, v146, v96
	s_add_i32 s61, s5, 0xc000
	v_add_u32_e32 v152, 0x80, v240
	s_mov_b32 m0, s61
	v_add_u32_e32 v241, v146, v142
	s_add_i32 s60, s5, 0xe000
	ds_read_b128 v[172:175], v148
	ds_read_b128 v[176:179], v148 offset:1024
	ds_read_b128 v[180:183], v148 offset:2048
	ds_read_b128 v[196:199], v148 offset:3072
	ds_read_b128 v[200:203], v148 offset:4096
	ds_read_b128 v[204:207], v148 offset:5120
	ds_read_b128 v[208:211], v148 offset:6144
	ds_read_b128 v[212:215], v148 offset:7168
	global_load_lds_dwordx4 v152, s[6:7]
	v_add_u32_e32 v152, 0x80, v241
	s_mov_b32 m0, s60
	s_nop 0
	global_load_lds_dwordx4 v152, s[6:7]
	s_waitcnt lgkmcnt(8)
	s_barrier
	s_waitcnt lgkmcnt(0)
	s_setprio 1
	s_waitcnt lgkmcnt(0)
	v_mfma_f32_16x16x32_bf16 v[126:129], v[156:159], v[172:175], 0
	v_mfma_f32_16x16x32_bf16 v[122:125], v[164:167], v[172:175], 0
	v_mfma_f32_16x16x32_bf16 v[118:121], v[156:159], v[180:183], 0
	v_mfma_f32_16x16x32_bf16 v[114:117], v[164:167], v[180:183], 0
	v_mfma_f32_16x16x32_bf16 v[110:113], v[156:159], v[200:203], 0
	v_mfma_f32_16x16x32_bf16 v[106:109], v[164:167], v[200:203], 0
	v_mfma_f32_16x16x32_bf16 v[102:105], v[156:159], v[208:211], 0
	v_mfma_f32_16x16x32_bf16 v[98:101], v[164:167], v[208:211], 0
	v_mfma_f32_16x16x32_bf16 v[126:129], v[160:163], v[176:179], v[126:129]
	v_mfma_f32_16x16x32_bf16 v[122:125], v[168:171], v[176:179], v[122:125]
	v_mfma_f32_16x16x32_bf16 v[118:121], v[160:163], v[196:199], v[118:121]
	v_mfma_f32_16x16x32_bf16 v[114:117], v[168:171], v[196:199], v[114:117]
	v_mfma_f32_16x16x32_bf16 v[110:113], v[160:163], v[204:207], v[110:113]
	v_mfma_f32_16x16x32_bf16 v[106:109], v[168:171], v[204:207], v[106:109]
	v_mfma_f32_16x16x32_bf16 v[102:105], v[160:163], v[212:215], v[102:105]
	v_mfma_f32_16x16x32_bf16 v[98:101], v[168:171], v[212:215], v[98:101]
	s_setprio 0
	s_barrier
	s_mov_b32 m0, s26
	v_or_b32_e32 v152, 0x14000, v147
	v_add_u32_e32 v154, 0x14100, v147
	v_add_u32_e32 v232, 0x100, v240
	v_add_u32_e32 v153, 0x14400, v147
	ds_read_b128 v[216:219], v152
	ds_read_b128 v[220:223], v153
	v_add_u32_e32 v155, 0x14500, v147
	ds_read_b128 v[224:227], v154
	ds_read_b128 v[228:231], v155
	global_load_lds_dwordx4 v232, s[12:13]
	v_add_u32_e32 v233, 0x100, v241
	s_mov_b32 m0, s27
	s_nop 0
	global_load_lds_dwordx4 v233, s[12:13]
	s_barrier
	s_waitcnt lgkmcnt(0)
	s_setprio 1
	s_waitcnt lgkmcnt(0)
	v_mfma_f32_16x16x32_bf16 v[92:95], v[216:219], v[172:175], 0
	v_mfma_f32_16x16x32_bf16 v[88:91], v[224:227], v[172:175], 0
	v_mfma_f32_16x16x32_bf16 v[84:87], v[216:219], v[180:183], 0
	v_mfma_f32_16x16x32_bf16 v[80:83], v[224:227], v[180:183], 0
	v_mfma_f32_16x16x32_bf16 v[76:79], v[216:219], v[200:203], 0
	v_mfma_f32_16x16x32_bf16 v[72:75], v[224:227], v[200:203], 0
	v_mfma_f32_16x16x32_bf16 v[68:71], v[216:219], v[208:211], 0
	v_mfma_f32_16x16x32_bf16 v[64:67], v[224:227], v[208:211], 0
	v_mfma_f32_16x16x32_bf16 v[92:95], v[220:223], v[176:179], v[92:95]
	v_mfma_f32_16x16x32_bf16 v[88:91], v[228:231], v[176:179], v[88:91]
	v_mfma_f32_16x16x32_bf16 v[84:87], v[220:223], v[196:199], v[84:87]
	v_mfma_f32_16x16x32_bf16 v[80:83], v[228:231], v[196:199], v[80:83]
	v_mfma_f32_16x16x32_bf16 v[76:79], v[220:223], v[204:207], v[76:79]
	v_mfma_f32_16x16x32_bf16 v[72:75], v[228:231], v[204:207], v[72:75]
	v_mfma_f32_16x16x32_bf16 v[68:71], v[220:223], v[212:215], v[68:71]
	v_mfma_f32_16x16x32_bf16 v[64:67], v[228:231], v[212:215], v[64:67]
	s_setprio 0
	s_mov_b32 m0, s5
	s_barrier
	ds_read_b128 v[172:175], v148 offset:16384
	ds_read_b128 v[176:179], v148 offset:17408
	ds_read_b128 v[180:183], v148 offset:18432
	ds_read_b128 v[196:199], v148 offset:19456
	ds_read_b128 v[200:203], v148 offset:20480
	ds_read_b128 v[204:207], v148 offset:21504
	ds_read_b128 v[208:211], v148 offset:22528
	ds_read_b128 v[212:215], v148 offset:23552
	global_load_lds_dwordx4 v232, s[14:15]
	s_mov_b32 m0, s24
	s_nop 0
	global_load_lds_dwordx4 v233, s[14:15]
	s_barrier
	s_waitcnt lgkmcnt(0)
	s_setprio 1
	s_waitcnt lgkmcnt(0)
	v_mfma_f32_16x16x32_bf16 v[60:63], v[156:159], v[172:175], 0
	v_mfma_f32_16x16x32_bf16 v[56:59], v[164:167], v[172:175], 0
	v_mfma_f32_16x16x32_bf16 v[52:55], v[156:159], v[180:183], 0
	v_mfma_f32_16x16x32_bf16 v[48:51], v[164:167], v[180:183], 0
	v_mfma_f32_16x16x32_bf16 v[44:47], v[156:159], v[200:203], 0
	v_mfma_f32_16x16x32_bf16 v[40:43], v[164:167], v[200:203], 0
	v_mfma_f32_16x16x32_bf16 v[36:39], v[156:159], v[208:211], 0
	v_mfma_f32_16x16x32_bf16 v[32:35], v[164:167], v[208:211], 0
	v_mfma_f32_16x16x32_bf16 v[60:63], v[160:163], v[176:179], v[60:63]
	v_mfma_f32_16x16x32_bf16 v[56:59], v[168:171], v[176:179], v[56:59]
	v_mfma_f32_16x16x32_bf16 v[52:55], v[160:163], v[196:199], v[52:55]
	v_mfma_f32_16x16x32_bf16 v[48:51], v[168:171], v[196:199], v[48:51]
	v_mfma_f32_16x16x32_bf16 v[44:47], v[160:163], v[204:207], v[44:47]
	v_mfma_f32_16x16x32_bf16 v[40:43], v[168:171], v[204:207], v[40:43]
	v_mfma_f32_16x16x32_bf16 v[36:39], v[160:163], v[212:215], v[36:39]
	v_mfma_f32_16x16x32_bf16 v[32:35], v[168:171], v[212:215], v[32:35]
	s_setprio 0
	s_barrier
; #define WAIT_V(n) asm volatile("s_waitcnt vmcnt(%0)" ::"n"(n) : "memory")
; #define WAIT_L(n) asm volatile("s_waitcnt lgkmcnt(%0)" ::"n"(n) : "memory")
; #define SBAR() __builtin_amdgcn_sched_barrier(0)
; #define STAGE(P, base, kt) do { _Pragma("unroll") for (int _i = 0; _i < 2; ++_i)                                        \
;       __builtin_amdgcn_global_load_lds((const unsigned*)((base) + (size_t)(sOff[_i] + (unsigned)(kt) * (BK * 2))),        \
;                                        (unsigned*)((P) + wid * 1024 + _i * 8192), 16, 0, 0); } while (0)
; #define LDA(dst, b, h) _Pragma("unroll") for (int m = 0; m < 4; ++m) _Pragma("unroll") for (int k = 0; k < 2; ++k) \
;       dst[m][k] = *(const bf16x8*)(SA(b, h) + aoff + (m * 2048 + k * 1024))
; #define LDB(dst, b, h) _Pragma("unroll") for (int n = 0; n < 2; ++n) _Pragma("unroll") for (int k = 0; k < 2; ++k) \
;       dst[n][k] = *(const bf16x8*)(SB(b, h) + boff + (n * 256 + k * 1024))
; #define BAR __builtin_amdgcn_s_barrier()
; template <int EPI, int N, int K>
; __device__ __forceinline__ void phase_gemm(const Params& p, const u16* __restrict__ A, const u16* __restrict__ Bt, int nM, char* shm,
;                            u16* __restrict__ outp, float* __restrict__ rowss) {
;     ...
;       WAIT_V(6); BAR; MMA(1, 1, At, B1); BAR;
;       LDB(B0, 1, 0); SBAR(); LDA(At, 1, 0); STAGE(SA(0, 1), A1, t + 2);
;       WAIT_L(8); BAR; WAIT_L(0); MMA(0, 0, At, B0); BAR; SBAR();
;       LDB(B1, 1, 1); STAGE(SB(1, 0), B0p, t + 3);
;       BAR; WAIT_L(0); MMA(0, 1, At, B1); BAR;
	s_mov_b32 m0, s28
	s_nop 0
	global_load_lds_dwordx4 v232, s[22:23]
	s_mov_b32 m0, s29
	s_nop 0
	global_load_lds_dwordx4 v233, s[22:23]
	s_waitcnt vmcnt(6)
	s_barrier
	s_setprio 1
	v_mfma_f32_16x16x32_bf16 v[28:31], v[216:219], v[172:175], 0
	v_mfma_f32_16x16x32_bf16 v[24:27], v[224:227], v[172:175], 0
	v_mfma_f32_16x16x32_bf16 v[20:23], v[216:219], v[180:183], 0
	v_mfma_f32_16x16x32_bf16 v[16:19], v[224:227], v[180:183], 0
	v_mfma_f32_16x16x32_bf16 v[12:15], v[216:219], v[200:203], 0
	v_mfma_f32_16x16x32_bf16 v[8:11], v[224:227], v[200:203], 0
	v_mfma_f32_16x16x32_bf16 v[4:7], v[216:219], v[208:211], 0
	v_mfma_f32_16x16x32_bf16 v[0:3], v[224:227], v[208:211], 0
	v_mfma_f32_16x16x32_bf16 v[28:31], v[220:223], v[176:179], v[28:31]
	v_mfma_f32_16x16x32_bf16 v[24:27], v[228:231], v[176:179], v[24:27]
	v_mfma_f32_16x16x32_bf16 v[20:23], v[220:223], v[196:199], v[20:23]
	v_mfma_f32_16x16x32_bf16 v[16:19], v[228:231], v[196:199], v[16:19]
	v_mfma_f32_16x16x32_bf16 v[12:15], v[220:223], v[204:207], v[12:15]
	v_mfma_f32_16x16x32_bf16 v[8:11], v[228:231], v[204:207], v[8:11]
	v_mfma_f32_16x16x32_bf16 v[4:7], v[220:223], v[212:215], v[4:7]
	v_mfma_f32_16x16x32_bf16 v[0:3], v[228:231], v[212:215], v[0:3]
	s_setprio 0
	v_or_b32_e32 v156, 0x18000, v147
	v_add_u32_e32 v158, 0x18100, v147
	s_barrier
	v_add_u32_e32 v157, 0x18400, v147
	ds_read_b128 v[164:167], v156
	ds_read_b128 v[168:171], v157
	v_add_u32_e32 v159, 0x18500, v147
	ds_read_b128 v[172:175], v158
	ds_read_b128 v[176:179], v159
	s_mov_b32 m0, s30
	ds_read_b128 v[180:183], v148 offset:32768
	ds_read_b128 v[196:199], v148 offset:33792
	ds_read_b128 v[200:203], v148 offset:34816
	ds_read_b128 v[204:207], v148 offset:35840
	ds_read_b128 v[208:211], v148 offset:36864
	ds_read_b128 v[212:215], v148 offset:37888
	ds_read_b128 v[216:219], v148 offset:38912
	ds_read_b128 v[220:223], v148 offset:39936
	global_load_lds_dwordx4 v232, s[6:7]
	s_mov_b32 m0, s31
	s_nop 0
	global_load_lds_dwordx4 v233, s[6:7]
	s_waitcnt lgkmcnt(8)
	s_barrier
	s_waitcnt lgkmcnt(0)
	s_setprio 1
	s_waitcnt lgkmcnt(0)
	v_mfma_f32_16x16x32_bf16 v[126:129], v[164:167], v[180:183], v[126:129]
	v_mfma_f32_16x16x32_bf16 v[122:125], v[172:175], v[180:183], v[122:125]
	v_mfma_f32_16x16x32_bf16 v[118:121], v[164:167], v[200:203], v[118:121]
	v_mfma_f32_16x16x32_bf16 v[114:117], v[172:175], v[200:203], v[114:117]
	v_mfma_f32_16x16x32_bf16 v[110:113], v[164:167], v[208:211], v[110:113]
	v_mfma_f32_16x16x32_bf16 v[106:109], v[172:175], v[208:211], v[106:109]
	v_mfma_f32_16x16x32_bf16 v[102:105], v[164:167], v[216:219], v[102:105]
	v_mfma_f32_16x16x32_bf16 v[98:101], v[172:175], v[216:219], v[98:101]
	v_mfma_f32_16x16x32_bf16 v[126:129], v[168:171], v[196:199], v[126:129]
	v_mfma_f32_16x16x32_bf16 v[122:125], v[176:179], v[196:199], v[122:125]
	v_mfma_f32_16x16x32_bf16 v[118:121], v[168:171], v[204:207], v[118:121]
	v_mfma_f32_16x16x32_bf16 v[114:117], v[176:179], v[204:207], v[114:117]
	v_mfma_f32_16x16x32_bf16 v[110:113], v[168:171], v[212:215], v[110:113]
	v_mfma_f32_16x16x32_bf16 v[106:109], v[176:179], v[212:215], v[106:109]
	v_mfma_f32_16x16x32_bf16 v[102:105], v[168:171], v[220:223], v[102:105]
	v_mfma_f32_16x16x32_bf16 v[98:101], v[176:179], v[220:223], v[98:101]
	s_setprio 0
	s_barrier
	s_mov_b32 m0, s33
	v_or_b32_e32 v160, 0x1c000, v147
	v_add_u32_e32 v162, 0x1c100, v147
	v_add_u32_e32 v240, 0x180, v240
	v_add_u32_e32 v161, 0x1c400, v147
	ds_read_b128 v[224:227], v160
	ds_read_b128 v[228:231], v161
	v_add_u32_e32 v163, 0x1c500, v147
	ds_read_b128 v[232:235], v162
	ds_read_b128 v[236:239], v163
	global_load_lds_dwordx4 v240, s[12:13]
	v_add_u32_e32 v241, 0x180, v241
	s_mov_b32 m0, s35
	s_nop 0
	global_load_lds_dwordx4 v241, s[12:13]
	s_barrier
; #define WAIT_V(n) asm volatile("s_waitcnt vmcnt(%0)" ::"n"(n) : "memory")
; #define WAIT_L(n) asm volatile("s_waitcnt lgkmcnt(%0)" ::"n"(n) : "memory")
; #define SBAR() __builtin_amdgcn_sched_barrier(0)
; #define STAGE(P, base, kt) do { _Pragma("unroll") for (int _i = 0; _i < 2; ++_i)                                        \
;       __builtin_amdgcn_global_load_lds((const unsigned*)((base) + (size_t)(sOff[_i] + (unsigned)(kt) * (BK * 2))),        \
;                                        (unsigned*)((P) + wid * 1024 + _i * 8192), 16, 0, 0); } while (0)
; #define LDA(dst, b, h) _Pragma("unroll") for (int m = 0; m < 4; ++m) _Pragma("unroll") for (int k = 0; k < 2; ++k) \
;       dst[m][k] = *(const bf16x8*)(SA(b, h) + aoff + (m * 2048 + k * 1024))
; #define BAR __builtin_amdgcn_s_barrier()
; template <int EPI, int N, int K>
; __device__ __forceinline__ void phase_gemm(const Params& p, const u16* __restrict__ A, const u16* __restrict__ Bt, int nM, char* shm,
;                            u16* __restrict__ outp, float* __restrict__ rowss) {
;     ...
;       BAR; WAIT_L(0); MMA(0, 1, At, B1); BAR;
;       LDA(At, 1, 1); STAGE(SA(1, 0), A0, t + 3);
;       BAR; WAIT_L(0); MMA(1, 0, At, B0); BAR; SBAR();
;       STAGE(SB(1, 1), B1p, t + 3);
;       WAIT_V(6); BAR; MMA(1, 1, At, B1); BAR;
;     }
	s_waitcnt lgkmcnt(0)
	s_setprio 1
	s_waitcnt lgkmcnt(0)
	v_mfma_f32_16x16x32_bf16 v[92:95], v[224:227], v[180:183], v[92:95]
	v_mfma_f32_16x16x32_bf16 v[88:91], v[232:235], v[180:183], v[88:91]
	v_mfma_f32_16x16x32_bf16 v[84:87], v[224:227], v[200:203], v[84:87]
	v_mfma_f32_16x16x32_bf16 v[80:83], v[232:235], v[200:203], v[80:83]
	v_mfma_f32_16x16x32_bf16 v[76:79], v[224:227], v[208:211], v[76:79]
	v_mfma_f32_16x16x32_bf16 v[72:75], v[232:235], v[208:211], v[72:75]
	v_mfma_f32_16x16x32_bf16 v[68:71], v[224:227], v[216:219], v[68:71]
	v_mfma_f32_16x16x32_bf16 v[64:67], v[232:235], v[216:219], v[64:67]
	v_mfma_f32_16x16x32_bf16 v[92:95], v[228:231], v[196:199], v[92:95]
	v_mfma_f32_16x16x32_bf16 v[88:91], v[236:239], v[196:199], v[88:91]
	v_mfma_f32_16x16x32_bf16 v[84:87], v[228:231], v[204:207], v[84:87]
	v_mfma_f32_16x16x32_bf16 v[80:83], v[236:239], v[204:207], v[80:83]
	v_mfma_f32_16x16x32_bf16 v[76:79], v[228:231], v[212:215], v[76:79]
	v_mfma_f32_16x16x32_bf16 v[72:75], v[236:239], v[212:215], v[72:75]
	v_mfma_f32_16x16x32_bf16 v[68:71], v[228:231], v[220:223], v[68:71]
	v_mfma_f32_16x16x32_bf16 v[64:67], v[236:239], v[220:223], v[64:67]
	s_setprio 0
	s_mov_b32 m0, s92
	s_barrier
	ds_read_b128 v[180:183], v148 offset:49152
	ds_read_b128 v[196:199], v148 offset:50176
	ds_read_b128 v[200:203], v148 offset:51200
	ds_read_b128 v[204:207], v148 offset:52224
	ds_read_b128 v[208:211], v148 offset:53248
	ds_read_b128 v[212:215], v148 offset:54272
	ds_read_b128 v[216:219], v148 offset:55296
	ds_read_b128 v[220:223], v148 offset:56320
	global_load_lds_dwordx4 v240, s[14:15]
	s_mov_b32 m0, s93
	s_nop 0
	global_load_lds_dwordx4 v241, s[14:15]
	s_barrier
	s_waitcnt lgkmcnt(0)
	s_setprio 1
	s_waitcnt lgkmcnt(0)
	v_mfma_f32_16x16x32_bf16 v[60:63], v[164:167], v[180:183], v[60:63]
	v_mfma_f32_16x16x32_bf16 v[56:59], v[172:175], v[180:183], v[56:59]
	v_mfma_f32_16x16x32_bf16 v[52:55], v[164:167], v[200:203], v[52:55]
	v_mfma_f32_16x16x32_bf16 v[48:51], v[172:175], v[200:203], v[48:51]
	v_mfma_f32_16x16x32_bf16 v[44:47], v[164:167], v[208:211], v[44:47]
	v_mfma_f32_16x16x32_bf16 v[40:43], v[172:175], v[208:211], v[40:43]
	v_mfma_f32_16x16x32_bf16 v[36:39], v[164:167], v[216:219], v[36:39]
	v_mfma_f32_16x16x32_bf16 v[32:35], v[172:175], v[216:219], v[32:35]
	v_mfma_f32_16x16x32_bf16 v[60:63], v[168:171], v[196:199], v[60:63]
	v_mfma_f32_16x16x32_bf16 v[56:59], v[176:179], v[196:199], v[56:59]
	v_mfma_f32_16x16x32_bf16 v[52:55], v[168:171], v[204:207], v[52:55]
	v_mfma_f32_16x16x32_bf16 v[48:51], v[176:179], v[204:207], v[48:51]
	v_mfma_f32_16x16x32_bf16 v[44:47], v[168:171], v[212:215], v[44:47]
	v_mfma_f32_16x16x32_bf16 v[40:43], v[176:179], v[212:215], v[40:43]
	v_mfma_f32_16x16x32_bf16 v[36:39], v[168:171], v[220:223], v[36:39]
	v_mfma_f32_16x16x32_bf16 v[32:35], v[176:179], v[220:223], v[32:35]
	s_setprio 0
	s_barrier
	s_mov_b32 m0, s52
	s_nop 0
	global_load_lds_dwordx4 v240, s[22:23]
	s_mov_b32 m0, s53
	s_nop 0
	global_load_lds_dwordx4 v241, s[22:23]
	s_waitcnt vmcnt(6)
	s_barrier
	s_setprio 1
	v_mfma_f32_16x16x32_bf16 v[28:31], v[224:227], v[180:183], v[28:31]
	v_mfma_f32_16x16x32_bf16 v[24:27], v[232:235], v[180:183], v[24:27]
	v_mfma_f32_16x16x32_bf16 v[20:23], v[224:227], v[200:203], v[20:23]
	v_mfma_f32_16x16x32_bf16 v[16:19], v[232:235], v[200:203], v[16:19]
	v_mfma_f32_16x16x32_bf16 v[12:15], v[224:227], v[208:211], v[12:15]
	v_mfma_f32_16x16x32_bf16 v[8:11], v[232:235], v[208:211], v[8:11]
	v_mfma_f32_16x16x32_bf16 v[4:7], v[224:227], v[216:219], v[4:7]
	v_mfma_f32_16x16x32_bf16 v[0:3], v[232:235], v[216:219], v[0:3]
	v_mfma_f32_16x16x32_bf16 v[28:31], v[228:231], v[196:199], v[28:31]
	v_mfma_f32_16x16x32_bf16 v[24:27], v[236:239], v[196:199], v[24:27]
	v_mfma_f32_16x16x32_bf16 v[20:23], v[228:231], v[204:207], v[20:23]
	v_mfma_f32_16x16x32_bf16 v[16:19], v[236:239], v[204:207], v[16:19]
	v_mfma_f32_16x16x32_bf16 v[12:15], v[228:231], v[212:215], v[12:15]
	v_mfma_f32_16x16x32_bf16 v[8:11], v[236:239], v[212:215], v[8:11]
	v_mfma_f32_16x16x32_bf16 v[4:7], v[228:231], v[220:223], v[4:7]
	v_mfma_f32_16x16x32_bf16 v[0:3], v[236:239], v[220:223], v[0:3]
	s_setprio 0
	s_add_i32 s59, s59, 2
	v_add_u32_e32 v142, 0x100, v142
	s_cmp_lt_u32 s59, 12
	v_add_u32_e32 v96, 0x100, v96
	s_barrier

; #define SBAR() __builtin_amdgcn_sched_barrier(0)
; template <int D0> __device__ __forceinline__ void pv_one(f32x16& od, int vb, bf16x8 pa0, bf16x8 pa1, bf16x8 pa2, bf16x8 pa3) {
;   const s16x4 l0 = tr_read<v_rd_off(D0, 0, 0)>(vb), h0 = tr_read<v_rd_off(D0, 0, 1)>(vb), l1 = tr_read<v_rd_off(D0, 1, 0)>(vb), h1 = tr_read<v_rd_off(D0, 1, 1)>(vb);
;   const s16x4 l2 = tr_read<v_rd_off(D0, 2, 0)>(vb), h2 = tr_read<v_rd_off(D0, 2, 1)>(vb), l3 = tr_read<v_rd_off(D0, 3, 0)>(vb), h3 = tr_read<v_rd_off(D0, 3, 1)>(vb);
;   asm volatile("s_waitcnt lgkmcnt(0)" ::: "memory"); SBAR();
;     ...
;   od = __builtin_amdgcn_mfma_f32_32x32x16_bf16(pa0, PK(l0, h0), od, 0, 0, 0);
;   od = __builtin_amdgcn_mfma_f32_32x32x16_bf16(pa1, PK(l1, h1), od, 0, 0, 0);
;   od = __builtin_amdgcn_mfma_f32_32x32x16_bf16(pa2, PK(l2, h2), od, 0, 0, 0);
;   od = __builtin_amdgcn_mfma_f32_32x32x16_bf16(pa3, PK(l3, h3), od, 0, 0, 0);
; __device__ __forceinline__ void da_partial2(f32x16& p0, f32x16& p1, float m_reg) {
;   constexpr float C = DA_SCALE * 1.4426950408889634f;
;   const float mnC = -m_reg * C;
; #pragma unroll
;   for (int r = 0; r < 16; ++r) p0[r] = fmaf(p0[r], C, mnC);
; #pragma unroll
;   for (int r = 0; r < 16; ++r) p1[r] = fmaf(p1[r], C, mnC);
; #pragma unroll
;   for (int r = 0; r < 16; ++r) p0[r] = __builtin_amdgcn_exp2f(p0[r]);
; }
.LBB0_244:
	v_add_u32_e32 v130, 0xfffd0000, v227
	v_add_u32_e32 v134, 0xfffe0000, v227
	global_load_dwordx4 v[138:141], v130, s[8:9]
	s_nop 0
	global_load_dwordx4 v[130:133], v130, s[2:3]
	s_nop 0
	global_load_dwordx4 v[142:145], v134, s[8:9]
	s_nop 0
	global_load_dwordx4 v[134:137], v134, s[2:3]
	v_add_u32_e32 v224, s10, v214
	ds_read_b64_tr_b16 v[166:167], v224 offset:0
	ds_read_b64_tr_b16 v[168:169], v224 offset:0x800
	ds_read_b64_tr_b16 v[170:171], v224 offset:0x1000
	ds_read_b64_tr_b16 v[172:173], v224 offset:0x1800
	ds_read_b64_tr_b16 v[174:175], v224 offset:0x2000
	ds_read_b64_tr_b16 v[176:177], v224 offset:0x2800
	ds_read_b64_tr_b16 v[178:179], v224 offset:0x3000
	ds_read_b64_tr_b16 v[180:181], v224 offset:0x3800
	s_waitcnt lgkmcnt(0)
	s_nop 0
	v_mfma_f32_32x32x16_bf16 v[0:15], v[146:149], v[166:169], v[0:15]
	ds_read_b64_tr_b16 v[166:167], v224 offset:0x200
	ds_read_b64_tr_b16 v[168:169], v224 offset:0xa00
	v_mfma_f32_32x32x16_bf16 v[0:15], v[150:153], v[170:173], v[0:15]
	ds_read_b64_tr_b16 v[170:171], v224 offset:0x1200
	ds_read_b64_tr_b16 v[172:173], v224 offset:0x1a00
	v_mfma_f32_32x32x16_bf16 v[0:15], v[154:157], v[174:177], v[0:15]
	ds_read_b64_tr_b16 v[174:175], v224 offset:0x2200
	ds_read_b64_tr_b16 v[176:177], v224 offset:0x2a00
	v_mfma_f32_32x32x16_bf16 v[0:15], v[158:161], v[178:181], v[0:15]
	ds_read_b64_tr_b16 v[178:179], v224 offset:0x3200
	ds_read_b64_tr_b16 v[180:181], v224 offset:0x3a00
	s_waitcnt vmcnt(4)
	v_add_u32_e32 v228, s4, v216
	ds_write_b128 v228, v[126:129]
	s_waitcnt lgkmcnt(1)
	v_mfma_f32_32x32x16_bf16 v[16:31], v[146:149], v[166:169], v[16:31]
	ds_read_b64_tr_b16 v[166:167], v224 offset:0x400
	ds_read_b64_tr_b16 v[168:169], v224 offset:0xc00
	v_mul_f32_e32 v196, 0xbe38aa3b, v213
	v_fmamk_f32 v80, v80, 0x3e38aa3b, v196
	v_fmamk_f32 v81, v81, 0x3e38aa3b, v196
	v_fmamk_f32 v82, v82, 0x3e38aa3b, v196
	v_mfma_f32_32x32x16_bf16 v[16:31], v[150:153], v[170:173], v[16:31]
	ds_read_b64_tr_b16 v[170:171], v224 offset:0x1400
	ds_read_b64_tr_b16 v[172:173], v224 offset:0x1c00
	v_fmamk_f32 v83, v83, 0x3e38aa3b, v196
	v_fmamk_f32 v84, v84, 0x3e38aa3b, v196
	v_fmamk_f32 v85, v85, 0x3e38aa3b, v196
	v_fmamk_f32 v86, v86, 0x3e38aa3b, v196
	v_mfma_f32_32x32x16_bf16 v[16:31], v[154:157], v[174:177], v[16:31]
	ds_read_b64_tr_b16 v[174:175], v224 offset:0x2400
	ds_read_b64_tr_b16 v[176:177], v224 offset:0x2c00
	v_fmamk_f32 v87, v87, 0x3e38aa3b, v196
	v_fmamk_f32 v88, v88, 0x3e38aa3b, v196
	v_fmamk_f32 v89, v89, 0x3e38aa3b, v196
	v_fmamk_f32 v90, v90, 0x3e38aa3b, v196
	v_mfma_f32_32x32x16_bf16 v[16:31], v[158:161], v[178:181], v[16:31]
	ds_read_b64_tr_b16 v[178:179], v224 offset:0x3400
	ds_read_b64_tr_b16 v[180:181], v224 offset:0x3c00
	v_fmamk_f32 v91, v91, 0x3e38aa3b, v196
	v_fmamk_f32 v92, v92, 0x3e38aa3b, v196
	v_fmamk_f32 v93, v93, 0x3e38aa3b, v196
	v_fmamk_f32 v94, v94, 0x3e38aa3b, v196
	v_add_u32_e32 v228, s4, v217
	ds_write_b128 v228, v[122:125]
	s_waitcnt lgkmcnt(1)
	v_mfma_f32_32x32x16_bf16 v[32:47], v[146:149], v[166:169], v[32:47]
	ds_read_b64_tr_b16 v[166:167], v224 offset:0x600
	ds_read_b64_tr_b16 v[168:169], v224 offset:0xe00
	v_fmamk_f32 v95, v95, 0x3e38aa3b, v196
	v_fmamk_f32 v197, v70, 0x3e38aa3b, v196
	v_fmamk_f32 v198, v71, 0x3e38aa3b, v196
	v_fmamk_f32 v199, v72, 0x3e38aa3b, v196
	v_mfma_f32_32x32x16_bf16 v[32:47], v[150:153], v[170:173], v[32:47]
	ds_read_b64_tr_b16 v[170:171], v224 offset:0x1600
	ds_read_b64_tr_b16 v[172:173], v224 offset:0x1e00
	v_fmamk_f32 v200, v73, 0x3e38aa3b, v196
	v_fmamk_f32 v201, v74, 0x3e38aa3b, v196
	v_fmamk_f32 v202, v75, 0x3e38aa3b, v196
	v_fmamk_f32 v203, v76, 0x3e38aa3b, v196
	v_mfma_f32_32x32x16_bf16 v[32:47], v[154:157], v[174:177], v[32:47]
	ds_read_b64_tr_b16 v[174:175], v224 offset:0x2600
	ds_read_b64_tr_b16 v[176:177], v224 offset:0x2e00
	v_fmamk_f32 v204, v77, 0x3e38aa3b, v196
	v_fmamk_f32 v205, v78, 0x3e38aa3b, v196
	v_mfma_f32_32x32x16_bf16 v[32:47], v[158:161], v[178:181], v[32:47]
	ds_read_b64_tr_b16 v[178:179], v224 offset:0x3600
	ds_read_b64_tr_b16 v[180:181], v224 offset:0x3e00
	v_add_u32_e32 v228, s4, v221
	ds_write_b128 v228, v[118:121] offset:49152
	s_waitcnt lgkmcnt(1)
	v_mfma_f32_32x32x16_bf16 v[48:63], v[146:149], v[166:169], v[48:63]
	v_add_u32_e32 v228, s4, v222
	ds_write_b128 v228, v[114:117] offset:49152
	v_exp_f32_e32 v146, v80
	v_exp_f32_e32 v147, v81
	v_exp_f32_e32 v148, v84
	v_exp_f32_e32 v149, v85
	v_mfma_f32_32x32x16_bf16 v[48:63], v[150:153], v[170:173], v[48:63]
	v_exp_f32_e32 v150, v88
	v_exp_f32_e32 v151, v89
	v_exp_f32_e32 v152, v92
	v_exp_f32_e32 v153, v93
	v_mfma_f32_32x32x16_bf16 v[48:63], v[154:157], v[174:177], v[48:63]
	v_exp_f32_e32 v154, v94
	v_exp_f32_e32 v155, v95
	v_exp_f32_e32 v156, v90
	v_exp_f32_e32 v157, v91
	v_fmamk_f32 v174, v64, 0x3e38aa3b, v196
	v_fmamk_f32 v175, v65, 0x3e38aa3b, v196
	v_mfma_f32_32x32x16_bf16 v[48:63], v[158:161], v[178:181], v[48:63]
	v_exp_f32_e32 v158, v86
	v_exp_f32_e32 v159, v87
	v_exp_f32_e32 v160, v82
	v_exp_f32_e32 v161, v83
	v_fmamk_f32 v178, v66, 0x3e38aa3b, v196
	v_fmamk_f32 v179, v67, 0x3e38aa3b, v196
	v_fmamk_f32 v180, v68, 0x3e38aa3b, v196
	v_fmamk_f32 v181, v69, 0x3e38aa3b, v196
	v_fmac_f32_e32 v196, 0x3e38aa3b, v79
	s_waitcnt lgkmcnt(0)
	s_barrier
; __device__ __forceinline__ void da_qkt(f32x16& p0, f32x16& p1, const char* Ks, const bf16x8* qr, int r32, int hi, int cbyte0) {
;   p0 = f32x16{}; p1 = f32x16{};
; #pragma unroll
;   for (int d0 = 0; d0 < 4; ++d0) {
;     int cbb = cbyte0 + (d0 * 16 + hi * 8) * 2;
;     bf16x8 b0 = *(const bf16x8*)(Ks + KSWZ(r32, cbb));
;     bf16x8 b1 = *(const bf16x8*)(Ks + KSWZ(32 + r32, cbb));
;     p0 = __builtin_amdgcn_mfma_f32_32x32x16_bf16(b0, qr[d0], p0, 0, 0, 0);
;     p1 = __builtin_amdgcn_mfma_f32_32x32x16_bf16(b1, qr[d0], p1, 0, 0, 0);
;   }
; __device__ __forceinline__ void da_finish2(f32x16& p0, f32x16& p1, float& m_reg, float& l_reg, float& alpha,
;                                            bf16x8& pa0, bf16x8& pa1, bf16x8& pa2, bf16x8& pa3) {
;   constexpr float C = DA_SCALE * 1.4426950408889634f;
; #pragma unroll
;   for (int r = 0; r < 16; ++r) p1[r] = __builtin_amdgcn_exp2f(p1[r]);
;   float ps = 0.f;
; #pragma unroll
;   for (int r = 0; r < 16; ++r) ps += p0[r];
; #pragma unroll
;   for (int r = 0; r < 16; ++r) ps += p1[r];
;   { auto rr = __builtin_amdgcn_permlane32_swap(__float_as_uint(ps), __float_as_uint(ps), false, false);
;     ps = __uint_as_float(rr[0]) + __uint_as_float(rr[1]); }
;   alpha = 1.f;
;   if (__builtin_expect(!__all(ps < DA_BIG), 0)) {
	v_add_u32_e32 v68, s4, v223
	ds_read_b128 v[64:67], v68 offset:49152
	ds_read_b128 v[68:71], v68 offset:57344
	v_add_u32_e32 v170, s4, v220
	ds_read_b128 v[166:169], v170 offset:49152
	ds_read_b128 v[170:173], v170 offset:57344
	v_exp_f32_e32 v176, v174
	s_waitcnt lgkmcnt(3)
	v_mfma_f32_32x32x16_bf16 v[80:95], v[64:67], v[110:113], 0
	v_exp_f32_e32 v177, v175
	v_exp_f32_e32 v182, v178
	v_exp_f32_e32 v183, v179
	v_exp_f32_e32 v180, v180
	v_exp_f32_e32 v181, v181
	v_exp_f32_e32 v178, v197
	v_exp_f32_e32 v179, v198
	s_waitcnt lgkmcnt(2)
	v_mfma_f32_32x32x16_bf16 v[64:79], v[68:71], v[110:113], 0
	v_exp_f32_e32 v174, v199
	v_exp_f32_e32 v175, v200
	s_waitcnt lgkmcnt(1)
	v_mfma_f32_32x32x16_bf16 v[80:95], v[166:169], v[106:109], v[80:95]
	s_waitcnt lgkmcnt(0)
	v_mfma_f32_32x32x16_bf16 v[64:79], v[170:173], v[106:109], v[64:79]
	v_add_u32_e32 v170, s4, v219
	ds_read_b128 v[166:169], v170 offset:49152
	ds_read_b128 v[170:173], v170 offset:57344
	s_waitcnt lgkmcnt(1)
	v_mfma_f32_32x32x16_bf16 v[80:95], v[166:169], v[102:105], v[80:95]
	s_waitcnt lgkmcnt(0)
	v_mfma_f32_32x32x16_bf16 v[64:79], v[170:173], v[102:105], v[64:79]
	v_add_u32_e32 v170, s4, v218
	ds_read_b128 v[166:169], v170 offset:49152
	ds_read_b128 v[170:173], v170 offset:57344
	s_waitcnt lgkmcnt(1)
	v_mfma_f32_32x32x16_bf16 v[80:95], v[166:169], v[98:101], v[80:95]
	v_add_f32_e32 v166, 0, v146
	v_add_f32_e32 v166, v147, v166
	v_add_f32_e32 v166, v160, v166
	v_add_f32_e32 v166, v161, v166
	v_add_f32_e32 v166, v148, v166
	v_add_f32_e32 v166, v149, v166
	v_add_f32_e32 v166, v158, v166
	v_add_f32_e32 v166, v159, v166
	v_add_f32_e32 v166, v150, v166
	v_add_f32_e32 v166, v151, v166
	v_add_f32_e32 v166, v156, v166
	v_add_f32_e32 v166, v157, v166
	v_add_f32_e32 v166, v152, v166
	v_add_f32_e32 v166, v153, v166
	v_add_f32_e32 v166, v154, v166
	v_add_f32_e32 v166, v155, v166
	v_add_f32_e32 v166, v176, v166
	v_add_f32_e32 v166, v177, v166
	v_add_f32_e32 v166, v182, v166
	v_add_f32_e32 v166, v183, v166
	v_add_f32_e32 v166, v180, v166
	v_add_f32_e32 v166, v181, v166
	s_waitcnt lgkmcnt(0)
	v_mfma_f32_32x32x16_bf16 v[64:79], v[170:173], v[98:101], v[64:79]
	v_exp_f32_e32 v172, v201
	v_add_f32_e32 v166, v178, v166
	v_exp_f32_e32 v173, v202
	v_add_f32_e32 v166, v179, v166
	v_exp_f32_e32 v170, v203
	v_add_f32_e32 v166, v174, v166
	v_exp_f32_e32 v171, v204
	v_add_f32_e32 v166, v175, v166
	v_exp_f32_e32 v168, v205
	v_add_f32_e32 v166, v172, v166
	v_exp_f32_e32 v169, v196
	v_add_f32_e32 v166, v173, v166
	v_add_f32_e32 v166, v170, v166
	v_add_f32_e32 v166, v171, v166
	v_add_f32_e32 v166, v168, v166
	v_add_f32_e32 v166, v169, v166
	v_mov_b32_e32 v167, v166
	s_nop 1
	v_permlane32_swap_b32_e32 v166, v167
	v_add_f32_e32 v225, v166, v167
	v_cmp_gt_f32_e32 vcc, s34, v225
	s_cmp_eq_u64 vcc, exec
	s_cbranch_scc0 .LBB0_255
	v_mov_b32_e32 v166, 1.0

; #define SBAR() __builtin_amdgcn_sched_barrier(0)
; template <int D0> __device__ __forceinline__ void pv_one(f32x16& od, int vb, bf16x8 pa0, bf16x8 pa1, bf16x8 pa2, bf16x8 pa3) {
;   const s16x4 l0 = tr_read<v_rd_off(D0, 0, 0)>(vb), h0 = tr_read<v_rd_off(D0, 0, 1)>(vb), l1 = tr_read<v_rd_off(D0, 1, 0)>(vb), h1 = tr_read<v_rd_off(D0, 1, 1)>(vb);
;   const s16x4 l2 = tr_read<v_rd_off(D0, 2, 0)>(vb), h2 = tr_read<v_rd_off(D0, 2, 1)>(vb), l3 = tr_read<v_rd_off(D0, 3, 0)>(vb), h3 = tr_read<v_rd_off(D0, 3, 1)>(vb);
;   asm volatile("s_waitcnt lgkmcnt(0)" ::: "memory"); SBAR();
;     ...
;   od = __builtin_amdgcn_mfma_f32_32x32x16_bf16(pa0, PK(l0, h0), od, 0, 0, 0);
;   od = __builtin_amdgcn_mfma_f32_32x32x16_bf16(pa1, PK(l1, h1), od, 0, 0, 0);
;   od = __builtin_amdgcn_mfma_f32_32x32x16_bf16(pa2, PK(l2, h2), od, 0, 0, 0);
;   od = __builtin_amdgcn_mfma_f32_32x32x16_bf16(pa3, PK(l3, h3), od, 0, 0, 0);
; __device__ __forceinline__ void da_partial2(f32x16& p0, f32x16& p1, float m_reg) {
;   constexpr float C = DA_SCALE * 1.4426950408889634f;
;   const float mnC = -m_reg * C;
; #pragma unroll
;   for (int r = 0; r < 16; ++r) p0[r] = fmaf(p0[r], C, mnC);
; #pragma unroll
;   for (int r = 0; r < 16; ++r) p1[r] = fmaf(p1[r], C, mnC);
; #pragma unroll
;   for (int r = 0; r < 16; ++r) p0[r] = __builtin_amdgcn_exp2f(p0[r]);
; }
.Lda_nodrain_s:
	v_add_u32_e32 v228, s10, v216
	ds_write_b128 v228, v[138:141]
	s_waitcnt lgkmcnt(1)
	v_mfma_f32_32x32x16_bf16 v[16:31], v[146:149], v[164:167], v[16:31]
	ds_read_b64_tr_b16 v[164:165], v180 offset:0x400
	ds_read_b64_tr_b16 v[166:167], v180 offset:0xc00
	v_mul_f32_e32 v206, 0xbe38aa3b, v213
	v_fmamk_f32 v80, v80, 0x3e38aa3b, v206
	v_fmamk_f32 v81, v81, 0x3e38aa3b, v206
	v_mfma_f32_32x32x16_bf16 v[16:31], v[150:153], v[168:171], v[16:31]
	ds_read_b64_tr_b16 v[168:169], v180 offset:0x1400
	ds_read_b64_tr_b16 v[170:171], v180 offset:0x1c00
	v_fmamk_f32 v82, v82, 0x3e38aa3b, v206
	v_fmamk_f32 v83, v83, 0x3e38aa3b, v206
	v_mfma_f32_32x32x16_bf16 v[16:31], v[154:157], v[172:175], v[16:31]
	ds_read_b64_tr_b16 v[172:173], v180 offset:0x2400
	ds_read_b64_tr_b16 v[174:175], v180 offset:0x2c00
	v_fmamk_f32 v84, v84, 0x3e38aa3b, v206
	v_fmamk_f32 v85, v85, 0x3e38aa3b, v206
	v_mfma_f32_32x32x16_bf16 v[16:31], v[158:161], v[176:179], v[16:31]
	ds_read_b64_tr_b16 v[176:177], v180 offset:0x3400
	ds_read_b64_tr_b16 v[178:179], v180 offset:0x3c00
	v_fmamk_f32 v86, v86, 0x3e38aa3b, v206
	v_fmamk_f32 v87, v87, 0x3e38aa3b, v206
	v_add_u32_e32 v228, s10, v217
	ds_write_b128 v228, v[142:145]
	s_waitcnt lgkmcnt(1)
	v_mfma_f32_32x32x16_bf16 v[32:47], v[146:149], v[164:167], v[32:47]
	ds_read_b64_tr_b16 v[164:165], v180 offset:0x600
	ds_read_b64_tr_b16 v[166:167], v180 offset:0xe00
	v_fmamk_f32 v88, v88, 0x3e38aa3b, v206
	v_fmamk_f32 v89, v89, 0x3e38aa3b, v206
	v_mfma_f32_32x32x16_bf16 v[32:47], v[150:153], v[168:171], v[32:47]
	ds_read_b64_tr_b16 v[168:169], v180 offset:0x1600
	ds_read_b64_tr_b16 v[170:171], v180 offset:0x1e00
	v_fmamk_f32 v90, v90, 0x3e38aa3b, v206
	v_fmamk_f32 v91, v91, 0x3e38aa3b, v206
	v_mfma_f32_32x32x16_bf16 v[32:47], v[154:157], v[172:175], v[32:47]
	ds_read_b64_tr_b16 v[172:173], v180 offset:0x2600
	ds_read_b64_tr_b16 v[174:175], v180 offset:0x2e00
	v_fmamk_f32 v92, v92, 0x3e38aa3b, v206
	v_fmamk_f32 v93, v93, 0x3e38aa3b, v206
	v_mfma_f32_32x32x16_bf16 v[32:47], v[158:161], v[176:179], v[32:47]
	ds_read_b64_tr_b16 v[176:177], v180 offset:0x3600
	ds_read_b64_tr_b16 v[178:179], v180 offset:0x3e00
	v_fmamk_f32 v94, v94, 0x3e38aa3b, v206
	v_fmamk_f32 v95, v95, 0x3e38aa3b, v206
	v_add_u32_e32 v228, s10, v221
	ds_write_b128 v228, v[130:133] offset:49152
	s_waitcnt lgkmcnt(1)
	v_mfma_f32_32x32x16_bf16 v[48:63], v[146:149], v[164:167], v[48:63]
	v_add_u32_e32 v228, s10, v222
	ds_write_b128 v228, v[134:137] offset:49152
	v_exp_f32_e32 v146, v80
	v_exp_f32_e32 v147, v81
	v_exp_f32_e32 v148, v82
	v_exp_f32_e32 v149, v83
	v_fma_f32 v164, v78, s20, v206
	v_fma_f32 v165, v79, s20, v206
	v_fma_f32 v166, v76, s20, v206
	v_fma_f32 v167, v77, s20, v206
	v_mfma_f32_32x32x16_bf16 v[48:63], v[150:153], v[168:171], v[48:63]
	v_exp_f32_e32 v150, v84
	v_exp_f32_e32 v151, v85
	v_exp_f32_e32 v152, v92
	v_exp_f32_e32 v153, v93
	v_fma_f32 v168, v74, s20, v206
	v_fma_f32 v169, v75, s20, v206
	v_fma_f32 v170, v72, s20, v206
	v_fma_f32 v171, v73, s20, v206
	v_mfma_f32_32x32x16_bf16 v[48:63], v[154:157], v[172:175], v[48:63]
	v_exp_f32_e32 v154, v94
	v_exp_f32_e32 v155, v95
	v_exp_f32_e32 v156, v90
	v_exp_f32_e32 v157, v91
	v_fma_f32 v172, v66, s20, v206
	v_fma_f32 v173, v67, s20, v206
	v_fma_f32 v174, v70, s20, v206
	v_fma_f32 v175, v71, s20, v206
	v_mfma_f32_32x32x16_bf16 v[48:63], v[158:161], v[176:179], v[48:63]
	v_exp_f32_e32 v158, v88
	v_exp_f32_e32 v159, v89
	v_exp_f32_e32 v160, v86
	v_exp_f32_e32 v161, v87
	v_fma_f32 v176, v64, s20, v206
	v_fma_f32 v177, v65, s20, v206
	v_fma_f32 v178, v68, s20, v206
	v_fma_f32 v179, v69, s20, v206
	v_add_u32_e32 v227, 0x40000, v227
	s_waitcnt lgkmcnt(0)
	s_barrier
	s_cbranch_scc1 .LBB0_256
	s_mov_b32 s13, s0
	s_mov_b32 s0, s12
	s_mov_b32 s12, s10
	s_mov_b32 s10, s4
	v_mov_b32_e32 v226, v225
	s_branch .LBB0_239

; __device__ __forceinline__ void na_task(const Params& p, int s, int r, int h, int w, int lane, u16* Odst, const float* rpb_lds) {
;     ...
;   f32x4 o[4] = {};
;   if (!meta) {
.LBB0_361:
	s_andn2_b64 vcc, exec, s[0:1]
	s_cbranch_vccnz .LBB0_343
	s_nop 5
	v_mov_b32_e32 v0, 0
	v_ashrrev_i32_e32 v17, 31, v16
	v_mov_b32_e32 v1, v0
	v_mov_b64_e32 v[2:3], 0
	v_mov_b64_e32 v[4:5], 0
	v_mov_b64_e32 v[6:7], 0
	v_mov_b64_e32 v[8:9], 0
	v_mov_b64_e32 v[10:11], 0
	v_mov_b64_e32 v[12:13], 0
	v_mov_b64_e32 v[14:15], 0
	s_branch .LBB0_343

; #define WAIT_V(n) asm volatile("s_waitcnt vmcnt(%0)" ::"n"(n) : "memory")
; #define WAIT_L(n) asm volatile("s_waitcnt lgkmcnt(%0)" ::"n"(n) : "memory")
; #define SBAR() __builtin_amdgcn_sched_barrier(0)
; #define STAGE(P, base, kt) do { _Pragma("unroll") for (int _i = 0; _i < 2; ++_i)                                        \
;       __builtin_amdgcn_global_load_lds((const unsigned*)((base) + (size_t)(sOff[_i] + (unsigned)(kt) * (BK * 2))),        \
;                                        (unsigned*)((P) + wid * 1024 + _i * 8192), 16, 0, 0); } while (0)
; #define LDA(dst, b, h) _Pragma("unroll") for (int m = 0; m < 4; ++m) _Pragma("unroll") for (int k = 0; k < 2; ++k) \
;       dst[m][k] = *(const bf16x8*)(SA(b, h) + aoff + (m * 2048 + k * 1024))
; #define LDB(dst, b, h) _Pragma("unroll") for (int n = 0; n < 2; ++n) _Pragma("unroll") for (int k = 0; k < 2; ++k) \
;       dst[n][k] = *(const bf16x8*)(SB(b, h) + boff + (n * 256 + k * 1024))
; #define BAR __builtin_amdgcn_s_barrier()
; template <int EPI, int N, int K>
; __device__ __forceinline__ void phase_gemm(const Params& p, const u16* __restrict__ A, const u16* __restrict__ Bt, int nM, char* shm,
;                            u16* __restrict__ outp, float* __restrict__ rowss) {
;     ...
;   for (;;) {
;     const char* A1 = A0 + (size_t)128 * K * 2;
;     const char* B1p = B0p + (size_t)128 * K * 2;
;     f32x4 acc[2][2][4][2] = {};
;     bf16x8 At[4][2], B0[2][2], B1[2][2];
;     if (wr == 1) BAR;
;     WAIT_V(0); BAR;
;     BAR;
;     for (int t = 0; t < nt - 2; t += 2) {
;       LDB(B0, 0, 0); SBAR(); LDA(At, 0, 0); STAGE(SA(1, 1), A1, t + 1);
;       WAIT_L(8); BAR; WAIT_L(0); MMA(0, 0, At, B0); BAR; SBAR();
;       LDB(B1, 0, 1); STAGE(SB(0, 0), B0p, t + 2);
;       BAR; WAIT_L(0); MMA(0, 1, At, B1); BAR;
;       LDA(At, 0, 1); STAGE(SA(0, 0), A0, t + 2);
;       BAR; WAIT_L(0); MMA(1, 0, At, B0); BAR; SBAR();
;       STAGE(SB(0, 1), B1p, t + 2);
;       WAIT_V(6); BAR; MMA(1, 1, At, B1); BAR;
.LBB0_378:
	s_add_u32 s6, s18, 0x40000
	s_addc_u32 s7, s19, 0
	s_waitcnt vmcnt(0)
	s_add_u32 s8, s16, 0x40000
	s_addc_u32 s9, s17, 0
	s_mov_b32 s11, -2
	v_mov_b32_e32 v96, v153
	v_mov_b32_e32 v130, v152
	s_barrier
	s_barrier
	v_or_b32_e32 v131, 0x10000, v150
	v_add_u32_e32 v133, 0x10100, v150
	v_add_u32_e32 v132, 0x10400, v150
	ds_read_b128 v[156:159], v131
	ds_read_b128 v[160:163], v132
	v_add_u32_e32 v146, 0x10500, v150
	ds_read_b128 v[164:167], v133
	ds_read_b128 v[168:171], v146
	v_add_u32_e32 v240, v147, v96
	s_add_i32 s26, s94, 0xc000
	v_add_u32_e32 v148, 0x80, v240
	s_mov_b32 m0, s26
	v_add_u32_e32 v241, v147, v130
	s_add_i32 s25, s94, 0xe000
	ds_read_b128 v[172:175], v151
	ds_read_b128 v[176:179], v151 offset:1024
	ds_read_b128 v[180:183], v151 offset:2048
	ds_read_b128 v[196:199], v151 offset:3072
	ds_read_b128 v[200:203], v151 offset:4096
	ds_read_b128 v[204:207], v151 offset:5120
	ds_read_b128 v[208:211], v151 offset:6144
	ds_read_b128 v[212:215], v151 offset:7168
	global_load_lds_dwordx4 v148, s[6:7]
	v_add_u32_e32 v148, 0x80, v241
	s_mov_b32 m0, s25
	s_nop 0
	global_load_lds_dwordx4 v148, s[6:7]
	s_waitcnt lgkmcnt(8)
	s_barrier
	s_waitcnt lgkmcnt(0)
	s_setprio 1
	s_waitcnt lgkmcnt(0)
	v_mfma_f32_16x16x32_bf16 v[126:129], v[156:159], v[172:175], 0
	v_mfma_f32_16x16x32_bf16 v[122:125], v[164:167], v[172:175], 0
	v_mfma_f32_16x16x32_bf16 v[118:121], v[156:159], v[180:183], 0
	v_mfma_f32_16x16x32_bf16 v[114:117], v[164:167], v[180:183], 0
	v_mfma_f32_16x16x32_bf16 v[110:113], v[156:159], v[200:203], 0
	v_mfma_f32_16x16x32_bf16 v[106:109], v[164:167], v[200:203], 0
	v_mfma_f32_16x16x32_bf16 v[102:105], v[156:159], v[208:211], 0
	v_mfma_f32_16x16x32_bf16 v[98:101], v[164:167], v[208:211], 0
	v_mfma_f32_16x16x32_bf16 v[126:129], v[160:163], v[176:179], v[126:129]
	v_mfma_f32_16x16x32_bf16 v[122:125], v[168:171], v[176:179], v[122:125]
	v_mfma_f32_16x16x32_bf16 v[118:121], v[160:163], v[196:199], v[118:121]
	v_mfma_f32_16x16x32_bf16 v[114:117], v[168:171], v[196:199], v[114:117]
	v_mfma_f32_16x16x32_bf16 v[110:113], v[160:163], v[204:207], v[110:113]
	v_mfma_f32_16x16x32_bf16 v[106:109], v[168:171], v[204:207], v[106:109]
	v_mfma_f32_16x16x32_bf16 v[102:105], v[160:163], v[212:215], v[102:105]
	v_mfma_f32_16x16x32_bf16 v[98:101], v[168:171], v[212:215], v[98:101]
	s_setprio 0
	s_barrier
	s_mov_b32 m0, s22
	v_or_b32_e32 v148, 0x14000, v150
	v_add_u32_e32 v154, 0x14100, v150
	v_add_u32_e32 v232, 0x100, v240
	v_add_u32_e32 v149, 0x14400, v150
	ds_read_b128 v[216:219], v148
	ds_read_b128 v[220:223], v149
	v_add_u32_e32 v155, 0x14500, v150
	ds_read_b128 v[224:227], v154
	ds_read_b128 v[228:231], v155
	global_load_lds_dwordx4 v232, s[16:17]
	v_add_u32_e32 v233, 0x100, v241
	s_mov_b32 m0, s23
	s_nop 0
	global_load_lds_dwordx4 v233, s[16:17]
	s_barrier
	s_waitcnt lgkmcnt(0)
	s_setprio 1
	s_waitcnt lgkmcnt(0)
	v_mfma_f32_16x16x32_bf16 v[92:95], v[216:219], v[172:175], 0
	v_mfma_f32_16x16x32_bf16 v[88:91], v[224:227], v[172:175], 0
	v_mfma_f32_16x16x32_bf16 v[84:87], v[216:219], v[180:183], 0
	v_mfma_f32_16x16x32_bf16 v[80:83], v[224:227], v[180:183], 0
	v_mfma_f32_16x16x32_bf16 v[76:79], v[216:219], v[200:203], 0
	v_mfma_f32_16x16x32_bf16 v[72:75], v[224:227], v[200:203], 0
	v_mfma_f32_16x16x32_bf16 v[68:71], v[216:219], v[208:211], 0
	v_mfma_f32_16x16x32_bf16 v[64:67], v[224:227], v[208:211], 0
	v_mfma_f32_16x16x32_bf16 v[92:95], v[220:223], v[176:179], v[92:95]
	v_mfma_f32_16x16x32_bf16 v[88:91], v[228:231], v[176:179], v[88:91]
	v_mfma_f32_16x16x32_bf16 v[84:87], v[220:223], v[196:199], v[84:87]
	v_mfma_f32_16x16x32_bf16 v[80:83], v[228:231], v[196:199], v[80:83]
	v_mfma_f32_16x16x32_bf16 v[76:79], v[220:223], v[204:207], v[76:79]
	v_mfma_f32_16x16x32_bf16 v[72:75], v[228:231], v[204:207], v[72:75]
	v_mfma_f32_16x16x32_bf16 v[68:71], v[220:223], v[212:215], v[68:71]
	v_mfma_f32_16x16x32_bf16 v[64:67], v[228:231], v[212:215], v[64:67]
	s_setprio 0
	s_mov_b32 m0, s94
	s_barrier
	ds_read_b128 v[172:175], v151 offset:16384
	ds_read_b128 v[176:179], v151 offset:17408
	ds_read_b128 v[180:183], v151 offset:18432
	ds_read_b128 v[196:199], v151 offset:19456
	ds_read_b128 v[200:203], v151 offset:20480
	ds_read_b128 v[204:207], v151 offset:21504
	ds_read_b128 v[208:211], v151 offset:22528
	ds_read_b128 v[212:215], v151 offset:23552
	global_load_lds_dwordx4 v232, s[18:19]
	s_mov_b32 m0, s95
	s_nop 0
	global_load_lds_dwordx4 v233, s[18:19]
	s_barrier
	s_waitcnt lgkmcnt(0)
	s_setprio 1
	s_waitcnt lgkmcnt(0)
	v_mfma_f32_16x16x32_bf16 v[60:63], v[156:159], v[172:175], 0
	v_mfma_f32_16x16x32_bf16 v[56:59], v[164:167], v[172:175], 0
	v_mfma_f32_16x16x32_bf16 v[52:55], v[156:159], v[180:183], 0
	v_mfma_f32_16x16x32_bf16 v[48:51], v[164:167], v[180:183], 0
	v_mfma_f32_16x16x32_bf16 v[44:47], v[156:159], v[200:203], 0
	v_mfma_f32_16x16x32_bf16 v[40:43], v[164:167], v[200:203], 0
	v_mfma_f32_16x16x32_bf16 v[36:39], v[156:159], v[208:211], 0
	v_mfma_f32_16x16x32_bf16 v[32:35], v[164:167], v[208:211], 0
	v_mfma_f32_16x16x32_bf16 v[60:63], v[160:163], v[176:179], v[60:63]
	v_mfma_f32_16x16x32_bf16 v[56:59], v[168:171], v[176:179], v[56:59]
	v_mfma_f32_16x16x32_bf16 v[52:55], v[160:163], v[196:199], v[52:55]
	v_mfma_f32_16x16x32_bf16 v[48:51], v[168:171], v[196:199], v[48:51]
	v_mfma_f32_16x16x32_bf16 v[44:47], v[160:163], v[204:207], v[44:47]
	v_mfma_f32_16x16x32_bf16 v[40:43], v[168:171], v[204:207], v[40:43]
	v_mfma_f32_16x16x32_bf16 v[36:39], v[160:163], v[212:215], v[36:39]
	v_mfma_f32_16x16x32_bf16 v[32:35], v[168:171], v[212:215], v[32:35]
	s_setprio 0
	s_barrier
	s_mov_b32 m0, s2
	s_nop 0
	global_load_lds_dwordx4 v232, s[8:9]
	s_mov_b32 m0, s3
	s_nop 0
	global_load_lds_dwordx4 v233, s[8:9]
	s_waitcnt vmcnt(6)
	s_barrier
; #define WAIT_V(n) asm volatile("s_waitcnt vmcnt(%0)" ::"n"(n) : "memory")
; #define WAIT_L(n) asm volatile("s_waitcnt lgkmcnt(%0)" ::"n"(n) : "memory")
; #define SBAR() __builtin_amdgcn_sched_barrier(0)
; #define STAGE(P, base, kt) do { _Pragma("unroll") for (int _i = 0; _i < 2; ++_i)                                        \
;       __builtin_amdgcn_global_load_lds((const unsigned*)((base) + (size_t)(sOff[_i] + (unsigned)(kt) * (BK * 2))),        \
;                                        (unsigned*)((P) + wid * 1024 + _i * 8192), 16, 0, 0); } while (0)
; #define LDA(dst, b, h) _Pragma("unroll") for (int m = 0; m < 4; ++m) _Pragma("unroll") for (int k = 0; k < 2; ++k) \
;       dst[m][k] = *(const bf16x8*)(SA(b, h) + aoff + (m * 2048 + k * 1024))
; #define LDB(dst, b, h) _Pragma("unroll") for (int n = 0; n < 2; ++n) _Pragma("unroll") for (int k = 0; k < 2; ++k) \
;       dst[n][k] = *(const bf16x8*)(SB(b, h) + boff + (n * 256 + k * 1024))
; #define BAR __builtin_amdgcn_s_barrier()
; template <int EPI, int N, int K>
; __device__ __forceinline__ void phase_gemm(const Params& p, const u16* __restrict__ A, const u16* __restrict__ Bt, int nM, char* shm,
;                            u16* __restrict__ outp, float* __restrict__ rowss) {
;     ...
;       WAIT_V(6); BAR; MMA(1, 1, At, B1); BAR;
;       LDB(B0, 1, 0); SBAR(); LDA(At, 1, 0); STAGE(SA(0, 1), A1, t + 2);
;       WAIT_L(8); BAR; WAIT_L(0); MMA(0, 0, At, B0); BAR; SBAR();
;       LDB(B1, 1, 1); STAGE(SB(1, 0), B0p, t + 3);
;       BAR; WAIT_L(0); MMA(0, 1, At, B1); BAR;
	s_setprio 1
	v_mfma_f32_16x16x32_bf16 v[28:31], v[216:219], v[172:175], 0
	v_mfma_f32_16x16x32_bf16 v[24:27], v[224:227], v[172:175], 0
	v_mfma_f32_16x16x32_bf16 v[20:23], v[216:219], v[180:183], 0
	v_mfma_f32_16x16x32_bf16 v[16:19], v[224:227], v[180:183], 0
	v_mfma_f32_16x16x32_bf16 v[12:15], v[216:219], v[200:203], 0
	v_mfma_f32_16x16x32_bf16 v[8:11], v[224:227], v[200:203], 0
	v_mfma_f32_16x16x32_bf16 v[4:7], v[216:219], v[208:211], 0
	v_mfma_f32_16x16x32_bf16 v[0:3], v[224:227], v[208:211], 0
	v_mfma_f32_16x16x32_bf16 v[28:31], v[220:223], v[176:179], v[28:31]
	v_mfma_f32_16x16x32_bf16 v[24:27], v[228:231], v[176:179], v[24:27]
	v_mfma_f32_16x16x32_bf16 v[20:23], v[220:223], v[196:199], v[20:23]
	v_mfma_f32_16x16x32_bf16 v[16:19], v[228:231], v[196:199], v[16:19]
	v_mfma_f32_16x16x32_bf16 v[12:15], v[220:223], v[204:207], v[12:15]
	v_mfma_f32_16x16x32_bf16 v[8:11], v[228:231], v[204:207], v[8:11]
	v_mfma_f32_16x16x32_bf16 v[4:7], v[220:223], v[212:215], v[4:7]
	v_mfma_f32_16x16x32_bf16 v[0:3], v[228:231], v[212:215], v[0:3]
	s_setprio 0
	v_or_b32_e32 v156, 0x18000, v150
	v_add_u32_e32 v158, 0x18100, v150
	s_barrier
	v_add_u32_e32 v157, 0x18400, v150
	ds_read_b128 v[164:167], v156
	ds_read_b128 v[168:171], v157
	v_add_u32_e32 v159, 0x18500, v150
	ds_read_b128 v[172:175], v158
	ds_read_b128 v[176:179], v159
	s_mov_b32 m0, s92
	ds_read_b128 v[180:183], v151 offset:32768
	ds_read_b128 v[196:199], v151 offset:33792
	ds_read_b128 v[200:203], v151 offset:34816
	ds_read_b128 v[204:207], v151 offset:35840
	ds_read_b128 v[208:211], v151 offset:36864
	ds_read_b128 v[212:215], v151 offset:37888
	ds_read_b128 v[216:219], v151 offset:38912
	ds_read_b128 v[220:223], v151 offset:39936
	global_load_lds_dwordx4 v232, s[6:7]
	s_mov_b32 m0, s0
	s_nop 0
	global_load_lds_dwordx4 v233, s[6:7]
	s_waitcnt lgkmcnt(8)
	s_barrier
	s_waitcnt lgkmcnt(0)
	s_setprio 1
	s_waitcnt lgkmcnt(0)
	v_mfma_f32_16x16x32_bf16 v[126:129], v[164:167], v[180:183], v[126:129]
	v_mfma_f32_16x16x32_bf16 v[122:125], v[172:175], v[180:183], v[122:125]
	v_mfma_f32_16x16x32_bf16 v[118:121], v[164:167], v[200:203], v[118:121]
	v_mfma_f32_16x16x32_bf16 v[114:117], v[172:175], v[200:203], v[114:117]
	v_mfma_f32_16x16x32_bf16 v[110:113], v[164:167], v[208:211], v[110:113]
	v_mfma_f32_16x16x32_bf16 v[106:109], v[172:175], v[208:211], v[106:109]
	v_mfma_f32_16x16x32_bf16 v[102:105], v[164:167], v[216:219], v[102:105]
	v_mfma_f32_16x16x32_bf16 v[98:101], v[172:175], v[216:219], v[98:101]
	v_mfma_f32_16x16x32_bf16 v[126:129], v[168:171], v[196:199], v[126:129]
	v_mfma_f32_16x16x32_bf16 v[122:125], v[176:179], v[196:199], v[122:125]
	v_mfma_f32_16x16x32_bf16 v[118:121], v[168:171], v[204:207], v[118:121]
	v_mfma_f32_16x16x32_bf16 v[114:117], v[176:179], v[204:207], v[114:117]
	v_mfma_f32_16x16x32_bf16 v[110:113], v[168:171], v[212:215], v[110:113]
	v_mfma_f32_16x16x32_bf16 v[106:109], v[176:179], v[212:215], v[106:109]
	v_mfma_f32_16x16x32_bf16 v[102:105], v[168:171], v[220:223], v[102:105]
	v_mfma_f32_16x16x32_bf16 v[98:101], v[176:179], v[220:223], v[98:101]
	s_setprio 0
	s_barrier
	s_mov_b32 m0, s1
	v_or_b32_e32 v160, 0x1c000, v150
	v_add_u32_e32 v162, 0x1c100, v150
	v_add_u32_e32 v240, 0x180, v240
	v_add_u32_e32 v161, 0x1c400, v150
	ds_read_b128 v[224:227], v160
	ds_read_b128 v[228:231], v161
	v_add_u32_e32 v163, 0x1c500, v150
	ds_read_b128 v[232:235], v162
	ds_read_b128 v[236:239], v163
	global_load_lds_dwordx4 v240, s[16:17]
	v_add_u32_e32 v241, 0x180, v241
	s_mov_b32 m0, s12
	s_nop 0
	global_load_lds_dwordx4 v241, s[16:17]
	s_barrier
; #define WAIT_V(n) asm volatile("s_waitcnt vmcnt(%0)" ::"n"(n) : "memory")
; #define WAIT_L(n) asm volatile("s_waitcnt lgkmcnt(%0)" ::"n"(n) : "memory")
; #define SBAR() __builtin_amdgcn_sched_barrier(0)
; #define STAGE(P, base, kt) do { _Pragma("unroll") for (int _i = 0; _i < 2; ++_i)                                        \
;       __builtin_amdgcn_global_load_lds((const unsigned*)((base) + (size_t)(sOff[_i] + (unsigned)(kt) * (BK * 2))),        \
;                                        (unsigned*)((P) + wid * 1024 + _i * 8192), 16, 0, 0); } while (0)
; #define LDA(dst, b, h) _Pragma("unroll") for (int m = 0; m < 4; ++m) _Pragma("unroll") for (int k = 0; k < 2; ++k) \
;       dst[m][k] = *(const bf16x8*)(SA(b, h) + aoff + (m * 2048 + k * 1024))
; #define BAR __builtin_amdgcn_s_barrier()
; template <int EPI, int N, int K>
; __device__ __forceinline__ void phase_gemm(const Params& p, const u16* __restrict__ A, const u16* __restrict__ Bt, int nM, char* shm,
;                            u16* __restrict__ outp, float* __restrict__ rowss) {
;     ...
;       BAR; WAIT_L(0); MMA(0, 1, At, B1); BAR;
;       LDA(At, 1, 1); STAGE(SA(1, 0), A0, t + 3);
;       BAR; WAIT_L(0); MMA(1, 0, At, B0); BAR; SBAR();
;       STAGE(SB(1, 1), B1p, t + 3);
;       WAIT_V(6); BAR; MMA(1, 1, At, B1); BAR;
;     }
	s_waitcnt lgkmcnt(0)
	s_setprio 1
	s_waitcnt lgkmcnt(0)
	v_mfma_f32_16x16x32_bf16 v[92:95], v[224:227], v[180:183], v[92:95]
	v_mfma_f32_16x16x32_bf16 v[88:91], v[232:235], v[180:183], v[88:91]
	v_mfma_f32_16x16x32_bf16 v[84:87], v[224:227], v[200:203], v[84:87]
	v_mfma_f32_16x16x32_bf16 v[80:83], v[232:235], v[200:203], v[80:83]
	v_mfma_f32_16x16x32_bf16 v[76:79], v[224:227], v[208:211], v[76:79]
	v_mfma_f32_16x16x32_bf16 v[72:75], v[232:235], v[208:211], v[72:75]
	v_mfma_f32_16x16x32_bf16 v[68:71], v[224:227], v[216:219], v[68:71]
	v_mfma_f32_16x16x32_bf16 v[64:67], v[232:235], v[216:219], v[64:67]
	v_mfma_f32_16x16x32_bf16 v[92:95], v[228:231], v[196:199], v[92:95]
	v_mfma_f32_16x16x32_bf16 v[88:91], v[236:239], v[196:199], v[88:91]
	v_mfma_f32_16x16x32_bf16 v[84:87], v[228:231], v[204:207], v[84:87]
	v_mfma_f32_16x16x32_bf16 v[80:83], v[236:239], v[204:207], v[80:83]
	v_mfma_f32_16x16x32_bf16 v[76:79], v[228:231], v[212:215], v[76:79]
	v_mfma_f32_16x16x32_bf16 v[72:75], v[236:239], v[212:215], v[72:75]
	v_mfma_f32_16x16x32_bf16 v[68:71], v[228:231], v[220:223], v[68:71]
	v_mfma_f32_16x16x32_bf16 v[64:67], v[236:239], v[220:223], v[64:67]
	s_setprio 0
	s_mov_b32 m0, s13
	s_barrier
	ds_read_b128 v[180:183], v151 offset:49152
	ds_read_b128 v[196:199], v151 offset:50176
	ds_read_b128 v[200:203], v151 offset:51200
	ds_read_b128 v[204:207], v151 offset:52224
	ds_read_b128 v[208:211], v151 offset:53248
	ds_read_b128 v[212:215], v151 offset:54272
	ds_read_b128 v[216:219], v151 offset:55296
	ds_read_b128 v[220:223], v151 offset:56320
	global_load_lds_dwordx4 v240, s[18:19]
	s_mov_b32 m0, s14
	s_nop 0
	global_load_lds_dwordx4 v241, s[18:19]
	s_barrier
	s_waitcnt lgkmcnt(0)
	s_setprio 1
	s_waitcnt lgkmcnt(0)
	v_mfma_f32_16x16x32_bf16 v[60:63], v[164:167], v[180:183], v[60:63]
	v_mfma_f32_16x16x32_bf16 v[56:59], v[172:175], v[180:183], v[56:59]
	v_mfma_f32_16x16x32_bf16 v[52:55], v[164:167], v[200:203], v[52:55]
	v_mfma_f32_16x16x32_bf16 v[48:51], v[172:175], v[200:203], v[48:51]
	v_mfma_f32_16x16x32_bf16 v[44:47], v[164:167], v[208:211], v[44:47]
	v_mfma_f32_16x16x32_bf16 v[40:43], v[172:175], v[208:211], v[40:43]
	v_mfma_f32_16x16x32_bf16 v[36:39], v[164:167], v[216:219], v[36:39]
	v_mfma_f32_16x16x32_bf16 v[32:35], v[172:175], v[216:219], v[32:35]
	v_mfma_f32_16x16x32_bf16 v[60:63], v[168:171], v[196:199], v[60:63]
	v_mfma_f32_16x16x32_bf16 v[56:59], v[176:179], v[196:199], v[56:59]
	v_mfma_f32_16x16x32_bf16 v[52:55], v[168:171], v[204:207], v[52:55]
	v_mfma_f32_16x16x32_bf16 v[48:51], v[176:179], v[204:207], v[48:51]
	v_mfma_f32_16x16x32_bf16 v[44:47], v[168:171], v[212:215], v[44:47]
	v_mfma_f32_16x16x32_bf16 v[40:43], v[176:179], v[212:215], v[40:43]
	v_mfma_f32_16x16x32_bf16 v[36:39], v[168:171], v[220:223], v[36:39]
	v_mfma_f32_16x16x32_bf16 v[32:35], v[176:179], v[220:223], v[32:35]
	s_setprio 0
	s_barrier
	s_mov_b32 m0, s15
	s_nop 0
	global_load_lds_dwordx4 v240, s[8:9]
	s_mov_b32 m0, s4
	s_nop 0
	global_load_lds_dwordx4 v241, s[8:9]
	s_waitcnt vmcnt(6)
	s_barrier
	s_setprio 1
	v_mfma_f32_16x16x32_bf16 v[28:31], v[224:227], v[180:183], v[28:31]
	v_mfma_f32_16x16x32_bf16 v[24:27], v[232:235], v[180:183], v[24:27]
	v_mfma_f32_16x16x32_bf16 v[20:23], v[224:227], v[200:203], v[20:23]
	v_mfma_f32_16x16x32_bf16 v[16:19], v[232:235], v[200:203], v[16:19]
	v_mfma_f32_16x16x32_bf16 v[12:15], v[224:227], v[208:211], v[12:15]
	v_mfma_f32_16x16x32_bf16 v[8:11], v[232:235], v[208:211], v[8:11]
	v_mfma_f32_16x16x32_bf16 v[4:7], v[224:227], v[216:219], v[4:7]
	v_mfma_f32_16x16x32_bf16 v[0:3], v[232:235], v[216:219], v[0:3]
	v_mfma_f32_16x16x32_bf16 v[28:31], v[228:231], v[196:199], v[28:31]
	v_mfma_f32_16x16x32_bf16 v[24:27], v[236:239], v[196:199], v[24:27]
	v_mfma_f32_16x16x32_bf16 v[20:23], v[228:231], v[204:207], v[20:23]
	v_mfma_f32_16x16x32_bf16 v[16:19], v[236:239], v[204:207], v[16:19]
	v_mfma_f32_16x16x32_bf16 v[12:15], v[228:231], v[212:215], v[12:15]
	v_mfma_f32_16x16x32_bf16 v[8:11], v[236:239], v[212:215], v[8:11]
	v_mfma_f32_16x16x32_bf16 v[4:7], v[228:231], v[220:223], v[4:7]
	v_mfma_f32_16x16x32_bf16 v[0:3], v[236:239], v[220:223], v[0:3]
	s_setprio 0
	s_add_i32 s11, s11, 2
	v_add_u32_e32 v130, 0x100, v130
	s_cmp_lt_u32 s11, 12
	v_add_u32_e32 v96, 0x100, v96
	s_barrier

; #define WAIT_V(n) asm volatile("s_waitcnt vmcnt(%0)" ::"n"(n) : "memory")
; #define WAIT_L(n) asm volatile("s_waitcnt lgkmcnt(%0)" ::"n"(n) : "memory")
; #define SBAR() __builtin_amdgcn_sched_barrier(0)
; #define STAGE(P, base, kt) do { _Pragma("unroll") for (int _i = 0; _i < 2; ++_i)                                        \
;       __builtin_amdgcn_global_load_lds((const unsigned*)((base) + (size_t)(sOff[_i] + (unsigned)(kt) * (BK * 2))),        \
;                                        (unsigned*)((P) + wid * 1024 + _i * 8192), 16, 0, 0); } while (0)
; #define LDA(dst, b, h) _Pragma("unroll") for (int m = 0; m < 4; ++m) _Pragma("unroll") for (int k = 0; k < 2; ++k) \
;       dst[m][k] = *(const bf16x8*)(SA(b, h) + aoff + (m * 2048 + k * 1024))
; #define LDB(dst, b, h) _Pragma("unroll") for (int n = 0; n < 2; ++n) _Pragma("unroll") for (int k = 0; k < 2; ++k) \
;       dst[n][k] = *(const bf16x8*)(SB(b, h) + boff + (n * 256 + k * 1024))
; #define BAR __builtin_amdgcn_s_barrier()
; template <int EPI, int N, int K>
; __device__ __forceinline__ void phase_gemm(const Params& p, const u16* __restrict__ A, const u16* __restrict__ Bt, int nM, char* shm,
;                            u16* __restrict__ outp, float* __restrict__ rowss) {
;     ...
;   for (;;) {
;     const char* A1 = A0 + (size_t)128 * K * 2;
;     const char* B1p = B0p + (size_t)128 * K * 2;
;     f32x4 acc[2][2][4][2] = {};
;     bf16x8 At[4][2], B0[2][2], B1[2][2];
;     if (wr == 1) BAR;
;     WAIT_V(0); BAR;
;     BAR;
;     for (int t = 0; t < nt - 2; t += 2) {
;       LDB(B0, 0, 0); SBAR(); LDA(At, 0, 0); STAGE(SA(1, 1), A1, t + 1);
;       WAIT_L(8); BAR; WAIT_L(0); MMA(0, 0, At, B0); BAR; SBAR();
;       LDB(B1, 0, 1); STAGE(SB(0, 0), B0p, t + 2);
;       BAR; WAIT_L(0); MMA(0, 1, At, B1); BAR;
;       LDA(At, 0, 1); STAGE(SA(0, 0), A0, t + 2);
;       BAR; WAIT_L(0); MMA(1, 0, At, B0); BAR; SBAR();
;       STAGE(SB(0, 1), B1p, t + 2);
;       WAIT_V(6); BAR; MMA(1, 1, At, B1); BAR;
.LBB0_432:
	s_add_u32 s16, s10, 0x40000
	s_addc_u32 s17, s11, 0
	s_waitcnt vmcnt(0)
	s_add_u32 s18, s8, 0x40000
	s_addc_u32 s19, s9, 0
	s_mov_b32 s22, -2
	v_mov_b32_e32 v96, v148
	v_mov_b32_e32 v142, v147
	s_barrier
	s_barrier
	v_or_b32_e32 v143, 0x10000, v145
	v_add_u32_e32 v150, 0x10100, v145
	v_add_u32_e32 v149, 0x10400, v145
	ds_read_b128 v[156:159], v143
	ds_read_b128 v[160:163], v149
	v_add_u32_e32 v151, 0x10500, v145
	ds_read_b128 v[164:167], v150
	ds_read_b128 v[168:171], v151
	v_add_u32_e32 v204, v144, v96
	s_add_i32 s62, s5, 0xc000
	v_add_u32_e32 v152, 0x80, v204
	s_mov_b32 m0, s62
	v_add_u32_e32 v205, v144, v142
	s_add_i32 s23, s5, 0xe000
	ds_read_b128 v[172:175], v146
	ds_read_b128 v[176:179], v146 offset:1024
	ds_read_b128 v[180:183], v146 offset:2048
	ds_read_b128 v[196:199], v146 offset:3072
	ds_read_b128 v[200:203], v146 offset:4096
	ds_read_b128 v[208:211], v146 offset:5120
	ds_read_b128 v[212:215], v146 offset:6144
	ds_read_b128 v[216:219], v146 offset:7168
	global_load_lds_dwordx4 v152, s[16:17]
	v_add_u32_e32 v152, 0x80, v205
	s_mov_b32 m0, s23
	s_nop 0
	global_load_lds_dwordx4 v152, s[16:17]
	s_waitcnt lgkmcnt(8)
	s_barrier
	s_waitcnt lgkmcnt(0)
	s_setprio 1
	s_waitcnt lgkmcnt(0)
	v_mfma_f32_16x16x32_bf16 v[126:129], v[156:159], v[172:175], 0
	v_mfma_f32_16x16x32_bf16 v[122:125], v[164:167], v[172:175], 0
	v_mfma_f32_16x16x32_bf16 v[118:121], v[156:159], v[180:183], 0
	v_mfma_f32_16x16x32_bf16 v[114:117], v[164:167], v[180:183], 0
	v_mfma_f32_16x16x32_bf16 v[110:113], v[156:159], v[200:203], 0
	v_mfma_f32_16x16x32_bf16 v[106:109], v[164:167], v[200:203], 0
	v_mfma_f32_16x16x32_bf16 v[102:105], v[156:159], v[212:215], 0
	v_mfma_f32_16x16x32_bf16 v[98:101], v[164:167], v[212:215], 0
	v_mfma_f32_16x16x32_bf16 v[126:129], v[160:163], v[176:179], v[126:129]
	v_mfma_f32_16x16x32_bf16 v[122:125], v[168:171], v[176:179], v[122:125]
	v_mfma_f32_16x16x32_bf16 v[118:121], v[160:163], v[196:199], v[118:121]
	v_mfma_f32_16x16x32_bf16 v[114:117], v[168:171], v[196:199], v[114:117]
	v_mfma_f32_16x16x32_bf16 v[110:113], v[160:163], v[208:211], v[110:113]
	v_mfma_f32_16x16x32_bf16 v[106:109], v[168:171], v[208:211], v[106:109]
	v_mfma_f32_16x16x32_bf16 v[102:105], v[160:163], v[216:219], v[102:105]
	v_mfma_f32_16x16x32_bf16 v[98:101], v[168:171], v[216:219], v[98:101]
	s_setprio 0
	s_barrier
	s_mov_b32 m0, s25
	v_or_b32_e32 v152, 0x14000, v145
	v_add_u32_e32 v154, 0x14100, v145
	v_add_u32_e32 v206, 0x100, v204
	v_add_u32_e32 v153, 0x14400, v145
	ds_read_b128 v[220:223], v152
	ds_read_b128 v[224:227], v153
	v_add_u32_e32 v155, 0x14500, v145
	ds_read_b128 v[228:231], v154
	ds_read_b128 v[232:235], v155
	global_load_lds_dwordx4 v206, s[8:9]
	v_add_u32_e32 v207, 0x100, v205
	s_mov_b32 m0, s26
	s_nop 0
	global_load_lds_dwordx4 v207, s[8:9]
	s_barrier
	s_waitcnt lgkmcnt(0)
	s_setprio 1
	s_waitcnt lgkmcnt(0)
	v_mfma_f32_16x16x32_bf16 v[92:95], v[220:223], v[172:175], 0
	v_mfma_f32_16x16x32_bf16 v[88:91], v[228:231], v[172:175], 0
	v_mfma_f32_16x16x32_bf16 v[84:87], v[220:223], v[180:183], 0
	v_mfma_f32_16x16x32_bf16 v[80:83], v[228:231], v[180:183], 0
	v_mfma_f32_16x16x32_bf16 v[76:79], v[220:223], v[200:203], 0
	v_mfma_f32_16x16x32_bf16 v[72:75], v[228:231], v[200:203], 0
	v_mfma_f32_16x16x32_bf16 v[68:71], v[220:223], v[212:215], 0
	v_mfma_f32_16x16x32_bf16 v[64:67], v[228:231], v[212:215], 0
	v_mfma_f32_16x16x32_bf16 v[92:95], v[224:227], v[176:179], v[92:95]
	v_mfma_f32_16x16x32_bf16 v[88:91], v[232:235], v[176:179], v[88:91]
	v_mfma_f32_16x16x32_bf16 v[84:87], v[224:227], v[196:199], v[84:87]
	v_mfma_f32_16x16x32_bf16 v[80:83], v[232:235], v[196:199], v[80:83]
	v_mfma_f32_16x16x32_bf16 v[76:79], v[224:227], v[208:211], v[76:79]
	v_mfma_f32_16x16x32_bf16 v[72:75], v[232:235], v[208:211], v[72:75]
	v_mfma_f32_16x16x32_bf16 v[68:71], v[224:227], v[216:219], v[68:71]
	v_mfma_f32_16x16x32_bf16 v[64:67], v[232:235], v[216:219], v[64:67]
	s_setprio 0
	s_mov_b32 m0, s5
	s_barrier
	ds_read_b128 v[172:175], v146 offset:16384
	ds_read_b128 v[176:179], v146 offset:17408
	ds_read_b128 v[180:183], v146 offset:18432
	ds_read_b128 v[196:199], v146 offset:19456
	ds_read_b128 v[200:203], v146 offset:20480
	ds_read_b128 v[208:211], v146 offset:21504
	ds_read_b128 v[212:215], v146 offset:22528
	ds_read_b128 v[216:219], v146 offset:23552
	global_load_lds_dwordx4 v206, s[10:11]
	s_mov_b32 m0, s24
	s_nop 0
	global_load_lds_dwordx4 v207, s[10:11]
	s_barrier
	s_waitcnt lgkmcnt(0)
	s_setprio 1
	s_waitcnt lgkmcnt(0)
	v_mfma_f32_16x16x32_bf16 v[60:63], v[156:159], v[172:175], 0
	v_mfma_f32_16x16x32_bf16 v[56:59], v[164:167], v[172:175], 0
	v_mfma_f32_16x16x32_bf16 v[52:55], v[156:159], v[180:183], 0
	v_mfma_f32_16x16x32_bf16 v[48:51], v[164:167], v[180:183], 0
	v_mfma_f32_16x16x32_bf16 v[44:47], v[156:159], v[200:203], 0
	v_mfma_f32_16x16x32_bf16 v[40:43], v[164:167], v[200:203], 0
	v_mfma_f32_16x16x32_bf16 v[36:39], v[156:159], v[212:215], 0
	v_mfma_f32_16x16x32_bf16 v[32:35], v[164:167], v[212:215], 0
	v_mfma_f32_16x16x32_bf16 v[60:63], v[160:163], v[176:179], v[60:63]
	v_mfma_f32_16x16x32_bf16 v[56:59], v[168:171], v[176:179], v[56:59]
	v_mfma_f32_16x16x32_bf16 v[52:55], v[160:163], v[196:199], v[52:55]
	v_mfma_f32_16x16x32_bf16 v[48:51], v[168:171], v[196:199], v[48:51]
	v_mfma_f32_16x16x32_bf16 v[44:47], v[160:163], v[208:211], v[44:47]
	v_mfma_f32_16x16x32_bf16 v[40:43], v[168:171], v[208:211], v[40:43]
	v_mfma_f32_16x16x32_bf16 v[36:39], v[160:163], v[216:219], v[36:39]
	v_mfma_f32_16x16x32_bf16 v[32:35], v[168:171], v[216:219], v[32:35]
	s_setprio 0
	s_barrier
	s_mov_b32 m0, s27
	s_nop 0
	global_load_lds_dwordx4 v206, s[18:19]
	s_mov_b32 m0, s28
	s_nop 0
	global_load_lds_dwordx4 v207, s[18:19]
	s_waitcnt vmcnt(6)
	s_barrier
; #define WAIT_V(n) asm volatile("s_waitcnt vmcnt(%0)" ::"n"(n) : "memory")
; #define WAIT_L(n) asm volatile("s_waitcnt lgkmcnt(%0)" ::"n"(n) : "memory")
; #define SBAR() __builtin_amdgcn_sched_barrier(0)
; #define STAGE(P, base, kt) do { _Pragma("unroll") for (int _i = 0; _i < 2; ++_i)                                        \
;       __builtin_amdgcn_global_load_lds((const unsigned*)((base) + (size_t)(sOff[_i] + (unsigned)(kt) * (BK * 2))),        \
;                                        (unsigned*)((P) + wid * 1024 + _i * 8192), 16, 0, 0); } while (0)
; #define LDA(dst, b, h) _Pragma("unroll") for (int m = 0; m < 4; ++m) _Pragma("unroll") for (int k = 0; k < 2; ++k) \
;       dst[m][k] = *(const bf16x8*)(SA(b, h) + aoff + (m * 2048 + k * 1024))
; #define LDB(dst, b, h) _Pragma("unroll") for (int n = 0; n < 2; ++n) _Pragma("unroll") for (int k = 0; k < 2; ++k) \
;       dst[n][k] = *(const bf16x8*)(SB(b, h) + boff + (n * 256 + k * 1024))
; #define BAR __builtin_amdgcn_s_barrier()
; template <int EPI, int N, int K>
; __device__ __forceinline__ void phase_gemm(const Params& p, const u16* __restrict__ A, const u16* __restrict__ Bt, int nM, char* shm,
;                            u16* __restrict__ outp, float* __restrict__ rowss) {
;     ...
;       WAIT_V(6); BAR; MMA(1, 1, At, B1); BAR;
;       LDB(B0, 1, 0); SBAR(); LDA(At, 1, 0); STAGE(SA(0, 1), A1, t + 2);
;       WAIT_L(8); BAR; WAIT_L(0); MMA(0, 0, At, B0); BAR; SBAR();
;       LDB(B1, 1, 1); STAGE(SB(1, 0), B0p, t + 3);
;       BAR; WAIT_L(0); MMA(0, 1, At, B1); BAR;
	s_setprio 1
	v_mfma_f32_16x16x32_bf16 v[28:31], v[220:223], v[172:175], 0
	v_mfma_f32_16x16x32_bf16 v[24:27], v[228:231], v[172:175], 0
	v_mfma_f32_16x16x32_bf16 v[20:23], v[220:223], v[180:183], 0
	v_mfma_f32_16x16x32_bf16 v[16:19], v[228:231], v[180:183], 0
	v_mfma_f32_16x16x32_bf16 v[12:15], v[220:223], v[200:203], 0
	v_mfma_f32_16x16x32_bf16 v[8:11], v[228:231], v[200:203], 0
	v_mfma_f32_16x16x32_bf16 v[4:7], v[220:223], v[212:215], 0
	v_mfma_f32_16x16x32_bf16 v[0:3], v[228:231], v[212:215], 0
	v_mfma_f32_16x16x32_bf16 v[28:31], v[224:227], v[176:179], v[28:31]
	v_mfma_f32_16x16x32_bf16 v[24:27], v[232:235], v[176:179], v[24:27]
	v_mfma_f32_16x16x32_bf16 v[20:23], v[224:227], v[196:199], v[20:23]
	v_mfma_f32_16x16x32_bf16 v[16:19], v[232:235], v[196:199], v[16:19]
	v_mfma_f32_16x16x32_bf16 v[12:15], v[224:227], v[208:211], v[12:15]
	v_mfma_f32_16x16x32_bf16 v[8:11], v[232:235], v[208:211], v[8:11]
	v_mfma_f32_16x16x32_bf16 v[4:7], v[224:227], v[216:219], v[4:7]
	v_mfma_f32_16x16x32_bf16 v[0:3], v[232:235], v[216:219], v[0:3]
	s_setprio 0
	v_or_b32_e32 v156, 0x18000, v145
	v_add_u32_e32 v158, 0x18100, v145
	s_barrier
	v_add_u32_e32 v157, 0x18400, v145
	ds_read_b128 v[164:167], v156
	ds_read_b128 v[168:171], v157
	v_add_u32_e32 v159, 0x18500, v145
	ds_read_b128 v[172:175], v158
	ds_read_b128 v[176:179], v159
	s_mov_b32 m0, s29
	ds_read_b128 v[180:183], v146 offset:32768
	ds_read_b128 v[196:199], v146 offset:33792
	ds_read_b128 v[200:203], v146 offset:34816
	ds_read_b128 v[208:211], v146 offset:35840
	ds_read_b128 v[212:215], v146 offset:36864
	ds_read_b128 v[216:219], v146 offset:37888
	ds_read_b128 v[220:223], v146 offset:38912
	ds_read_b128 v[224:227], v146 offset:39936
	global_load_lds_dwordx4 v206, s[16:17]
	s_mov_b32 m0, s30
	s_nop 0
	global_load_lds_dwordx4 v207, s[16:17]
	s_waitcnt lgkmcnt(8)
	s_barrier
	s_waitcnt lgkmcnt(0)
	s_setprio 1
	s_waitcnt lgkmcnt(0)
	v_mfma_f32_16x16x32_bf16 v[126:129], v[164:167], v[180:183], v[126:129]
	v_mfma_f32_16x16x32_bf16 v[122:125], v[172:175], v[180:183], v[122:125]
	v_mfma_f32_16x16x32_bf16 v[118:121], v[164:167], v[200:203], v[118:121]
	v_mfma_f32_16x16x32_bf16 v[114:117], v[172:175], v[200:203], v[114:117]
	v_mfma_f32_16x16x32_bf16 v[110:113], v[164:167], v[212:215], v[110:113]
	v_mfma_f32_16x16x32_bf16 v[106:109], v[172:175], v[212:215], v[106:109]
	v_mfma_f32_16x16x32_bf16 v[102:105], v[164:167], v[220:223], v[102:105]
	v_mfma_f32_16x16x32_bf16 v[98:101], v[172:175], v[220:223], v[98:101]
	v_mfma_f32_16x16x32_bf16 v[126:129], v[168:171], v[196:199], v[126:129]
	v_mfma_f32_16x16x32_bf16 v[122:125], v[176:179], v[196:199], v[122:125]
	v_mfma_f32_16x16x32_bf16 v[118:121], v[168:171], v[208:211], v[118:121]
	v_mfma_f32_16x16x32_bf16 v[114:117], v[176:179], v[208:211], v[114:117]
	v_mfma_f32_16x16x32_bf16 v[110:113], v[168:171], v[216:219], v[110:113]
	v_mfma_f32_16x16x32_bf16 v[106:109], v[176:179], v[216:219], v[106:109]
	v_mfma_f32_16x16x32_bf16 v[102:105], v[168:171], v[224:227], v[102:105]
	v_mfma_f32_16x16x32_bf16 v[98:101], v[176:179], v[224:227], v[98:101]
	s_setprio 0
	s_barrier
	s_mov_b32 m0, s31
	v_or_b32_e32 v160, 0x1c000, v145
	v_add_u32_e32 v162, 0x1c100, v145
	v_add_u32_e32 v204, 0x180, v204
	v_add_u32_e32 v161, 0x1c400, v145
	ds_read_b128 v[228:231], v160
	ds_read_b128 v[232:235], v161
	v_add_u32_e32 v163, 0x1c500, v145
	ds_read_b128 v[236:239], v162
	ds_read_b128 v[240:243], v163
	global_load_lds_dwordx4 v204, s[8:9]
	v_add_u32_e32 v205, 0x180, v205
	s_mov_b32 m0, s33
	s_nop 0
	global_load_lds_dwordx4 v205, s[8:9]
	s_barrier
; #define WAIT_V(n) asm volatile("s_waitcnt vmcnt(%0)" ::"n"(n) : "memory")
; #define WAIT_L(n) asm volatile("s_waitcnt lgkmcnt(%0)" ::"n"(n) : "memory")
; #define SBAR() __builtin_amdgcn_sched_barrier(0)
; #define STAGE(P, base, kt) do { _Pragma("unroll") for (int _i = 0; _i < 2; ++_i)                                        \
;       __builtin_amdgcn_global_load_lds((const unsigned*)((base) + (size_t)(sOff[_i] + (unsigned)(kt) * (BK * 2))),        \
;                                        (unsigned*)((P) + wid * 1024 + _i * 8192), 16, 0, 0); } while (0)
; #define LDA(dst, b, h) _Pragma("unroll") for (int m = 0; m < 4; ++m) _Pragma("unroll") for (int k = 0; k < 2; ++k) \
;       dst[m][k] = *(const bf16x8*)(SA(b, h) + aoff + (m * 2048 + k * 1024))
; #define BAR __builtin_amdgcn_s_barrier()
; template <int EPI, int N, int K>
; __device__ __forceinline__ void phase_gemm(const Params& p, const u16* __restrict__ A, const u16* __restrict__ Bt, int nM, char* shm,
;                            u16* __restrict__ outp, float* __restrict__ rowss) {
;     ...
;       BAR; WAIT_L(0); MMA(0, 1, At, B1); BAR;
;       LDA(At, 1, 1); STAGE(SA(1, 0), A0, t + 3);
;       BAR; WAIT_L(0); MMA(1, 0, At, B0); BAR; SBAR();
;       STAGE(SB(1, 1), B1p, t + 3);
;       WAIT_V(6); BAR; MMA(1, 1, At, B1); BAR;
;     }
	s_waitcnt lgkmcnt(0)
	s_setprio 1
	s_waitcnt lgkmcnt(0)
	v_mfma_f32_16x16x32_bf16 v[92:95], v[228:231], v[180:183], v[92:95]
	v_mfma_f32_16x16x32_bf16 v[88:91], v[236:239], v[180:183], v[88:91]
	v_mfma_f32_16x16x32_bf16 v[84:87], v[228:231], v[200:203], v[84:87]
	v_mfma_f32_16x16x32_bf16 v[80:83], v[236:239], v[200:203], v[80:83]
	v_mfma_f32_16x16x32_bf16 v[76:79], v[228:231], v[212:215], v[76:79]
	v_mfma_f32_16x16x32_bf16 v[72:75], v[236:239], v[212:215], v[72:75]
	v_mfma_f32_16x16x32_bf16 v[68:71], v[228:231], v[220:223], v[68:71]
	v_mfma_f32_16x16x32_bf16 v[64:67], v[236:239], v[220:223], v[64:67]
	v_mfma_f32_16x16x32_bf16 v[92:95], v[232:235], v[196:199], v[92:95]
	v_mfma_f32_16x16x32_bf16 v[88:91], v[240:243], v[196:199], v[88:91]
	v_mfma_f32_16x16x32_bf16 v[84:87], v[232:235], v[208:211], v[84:87]
	v_mfma_f32_16x16x32_bf16 v[80:83], v[240:243], v[208:211], v[80:83]
	v_mfma_f32_16x16x32_bf16 v[76:79], v[232:235], v[216:219], v[76:79]
	v_mfma_f32_16x16x32_bf16 v[72:75], v[240:243], v[216:219], v[72:75]
	v_mfma_f32_16x16x32_bf16 v[68:71], v[232:235], v[224:227], v[68:71]
	v_mfma_f32_16x16x32_bf16 v[64:67], v[240:243], v[224:227], v[64:67]
	s_setprio 0
	s_mov_b32 m0, s35
	s_barrier
	ds_read_b128 v[180:183], v146 offset:49152
	ds_read_b128 v[196:199], v146 offset:50176
	ds_read_b128 v[200:203], v146 offset:51200
	ds_read_b128 v[208:211], v146 offset:52224
	ds_read_b128 v[212:215], v146 offset:53248
	ds_read_b128 v[216:219], v146 offset:54272
	ds_read_b128 v[220:223], v146 offset:55296
	ds_read_b128 v[224:227], v146 offset:56320
	global_load_lds_dwordx4 v204, s[10:11]
	s_mov_b32 m0, s52
	s_nop 0
	global_load_lds_dwordx4 v205, s[10:11]
	s_barrier
	s_waitcnt lgkmcnt(0)
	s_setprio 1
	s_waitcnt lgkmcnt(0)
	v_mfma_f32_16x16x32_bf16 v[60:63], v[164:167], v[180:183], v[60:63]
	v_mfma_f32_16x16x32_bf16 v[56:59], v[172:175], v[180:183], v[56:59]
	v_mfma_f32_16x16x32_bf16 v[52:55], v[164:167], v[200:203], v[52:55]
	v_mfma_f32_16x16x32_bf16 v[48:51], v[172:175], v[200:203], v[48:51]
	v_mfma_f32_16x16x32_bf16 v[44:47], v[164:167], v[212:215], v[44:47]
	v_mfma_f32_16x16x32_bf16 v[40:43], v[172:175], v[212:215], v[40:43]
	v_mfma_f32_16x16x32_bf16 v[36:39], v[164:167], v[220:223], v[36:39]
	v_mfma_f32_16x16x32_bf16 v[32:35], v[172:175], v[220:223], v[32:35]
	v_mfma_f32_16x16x32_bf16 v[60:63], v[168:171], v[196:199], v[60:63]
	v_mfma_f32_16x16x32_bf16 v[56:59], v[176:179], v[196:199], v[56:59]
	v_mfma_f32_16x16x32_bf16 v[52:55], v[168:171], v[208:211], v[52:55]
	v_mfma_f32_16x16x32_bf16 v[48:51], v[176:179], v[208:211], v[48:51]
	v_mfma_f32_16x16x32_bf16 v[44:47], v[168:171], v[216:219], v[44:47]
	v_mfma_f32_16x16x32_bf16 v[40:43], v[176:179], v[216:219], v[40:43]
	v_mfma_f32_16x16x32_bf16 v[36:39], v[168:171], v[224:227], v[36:39]
	v_mfma_f32_16x16x32_bf16 v[32:35], v[176:179], v[224:227], v[32:35]
	s_setprio 0
	s_barrier
	s_mov_b32 m0, s53
	s_nop 0
	global_load_lds_dwordx4 v204, s[18:19]
	s_mov_b32 m0, s54
	s_nop 0
	global_load_lds_dwordx4 v205, s[18:19]
	s_waitcnt vmcnt(6)
	s_barrier
	s_setprio 1
	v_mfma_f32_16x16x32_bf16 v[28:31], v[228:231], v[180:183], v[28:31]
	v_mfma_f32_16x16x32_bf16 v[24:27], v[236:239], v[180:183], v[24:27]
	v_mfma_f32_16x16x32_bf16 v[20:23], v[228:231], v[200:203], v[20:23]
	v_mfma_f32_16x16x32_bf16 v[16:19], v[236:239], v[200:203], v[16:19]
	v_mfma_f32_16x16x32_bf16 v[12:15], v[228:231], v[212:215], v[12:15]
	v_mfma_f32_16x16x32_bf16 v[8:11], v[236:239], v[212:215], v[8:11]
	v_mfma_f32_16x16x32_bf16 v[4:7], v[228:231], v[220:223], v[4:7]
	v_mfma_f32_16x16x32_bf16 v[0:3], v[236:239], v[220:223], v[0:3]
	v_mfma_f32_16x16x32_bf16 v[28:31], v[232:235], v[196:199], v[28:31]
	v_mfma_f32_16x16x32_bf16 v[24:27], v[240:243], v[196:199], v[24:27]
	v_mfma_f32_16x16x32_bf16 v[20:23], v[232:235], v[208:211], v[20:23]
	v_mfma_f32_16x16x32_bf16 v[16:19], v[240:243], v[208:211], v[16:19]
	v_mfma_f32_16x16x32_bf16 v[12:15], v[232:235], v[216:219], v[12:15]
	v_mfma_f32_16x16x32_bf16 v[8:11], v[240:243], v[216:219], v[8:11]
	v_mfma_f32_16x16x32_bf16 v[4:7], v[232:235], v[224:227], v[4:7]
	v_mfma_f32_16x16x32_bf16 v[0:3], v[240:243], v[224:227], v[0:3]
	s_setprio 0
	s_add_i32 s22, s22, 2
	v_add_u32_e32 v142, 0x100, v142
	s_cmp_lt_u32 s22, 12
	v_add_u32_e32 v96, 0x100, v96
	s_barrier

; #define WAIT_V(n) asm volatile("s_waitcnt vmcnt(%0)" ::"n"(n) : "memory")
; #define WAIT_L(n) asm volatile("s_waitcnt lgkmcnt(%0)" ::"n"(n) : "memory")
; #define SBAR() __builtin_amdgcn_sched_barrier(0)
; #define STAGE(P, base, kt) do { _Pragma("unroll") for (int _i = 0; _i < 2; ++_i)                                        \
;       __builtin_amdgcn_global_load_lds((const unsigned*)((base) + (size_t)(sOff[_i] + (unsigned)(kt) * (BK * 2))),        \
;                                        (unsigned*)((P) + wid * 1024 + _i * 8192), 16, 0, 0); } while (0)
; #define LDA(dst, b, h) _Pragma("unroll") for (int m = 0; m < 4; ++m) _Pragma("unroll") for (int k = 0; k < 2; ++k) \
;       dst[m][k] = *(const bf16x8*)(SA(b, h) + aoff + (m * 2048 + k * 1024))
; #define LDB(dst, b, h) _Pragma("unroll") for (int n = 0; n < 2; ++n) _Pragma("unroll") for (int k = 0; k < 2; ++k) \
;       dst[n][k] = *(const bf16x8*)(SB(b, h) + boff + (n * 256 + k * 1024))
; #define BAR __builtin_amdgcn_s_barrier()
; template <int EPI, int N, int K>
; __device__ __forceinline__ void phase_gemm(const Params& p, const u16* __restrict__ A, const u16* __restrict__ Bt, int nM, char* shm,
;                            u16* __restrict__ outp, float* __restrict__ rowss) {
;     ...
;   for (;;) {
;     const char* A1 = A0 + (size_t)128 * K * 2;
;     const char* B1p = B0p + (size_t)128 * K * 2;
;     f32x4 acc[2][2][4][2] = {};
;     bf16x8 At[4][2], B0[2][2], B1[2][2];
;     if (wr == 1) BAR;
;     WAIT_V(0); BAR;
;     BAR;
;     for (int t = 0; t < nt - 2; t += 2) {
;       LDB(B0, 0, 0); SBAR(); LDA(At, 0, 0); STAGE(SA(1, 1), A1, t + 1);
;       WAIT_L(8); BAR; WAIT_L(0); MMA(0, 0, At, B0); BAR; SBAR();
;       LDB(B1, 0, 1); STAGE(SB(0, 0), B0p, t + 2);
;       BAR; WAIT_L(0); MMA(0, 1, At, B1); BAR;
;       LDA(At, 0, 1); STAGE(SA(0, 0), A0, t + 2);
;       BAR; WAIT_L(0); MMA(1, 0, At, B0); BAR; SBAR();
;       STAGE(SB(0, 1), B1p, t + 2);
;       WAIT_V(6); BAR; MMA(1, 1, At, B1); BAR;
.LBB0_516:
	s_add_u32 s4, s12, 0xb0000
	s_addc_u32 s5, s13, 0
	s_waitcnt vmcnt(0)
	s_add_u32 s18, s10, 0xb0000
	s_addc_u32 s19, s11, 0
	s_mov_b32 s58, -2
	v_mov_b32_e32 v96, v150
	v_mov_b32_e32 v142, v149
	s_waitcnt lgkmcnt(0)
	s_barrier
	s_barrier
	v_or_b32_e32 v143, 0x10000, v146
	v_add_u32_e32 v145, 0x10100, v146
	v_add_u32_e32 v144, 0x10400, v146
	ds_read_b128 v[156:159], v143
	ds_read_b128 v[160:163], v144
	v_add_u32_e32 v151, 0x10500, v146
	ds_read_b128 v[164:167], v145
	ds_read_b128 v[168:171], v151
	v_add_u32_e32 v204, v148, v96
	s_add_i32 s60, s25, 0xc000
	v_add_u32_e32 v152, 0x80, v204
	s_mov_b32 m0, s60
	v_add_u32_e32 v205, v148, v142
	s_add_i32 s59, s25, 0xe000
	ds_read_b128 v[172:175], v147
	ds_read_b128 v[176:179], v147 offset:1024
	ds_read_b128 v[180:183], v147 offset:2048
	ds_read_b128 v[196:199], v147 offset:3072
	ds_read_b128 v[200:203], v147 offset:4096
	ds_read_b128 v[208:211], v147 offset:5120
	ds_read_b128 v[212:215], v147 offset:6144
	ds_read_b128 v[216:219], v147 offset:7168
	global_load_lds_dwordx4 v152, s[4:5]
	v_add_u32_e32 v152, 0x80, v205
	s_mov_b32 m0, s59
	s_nop 0
	global_load_lds_dwordx4 v152, s[4:5]
	s_waitcnt lgkmcnt(8)
	s_barrier
	s_waitcnt lgkmcnt(0)
	s_setprio 1
	s_waitcnt lgkmcnt(0)
	v_mfma_f32_16x16x32_bf16 v[126:129], v[156:159], v[172:175], 0
	v_mfma_f32_16x16x32_bf16 v[122:125], v[164:167], v[172:175], 0
	v_mfma_f32_16x16x32_bf16 v[118:121], v[156:159], v[180:183], 0
	v_mfma_f32_16x16x32_bf16 v[114:117], v[164:167], v[180:183], 0
	v_mfma_f32_16x16x32_bf16 v[110:113], v[156:159], v[200:203], 0
	v_mfma_f32_16x16x32_bf16 v[106:109], v[164:167], v[200:203], 0
	v_mfma_f32_16x16x32_bf16 v[102:105], v[156:159], v[212:215], 0
	v_mfma_f32_16x16x32_bf16 v[98:101], v[164:167], v[212:215], 0
	v_mfma_f32_16x16x32_bf16 v[126:129], v[160:163], v[176:179], v[126:129]
	v_mfma_f32_16x16x32_bf16 v[122:125], v[168:171], v[176:179], v[122:125]
	v_mfma_f32_16x16x32_bf16 v[118:121], v[160:163], v[196:199], v[118:121]
	v_mfma_f32_16x16x32_bf16 v[114:117], v[168:171], v[196:199], v[114:117]
	v_mfma_f32_16x16x32_bf16 v[110:113], v[160:163], v[208:211], v[110:113]
	v_mfma_f32_16x16x32_bf16 v[106:109], v[168:171], v[208:211], v[106:109]
	v_mfma_f32_16x16x32_bf16 v[102:105], v[160:163], v[216:219], v[102:105]
	v_mfma_f32_16x16x32_bf16 v[98:101], v[168:171], v[216:219], v[98:101]
	s_setprio 0
	s_barrier
	s_mov_b32 m0, s28
	v_or_b32_e32 v152, 0x14000, v146
	v_add_u32_e32 v154, 0x14100, v146
	v_add_u32_e32 v206, 0x100, v204
	v_add_u32_e32 v153, 0x14400, v146
	ds_read_b128 v[220:223], v152
	ds_read_b128 v[224:227], v153
	v_add_u32_e32 v155, 0x14500, v146
	ds_read_b128 v[228:231], v154
	ds_read_b128 v[232:235], v155
	global_load_lds_dwordx4 v206, s[10:11]
	v_add_u32_e32 v207, 0x100, v205
	s_mov_b32 m0, s29
	s_nop 0
	global_load_lds_dwordx4 v207, s[10:11]
	s_barrier
	s_waitcnt lgkmcnt(0)
	s_setprio 1
	s_waitcnt lgkmcnt(0)
	v_mfma_f32_16x16x32_bf16 v[92:95], v[220:223], v[172:175], 0
	v_mfma_f32_16x16x32_bf16 v[88:91], v[228:231], v[172:175], 0
	v_mfma_f32_16x16x32_bf16 v[84:87], v[220:223], v[180:183], 0
	v_mfma_f32_16x16x32_bf16 v[80:83], v[228:231], v[180:183], 0
	v_mfma_f32_16x16x32_bf16 v[76:79], v[220:223], v[200:203], 0
	v_mfma_f32_16x16x32_bf16 v[72:75], v[228:231], v[200:203], 0
	v_mfma_f32_16x16x32_bf16 v[68:71], v[220:223], v[212:215], 0
	v_mfma_f32_16x16x32_bf16 v[64:67], v[228:231], v[212:215], 0
	v_mfma_f32_16x16x32_bf16 v[92:95], v[224:227], v[176:179], v[92:95]
	v_mfma_f32_16x16x32_bf16 v[88:91], v[232:235], v[176:179], v[88:91]
	v_mfma_f32_16x16x32_bf16 v[84:87], v[224:227], v[196:199], v[84:87]
	v_mfma_f32_16x16x32_bf16 v[80:83], v[232:235], v[196:199], v[80:83]
	v_mfma_f32_16x16x32_bf16 v[76:79], v[224:227], v[208:211], v[76:79]
	v_mfma_f32_16x16x32_bf16 v[72:75], v[232:235], v[208:211], v[72:75]
	v_mfma_f32_16x16x32_bf16 v[68:71], v[224:227], v[216:219], v[68:71]
	v_mfma_f32_16x16x32_bf16 v[64:67], v[232:235], v[216:219], v[64:67]
	s_setprio 0
	s_mov_b32 m0, s25
	s_barrier
	ds_read_b128 v[172:175], v147 offset:16384
	ds_read_b128 v[176:179], v147 offset:17408
	ds_read_b128 v[180:183], v147 offset:18432
	ds_read_b128 v[196:199], v147 offset:19456
	ds_read_b128 v[200:203], v147 offset:20480
	ds_read_b128 v[208:211], v147 offset:21504
	ds_read_b128 v[212:215], v147 offset:22528
	ds_read_b128 v[216:219], v147 offset:23552
	global_load_lds_dwordx4 v206, s[12:13]
	s_mov_b32 m0, s26
	s_nop 0
	global_load_lds_dwordx4 v207, s[12:13]
	s_barrier
	s_waitcnt lgkmcnt(0)
	s_setprio 1
	s_waitcnt lgkmcnt(0)
	v_mfma_f32_16x16x32_bf16 v[60:63], v[156:159], v[172:175], 0
	v_mfma_f32_16x16x32_bf16 v[56:59], v[164:167], v[172:175], 0
	v_mfma_f32_16x16x32_bf16 v[52:55], v[156:159], v[180:183], 0
	v_mfma_f32_16x16x32_bf16 v[48:51], v[164:167], v[180:183], 0
	v_mfma_f32_16x16x32_bf16 v[44:47], v[156:159], v[200:203], 0
	v_mfma_f32_16x16x32_bf16 v[40:43], v[164:167], v[200:203], 0
	v_mfma_f32_16x16x32_bf16 v[36:39], v[156:159], v[212:215], 0
	v_mfma_f32_16x16x32_bf16 v[32:35], v[164:167], v[212:215], 0
	v_mfma_f32_16x16x32_bf16 v[60:63], v[160:163], v[176:179], v[60:63]
	v_mfma_f32_16x16x32_bf16 v[56:59], v[168:171], v[176:179], v[56:59]
	v_mfma_f32_16x16x32_bf16 v[52:55], v[160:163], v[196:199], v[52:55]
	v_mfma_f32_16x16x32_bf16 v[48:51], v[168:171], v[196:199], v[48:51]
	v_mfma_f32_16x16x32_bf16 v[44:47], v[160:163], v[208:211], v[44:47]
	v_mfma_f32_16x16x32_bf16 v[40:43], v[168:171], v[208:211], v[40:43]
	v_mfma_f32_16x16x32_bf16 v[36:39], v[160:163], v[216:219], v[36:39]
	v_mfma_f32_16x16x32_bf16 v[32:35], v[168:171], v[216:219], v[32:35]
	s_setprio 0
	s_barrier
; #define WAIT_V(n) asm volatile("s_waitcnt vmcnt(%0)" ::"n"(n) : "memory")
; #define WAIT_L(n) asm volatile("s_waitcnt lgkmcnt(%0)" ::"n"(n) : "memory")
; #define SBAR() __builtin_amdgcn_sched_barrier(0)
; #define STAGE(P, base, kt) do { _Pragma("unroll") for (int _i = 0; _i < 2; ++_i)                                        \
;       __builtin_amdgcn_global_load_lds((const unsigned*)((base) + (size_t)(sOff[_i] + (unsigned)(kt) * (BK * 2))),        \
;                                        (unsigned*)((P) + wid * 1024 + _i * 8192), 16, 0, 0); } while (0)
; #define LDA(dst, b, h) _Pragma("unroll") for (int m = 0; m < 4; ++m) _Pragma("unroll") for (int k = 0; k < 2; ++k) \
;       dst[m][k] = *(const bf16x8*)(SA(b, h) + aoff + (m * 2048 + k * 1024))
; #define LDB(dst, b, h) _Pragma("unroll") for (int n = 0; n < 2; ++n) _Pragma("unroll") for (int k = 0; k < 2; ++k) \
;       dst[n][k] = *(const bf16x8*)(SB(b, h) + boff + (n * 256 + k * 1024))
; #define BAR __builtin_amdgcn_s_barrier()
; template <int EPI, int N, int K>
; __device__ __forceinline__ void phase_gemm(const Params& p, const u16* __restrict__ A, const u16* __restrict__ Bt, int nM, char* shm,
;                            u16* __restrict__ outp, float* __restrict__ rowss) {
;     ...
;       WAIT_V(6); BAR; MMA(1, 1, At, B1); BAR;
;       LDB(B0, 1, 0); SBAR(); LDA(At, 1, 0); STAGE(SA(0, 1), A1, t + 2);
;       WAIT_L(8); BAR; WAIT_L(0); MMA(0, 0, At, B0); BAR; SBAR();
;       LDB(B1, 1, 1); STAGE(SB(1, 0), B0p, t + 3);
;       BAR; WAIT_L(0); MMA(0, 1, At, B1); BAR;
	s_mov_b32 m0, s30
	s_nop 0
	global_load_lds_dwordx4 v206, s[18:19]
	s_mov_b32 m0, s31
	s_nop 0
	global_load_lds_dwordx4 v207, s[18:19]
	s_waitcnt vmcnt(6)
	s_barrier
	s_setprio 1
	v_mfma_f32_16x16x32_bf16 v[28:31], v[220:223], v[172:175], 0
	v_mfma_f32_16x16x32_bf16 v[24:27], v[228:231], v[172:175], 0
	v_mfma_f32_16x16x32_bf16 v[20:23], v[220:223], v[180:183], 0
	v_mfma_f32_16x16x32_bf16 v[16:19], v[228:231], v[180:183], 0
	v_mfma_f32_16x16x32_bf16 v[12:15], v[220:223], v[200:203], 0
	v_mfma_f32_16x16x32_bf16 v[8:11], v[228:231], v[200:203], 0
	v_mfma_f32_16x16x32_bf16 v[4:7], v[220:223], v[212:215], 0
	v_mfma_f32_16x16x32_bf16 v[0:3], v[228:231], v[212:215], 0
	v_mfma_f32_16x16x32_bf16 v[28:31], v[224:227], v[176:179], v[28:31]
	v_mfma_f32_16x16x32_bf16 v[24:27], v[232:235], v[176:179], v[24:27]
	v_mfma_f32_16x16x32_bf16 v[20:23], v[224:227], v[196:199], v[20:23]
	v_mfma_f32_16x16x32_bf16 v[16:19], v[232:235], v[196:199], v[16:19]
	v_mfma_f32_16x16x32_bf16 v[12:15], v[224:227], v[208:211], v[12:15]
	v_mfma_f32_16x16x32_bf16 v[8:11], v[232:235], v[208:211], v[8:11]
	v_mfma_f32_16x16x32_bf16 v[4:7], v[224:227], v[216:219], v[4:7]
	v_mfma_f32_16x16x32_bf16 v[0:3], v[232:235], v[216:219], v[0:3]
	s_setprio 0
	v_or_b32_e32 v156, 0x18000, v146
	v_add_u32_e32 v158, 0x18100, v146
	s_barrier
	v_add_u32_e32 v157, 0x18400, v146
	ds_read_b128 v[164:167], v156
	ds_read_b128 v[168:171], v157
	v_add_u32_e32 v159, 0x18500, v146
	ds_read_b128 v[172:175], v158
	ds_read_b128 v[176:179], v159
	s_mov_b32 m0, s33
	ds_read_b128 v[180:183], v147 offset:32768
	ds_read_b128 v[196:199], v147 offset:33792
	ds_read_b128 v[200:203], v147 offset:34816
	ds_read_b128 v[208:211], v147 offset:35840
	ds_read_b128 v[212:215], v147 offset:36864
	ds_read_b128 v[216:219], v147 offset:37888
	ds_read_b128 v[220:223], v147 offset:38912
	ds_read_b128 v[224:227], v147 offset:39936
	global_load_lds_dwordx4 v206, s[4:5]
	s_mov_b32 m0, s35
	s_nop 0
	global_load_lds_dwordx4 v207, s[4:5]
	s_waitcnt lgkmcnt(8)
	s_barrier
	s_waitcnt lgkmcnt(0)
	s_setprio 1
	s_waitcnt lgkmcnt(0)
	v_mfma_f32_16x16x32_bf16 v[126:129], v[164:167], v[180:183], v[126:129]
	v_mfma_f32_16x16x32_bf16 v[122:125], v[172:175], v[180:183], v[122:125]
	v_mfma_f32_16x16x32_bf16 v[118:121], v[164:167], v[200:203], v[118:121]
	v_mfma_f32_16x16x32_bf16 v[114:117], v[172:175], v[200:203], v[114:117]
	v_mfma_f32_16x16x32_bf16 v[110:113], v[164:167], v[212:215], v[110:113]
	v_mfma_f32_16x16x32_bf16 v[106:109], v[172:175], v[212:215], v[106:109]
	v_mfma_f32_16x16x32_bf16 v[102:105], v[164:167], v[220:223], v[102:105]
	v_mfma_f32_16x16x32_bf16 v[98:101], v[172:175], v[220:223], v[98:101]
	v_mfma_f32_16x16x32_bf16 v[126:129], v[168:171], v[196:199], v[126:129]
	v_mfma_f32_16x16x32_bf16 v[122:125], v[176:179], v[196:199], v[122:125]
	v_mfma_f32_16x16x32_bf16 v[118:121], v[168:171], v[208:211], v[118:121]
	v_mfma_f32_16x16x32_bf16 v[114:117], v[176:179], v[208:211], v[114:117]
	v_mfma_f32_16x16x32_bf16 v[110:113], v[168:171], v[216:219], v[110:113]
	v_mfma_f32_16x16x32_bf16 v[106:109], v[176:179], v[216:219], v[106:109]
	v_mfma_f32_16x16x32_bf16 v[102:105], v[168:171], v[224:227], v[102:105]
	v_mfma_f32_16x16x32_bf16 v[98:101], v[176:179], v[224:227], v[98:101]
	s_setprio 0
	s_barrier
	s_mov_b32 m0, s92
	v_or_b32_e32 v160, 0x1c000, v146
	v_add_u32_e32 v162, 0x1c100, v146
	v_add_u32_e32 v204, 0x180, v204
	v_add_u32_e32 v161, 0x1c400, v146
	ds_read_b128 v[228:231], v160
	ds_read_b128 v[232:235], v161
	v_add_u32_e32 v163, 0x1c500, v146
	ds_read_b128 v[236:239], v162
	ds_read_b128 v[240:243], v163
	global_load_lds_dwordx4 v204, s[10:11]
	v_add_u32_e32 v205, 0x180, v205
	s_mov_b32 m0, s93
	s_nop 0
	global_load_lds_dwordx4 v205, s[10:11]
	s_barrier
; #define WAIT_V(n) asm volatile("s_waitcnt vmcnt(%0)" ::"n"(n) : "memory")
; #define WAIT_L(n) asm volatile("s_waitcnt lgkmcnt(%0)" ::"n"(n) : "memory")
; #define SBAR() __builtin_amdgcn_sched_barrier(0)
; #define STAGE(P, base, kt) do { _Pragma("unroll") for (int _i = 0; _i < 2; ++_i)                                        \
;       __builtin_amdgcn_global_load_lds((const unsigned*)((base) + (size_t)(sOff[_i] + (unsigned)(kt) * (BK * 2))),        \
;                                        (unsigned*)((P) + wid * 1024 + _i * 8192), 16, 0, 0); } while (0)
; #define LDA(dst, b, h) _Pragma("unroll") for (int m = 0; m < 4; ++m) _Pragma("unroll") for (int k = 0; k < 2; ++k) \
;       dst[m][k] = *(const bf16x8*)(SA(b, h) + aoff + (m * 2048 + k * 1024))
; #define BAR __builtin_amdgcn_s_barrier()
; template <int EPI, int N, int K>
; __device__ __forceinline__ void phase_gemm(const Params& p, const u16* __restrict__ A, const u16* __restrict__ Bt, int nM, char* shm,
;                            u16* __restrict__ outp, float* __restrict__ rowss) {
;     ...
;       BAR; WAIT_L(0); MMA(0, 1, At, B1); BAR;
;       LDA(At, 1, 1); STAGE(SA(1, 0), A0, t + 3);
;       BAR; WAIT_L(0); MMA(1, 0, At, B0); BAR; SBAR();
;       STAGE(SB(1, 1), B1p, t + 3);
;       WAIT_V(6); BAR; MMA(1, 1, At, B1); BAR;
;     }
	s_waitcnt lgkmcnt(0)
	s_setprio 1
	s_waitcnt lgkmcnt(0)
	v_mfma_f32_16x16x32_bf16 v[92:95], v[228:231], v[180:183], v[92:95]
	v_mfma_f32_16x16x32_bf16 v[88:91], v[236:239], v[180:183], v[88:91]
	v_mfma_f32_16x16x32_bf16 v[84:87], v[228:231], v[200:203], v[84:87]
	v_mfma_f32_16x16x32_bf16 v[80:83], v[236:239], v[200:203], v[80:83]
	v_mfma_f32_16x16x32_bf16 v[76:79], v[228:231], v[212:215], v[76:79]
	v_mfma_f32_16x16x32_bf16 v[72:75], v[236:239], v[212:215], v[72:75]
	v_mfma_f32_16x16x32_bf16 v[68:71], v[228:231], v[220:223], v[68:71]
	v_mfma_f32_16x16x32_bf16 v[64:67], v[236:239], v[220:223], v[64:67]
	v_mfma_f32_16x16x32_bf16 v[92:95], v[232:235], v[196:199], v[92:95]
	v_mfma_f32_16x16x32_bf16 v[88:91], v[240:243], v[196:199], v[88:91]
	v_mfma_f32_16x16x32_bf16 v[84:87], v[232:235], v[208:211], v[84:87]
	v_mfma_f32_16x16x32_bf16 v[80:83], v[240:243], v[208:211], v[80:83]
	v_mfma_f32_16x16x32_bf16 v[76:79], v[232:235], v[216:219], v[76:79]
	v_mfma_f32_16x16x32_bf16 v[72:75], v[240:243], v[216:219], v[72:75]
	v_mfma_f32_16x16x32_bf16 v[68:71], v[232:235], v[224:227], v[68:71]
	v_mfma_f32_16x16x32_bf16 v[64:67], v[240:243], v[224:227], v[64:67]
	s_setprio 0
	s_mov_b32 m0, s94
	s_barrier
	ds_read_b128 v[180:183], v147 offset:49152
	ds_read_b128 v[196:199], v147 offset:50176
	ds_read_b128 v[200:203], v147 offset:51200
	ds_read_b128 v[208:211], v147 offset:52224
	ds_read_b128 v[212:215], v147 offset:53248
	ds_read_b128 v[216:219], v147 offset:54272
	ds_read_b128 v[220:223], v147 offset:55296
	ds_read_b128 v[224:227], v147 offset:56320
	global_load_lds_dwordx4 v204, s[12:13]
	s_mov_b32 m0, s52
	s_nop 0
	global_load_lds_dwordx4 v205, s[12:13]
	s_barrier
	s_waitcnt lgkmcnt(0)
	s_setprio 1
	s_waitcnt lgkmcnt(0)
	v_mfma_f32_16x16x32_bf16 v[60:63], v[164:167], v[180:183], v[60:63]
	v_mfma_f32_16x16x32_bf16 v[56:59], v[172:175], v[180:183], v[56:59]
	v_mfma_f32_16x16x32_bf16 v[52:55], v[164:167], v[200:203], v[52:55]
	v_mfma_f32_16x16x32_bf16 v[48:51], v[172:175], v[200:203], v[48:51]
	v_mfma_f32_16x16x32_bf16 v[44:47], v[164:167], v[212:215], v[44:47]
	v_mfma_f32_16x16x32_bf16 v[40:43], v[172:175], v[212:215], v[40:43]
	v_mfma_f32_16x16x32_bf16 v[36:39], v[164:167], v[220:223], v[36:39]
	v_mfma_f32_16x16x32_bf16 v[32:35], v[172:175], v[220:223], v[32:35]
	v_mfma_f32_16x16x32_bf16 v[60:63], v[168:171], v[196:199], v[60:63]
	v_mfma_f32_16x16x32_bf16 v[56:59], v[176:179], v[196:199], v[56:59]
	v_mfma_f32_16x16x32_bf16 v[52:55], v[168:171], v[208:211], v[52:55]
	v_mfma_f32_16x16x32_bf16 v[48:51], v[176:179], v[208:211], v[48:51]
	v_mfma_f32_16x16x32_bf16 v[44:47], v[168:171], v[216:219], v[44:47]
	v_mfma_f32_16x16x32_bf16 v[40:43], v[176:179], v[216:219], v[40:43]
	v_mfma_f32_16x16x32_bf16 v[36:39], v[168:171], v[224:227], v[36:39]
	v_mfma_f32_16x16x32_bf16 v[32:35], v[176:179], v[224:227], v[32:35]
	s_setprio 0
	s_barrier
	s_mov_b32 m0, s53
	s_nop 0
	global_load_lds_dwordx4 v204, s[18:19]
	s_mov_b32 m0, s54
	s_nop 0
	global_load_lds_dwordx4 v205, s[18:19]
	s_waitcnt vmcnt(6)
	s_barrier
	s_setprio 1
	v_mfma_f32_16x16x32_bf16 v[28:31], v[228:231], v[180:183], v[28:31]
	v_mfma_f32_16x16x32_bf16 v[24:27], v[236:239], v[180:183], v[24:27]
	v_mfma_f32_16x16x32_bf16 v[20:23], v[228:231], v[200:203], v[20:23]
	v_mfma_f32_16x16x32_bf16 v[16:19], v[236:239], v[200:203], v[16:19]
	v_mfma_f32_16x16x32_bf16 v[12:15], v[228:231], v[212:215], v[12:15]
	v_mfma_f32_16x16x32_bf16 v[8:11], v[236:239], v[212:215], v[8:11]
	v_mfma_f32_16x16x32_bf16 v[4:7], v[228:231], v[220:223], v[4:7]
	v_mfma_f32_16x16x32_bf16 v[0:3], v[236:239], v[220:223], v[0:3]
	v_mfma_f32_16x16x32_bf16 v[28:31], v[232:235], v[196:199], v[28:31]
	v_mfma_f32_16x16x32_bf16 v[24:27], v[240:243], v[196:199], v[24:27]
	v_mfma_f32_16x16x32_bf16 v[20:23], v[232:235], v[208:211], v[20:23]
	v_mfma_f32_16x16x32_bf16 v[16:19], v[240:243], v[208:211], v[16:19]
	v_mfma_f32_16x16x32_bf16 v[12:15], v[232:235], v[216:219], v[12:15]
	v_mfma_f32_16x16x32_bf16 v[8:11], v[240:243], v[216:219], v[8:11]
	v_mfma_f32_16x16x32_bf16 v[4:7], v[232:235], v[224:227], v[4:7]
	v_mfma_f32_16x16x32_bf16 v[0:3], v[240:243], v[224:227], v[0:3]
	s_setprio 0
	s_add_i32 s58, s58, 2
	v_add_u32_e32 v142, 0x100, v142
	s_cmp_lt_u32 s58, 40
	v_add_u32_e32 v96, 0x100, v96
	s_barrier

; #define WAIT_V(n) asm volatile("s_waitcnt vmcnt(%0)" ::"n"(n) : "memory")
; #define WAIT_L(n) asm volatile("s_waitcnt lgkmcnt(%0)" ::"n"(n) : "memory")
; #define SBAR() __builtin_amdgcn_sched_barrier(0)
; #define STAGE(P, base, kt) do { _Pragma("unroll") for (int _i = 0; _i < 2; ++_i)                                        \
;       __builtin_amdgcn_global_load_lds((const unsigned*)((base) + (size_t)(sOff[_i] + (unsigned)(kt) * (BK * 2))),        \
;                                        (unsigned*)((P) + wid * 1024 + _i * 8192), 16, 0, 0); } while (0)
; #define LDA(dst, b, h) _Pragma("unroll") for (int m = 0; m < 4; ++m) _Pragma("unroll") for (int k = 0; k < 2; ++k) \
;       dst[m][k] = *(const bf16x8*)(SA(b, h) + aoff + (m * 2048 + k * 1024))
; #define LDB(dst, b, h) _Pragma("unroll") for (int n = 0; n < 2; ++n) _Pragma("unroll") for (int k = 0; k < 2; ++k) \
;       dst[n][k] = *(const bf16x8*)(SB(b, h) + boff + (n * 256 + k * 1024))
; #define BAR __builtin_amdgcn_s_barrier()
; template <int EPI, int N, int K>
; __device__ __forceinline__ void phase_gemm(const Params& p, const u16* __restrict__ A, const u16* __restrict__ Bt, int nM, char* shm,
;                            u16* __restrict__ outp, float* __restrict__ rowss) {
;     ...
;   for (;;) {
;     const char* A1 = A0 + (size_t)128 * K * 2;
;     const char* B1p = B0p + (size_t)128 * K * 2;
;     f32x4 acc[2][2][4][2] = {};
;     bf16x8 At[4][2], B0[2][2], B1[2][2];
;     if (wr == 1) BAR;
;     WAIT_V(0); BAR;
;     BAR;
;     for (int t = 0; t < nt - 2; t += 2) {
;       LDB(B0, 0, 0); SBAR(); LDA(At, 0, 0); STAGE(SA(1, 1), A1, t + 1);
;       WAIT_L(8); BAR; WAIT_L(0); MMA(0, 0, At, B0); BAR; SBAR();
;       LDB(B1, 0, 1); STAGE(SB(0, 0), B0p, t + 2);
;       BAR; WAIT_L(0); MMA(0, 1, At, B1); BAR;
;       LDA(At, 0, 1); STAGE(SA(0, 0), A0, t + 2);
;       BAR; WAIT_L(0); MMA(1, 0, At, B0); BAR; SBAR();
;       STAGE(SB(0, 1), B1p, t + 2);
;       WAIT_V(6); BAR; MMA(1, 1, At, B1); BAR;
.LBB0_552:
	s_add_u32 s14, s8, 0x40000
	s_addc_u32 s15, s9, 0
	s_waitcnt vmcnt(0)
	s_add_u32 s16, s6, 0x40000
	s_addc_u32 s17, s7, 0
	s_mov_b32 s53, -2
	v_mov_b32_e32 v140, v146
	v_mov_b32_e32 v141, v145
	s_barrier
	s_barrier
	v_or_b32_e32 v147, 0x10000, v143
	v_add_u32_e32 v149, 0x10100, v143
	v_add_u32_e32 v148, 0x10400, v143
	ds_read_b128 v[156:159], v147
	ds_read_b128 v[160:163], v148
	v_add_u32_e32 v150, 0x10500, v143
	ds_read_b128 v[164:167], v149
	ds_read_b128 v[168:171], v150
	v_add_u32_e32 v196, v142, v140
	s_add_i32 s55, s19, 0xc000
	v_add_u32_e32 v151, 0x80, v196
	s_mov_b32 m0, s55
	v_add_u32_e32 v197, v142, v141
	s_add_i32 s54, s19, 0xe000
	ds_read_b128 v[172:175], v144
	ds_read_b128 v[176:179], v144 offset:1024
	ds_read_b128 v[180:183], v144 offset:2048
	ds_read_b128 v[208:211], v144 offset:3072
	ds_read_b128 v[212:215], v144 offset:4096
	ds_read_b128 v[216:219], v144 offset:5120
	ds_read_b128 v[220:223], v144 offset:6144
	ds_read_b128 v[224:227], v144 offset:7168
	global_load_lds_dwordx4 v151, s[14:15]
	v_add_u32_e32 v151, 0x80, v197
	s_mov_b32 m0, s54
	s_nop 0
	global_load_lds_dwordx4 v151, s[14:15]
	s_waitcnt lgkmcnt(8)
	s_barrier
	s_waitcnt lgkmcnt(0)
	s_setprio 1
	s_waitcnt lgkmcnt(0)
	v_mfma_f32_16x16x32_bf16 v[126:129], v[156:159], v[172:175], 0
	v_mfma_f32_16x16x32_bf16 v[122:125], v[164:167], v[172:175], 0
	v_mfma_f32_16x16x32_bf16 v[118:121], v[156:159], v[180:183], 0
	v_mfma_f32_16x16x32_bf16 v[114:117], v[164:167], v[180:183], 0
	v_mfma_f32_16x16x32_bf16 v[110:113], v[156:159], v[212:215], 0
	v_mfma_f32_16x16x32_bf16 v[106:109], v[164:167], v[212:215], 0
	v_mfma_f32_16x16x32_bf16 v[102:105], v[156:159], v[220:223], 0
	v_mfma_f32_16x16x32_bf16 v[98:101], v[164:167], v[220:223], 0
	v_mfma_f32_16x16x32_bf16 v[126:129], v[160:163], v[176:179], v[126:129]
	v_mfma_f32_16x16x32_bf16 v[122:125], v[168:171], v[176:179], v[122:125]
	v_mfma_f32_16x16x32_bf16 v[118:121], v[160:163], v[208:211], v[118:121]
	v_mfma_f32_16x16x32_bf16 v[114:117], v[168:171], v[208:211], v[114:117]
	v_mfma_f32_16x16x32_bf16 v[110:113], v[160:163], v[216:219], v[110:113]
	v_mfma_f32_16x16x32_bf16 v[106:109], v[168:171], v[216:219], v[106:109]
	v_mfma_f32_16x16x32_bf16 v[102:105], v[160:163], v[224:227], v[102:105]
	v_mfma_f32_16x16x32_bf16 v[98:101], v[168:171], v[224:227], v[98:101]
	s_setprio 0
	s_barrier
	s_mov_b32 m0, s23
	v_or_b32_e32 v151, 0x14000, v143
	v_add_u32_e32 v153, 0x14100, v143
	v_add_u32_e32 v198, 0x100, v196
	v_add_u32_e32 v152, 0x14400, v143
	ds_read_b128 v[228:231], v151
	ds_read_b128 v[232:235], v152
	v_add_u32_e32 v154, 0x14500, v143
	ds_read_b128 v[236:239], v153
	ds_read_b128 v[240:243], v154
	global_load_lds_dwordx4 v198, s[6:7]
	v_add_u32_e32 v199, 0x100, v197
	s_mov_b32 m0, s92
	s_nop 0
	global_load_lds_dwordx4 v199, s[6:7]
	s_barrier
	s_waitcnt lgkmcnt(0)
	s_setprio 1
	s_waitcnt lgkmcnt(0)
	v_mfma_f32_16x16x32_bf16 v[92:95], v[228:231], v[172:175], 0
	v_mfma_f32_16x16x32_bf16 v[88:91], v[236:239], v[172:175], 0
	v_mfma_f32_16x16x32_bf16 v[84:87], v[228:231], v[180:183], 0
	v_mfma_f32_16x16x32_bf16 v[80:83], v[236:239], v[180:183], 0
	v_mfma_f32_16x16x32_bf16 v[76:79], v[228:231], v[212:215], 0
	v_mfma_f32_16x16x32_bf16 v[72:75], v[236:239], v[212:215], 0
	v_mfma_f32_16x16x32_bf16 v[68:71], v[228:231], v[220:223], 0
	v_mfma_f32_16x16x32_bf16 v[64:67], v[236:239], v[220:223], 0
	v_mfma_f32_16x16x32_bf16 v[92:95], v[232:235], v[176:179], v[92:95]
	v_mfma_f32_16x16x32_bf16 v[88:91], v[240:243], v[176:179], v[88:91]
	v_mfma_f32_16x16x32_bf16 v[84:87], v[232:235], v[208:211], v[84:87]
	v_mfma_f32_16x16x32_bf16 v[80:83], v[240:243], v[208:211], v[80:83]
	v_mfma_f32_16x16x32_bf16 v[76:79], v[232:235], v[216:219], v[76:79]
	v_mfma_f32_16x16x32_bf16 v[72:75], v[240:243], v[216:219], v[72:75]
	v_mfma_f32_16x16x32_bf16 v[68:71], v[232:235], v[224:227], v[68:71]
	v_mfma_f32_16x16x32_bf16 v[64:67], v[240:243], v[224:227], v[64:67]
	s_setprio 0
	s_mov_b32 m0, s19
	s_barrier
	ds_read_b128 v[172:175], v144 offset:16384
	ds_read_b128 v[176:179], v144 offset:17408
	ds_read_b128 v[180:183], v144 offset:18432
	ds_read_b128 v[208:211], v144 offset:19456
	ds_read_b128 v[212:215], v144 offset:20480
	ds_read_b128 v[216:219], v144 offset:21504
	ds_read_b128 v[220:223], v144 offset:22528
	ds_read_b128 v[224:227], v144 offset:23552
	global_load_lds_dwordx4 v198, s[8:9]
	s_mov_b32 m0, s22
	s_nop 0
	global_load_lds_dwordx4 v199, s[8:9]
	s_barrier
	s_waitcnt lgkmcnt(0)
	s_setprio 1
	s_waitcnt lgkmcnt(0)
	v_mfma_f32_16x16x32_bf16 v[60:63], v[156:159], v[172:175], 0
	v_mfma_f32_16x16x32_bf16 v[56:59], v[164:167], v[172:175], 0
	v_mfma_f32_16x16x32_bf16 v[52:55], v[156:159], v[180:183], 0
	v_mfma_f32_16x16x32_bf16 v[48:51], v[164:167], v[180:183], 0
	v_mfma_f32_16x16x32_bf16 v[44:47], v[156:159], v[212:215], 0
	v_mfma_f32_16x16x32_bf16 v[40:43], v[164:167], v[212:215], 0
	v_mfma_f32_16x16x32_bf16 v[36:39], v[156:159], v[220:223], 0
	v_mfma_f32_16x16x32_bf16 v[32:35], v[164:167], v[220:223], 0
	v_mfma_f32_16x16x32_bf16 v[60:63], v[160:163], v[176:179], v[60:63]
	v_mfma_f32_16x16x32_bf16 v[56:59], v[168:171], v[176:179], v[56:59]
	v_mfma_f32_16x16x32_bf16 v[52:55], v[160:163], v[208:211], v[52:55]
	v_mfma_f32_16x16x32_bf16 v[48:51], v[168:171], v[208:211], v[48:51]
	v_mfma_f32_16x16x32_bf16 v[44:47], v[160:163], v[216:219], v[44:47]
	v_mfma_f32_16x16x32_bf16 v[40:43], v[168:171], v[216:219], v[40:43]
	v_mfma_f32_16x16x32_bf16 v[36:39], v[160:163], v[224:227], v[36:39]
	v_mfma_f32_16x16x32_bf16 v[32:35], v[168:171], v[224:227], v[32:35]
	s_setprio 0
	s_barrier
	s_mov_b32 m0, s94
	s_nop 0
	global_load_lds_dwordx4 v198, s[16:17]
	s_mov_b32 m0, s95
	s_nop 0
	global_load_lds_dwordx4 v199, s[16:17]
	s_waitcnt vmcnt(6)
	s_barrier
; #define WAIT_V(n) asm volatile("s_waitcnt vmcnt(%0)" ::"n"(n) : "memory")
; #define WAIT_L(n) asm volatile("s_waitcnt lgkmcnt(%0)" ::"n"(n) : "memory")
; #define SBAR() __builtin_amdgcn_sched_barrier(0)
; #define STAGE(P, base, kt) do { _Pragma("unroll") for (int _i = 0; _i < 2; ++_i)                                        \
;       __builtin_amdgcn_global_load_lds((const unsigned*)((base) + (size_t)(sOff[_i] + (unsigned)(kt) * (BK * 2))),        \
;                                        (unsigned*)((P) + wid * 1024 + _i * 8192), 16, 0, 0); } while (0)
; #define LDA(dst, b, h) _Pragma("unroll") for (int m = 0; m < 4; ++m) _Pragma("unroll") for (int k = 0; k < 2; ++k) \
;       dst[m][k] = *(const bf16x8*)(SA(b, h) + aoff + (m * 2048 + k * 1024))
; #define LDB(dst, b, h) _Pragma("unroll") for (int n = 0; n < 2; ++n) _Pragma("unroll") for (int k = 0; k < 2; ++k) \
;       dst[n][k] = *(const bf16x8*)(SB(b, h) + boff + (n * 256 + k * 1024))
; #define BAR __builtin_amdgcn_s_barrier()
; template <int EPI, int N, int K>
; __device__ __forceinline__ void phase_gemm(const Params& p, const u16* __restrict__ A, const u16* __restrict__ Bt, int nM, char* shm,
;                            u16* __restrict__ outp, float* __restrict__ rowss) {
;     ...
;       WAIT_V(6); BAR; MMA(1, 1, At, B1); BAR;
;       LDB(B0, 1, 0); SBAR(); LDA(At, 1, 0); STAGE(SA(0, 1), A1, t + 2);
;       WAIT_L(8); BAR; WAIT_L(0); MMA(0, 0, At, B0); BAR; SBAR();
;       LDB(B1, 1, 1); STAGE(SB(1, 0), B0p, t + 3);
;       BAR; WAIT_L(0); MMA(0, 1, At, B1); BAR;
	s_setprio 1
	v_mfma_f32_16x16x32_bf16 v[28:31], v[228:231], v[172:175], 0
	v_mfma_f32_16x16x32_bf16 v[24:27], v[236:239], v[172:175], 0
	v_mfma_f32_16x16x32_bf16 v[20:23], v[228:231], v[180:183], 0
	v_mfma_f32_16x16x32_bf16 v[16:19], v[236:239], v[180:183], 0
	v_mfma_f32_16x16x32_bf16 v[12:15], v[228:231], v[212:215], 0
	v_mfma_f32_16x16x32_bf16 v[8:11], v[236:239], v[212:215], 0
	v_mfma_f32_16x16x32_bf16 v[4:7], v[228:231], v[220:223], 0
	v_mfma_f32_16x16x32_bf16 v[0:3], v[236:239], v[220:223], 0
	v_mfma_f32_16x16x32_bf16 v[28:31], v[232:235], v[176:179], v[28:31]
	v_mfma_f32_16x16x32_bf16 v[24:27], v[240:243], v[176:179], v[24:27]
	v_mfma_f32_16x16x32_bf16 v[20:23], v[232:235], v[208:211], v[20:23]
	v_mfma_f32_16x16x32_bf16 v[16:19], v[240:243], v[208:211], v[16:19]
	v_mfma_f32_16x16x32_bf16 v[12:15], v[232:235], v[216:219], v[12:15]
	v_mfma_f32_16x16x32_bf16 v[8:11], v[240:243], v[216:219], v[8:11]
	v_mfma_f32_16x16x32_bf16 v[4:7], v[232:235], v[224:227], v[4:7]
	v_mfma_f32_16x16x32_bf16 v[0:3], v[240:243], v[224:227], v[0:3]
	s_setprio 0
	v_or_b32_e32 v155, 0x18000, v143
	v_add_u32_e32 v157, 0x18100, v143
	s_barrier
	v_add_u32_e32 v156, 0x18400, v143
	ds_read_b128 v[164:167], v155
	ds_read_b128 v[168:171], v156
	v_add_u32_e32 v158, 0x18500, v143
	ds_read_b128 v[172:175], v157
	ds_read_b128 v[176:179], v158
	s_mov_b32 m0, s96
	ds_read_b128 v[180:183], v144 offset:32768
	ds_read_b128 v[208:211], v144 offset:33792
	ds_read_b128 v[212:215], v144 offset:34816
	ds_read_b128 v[216:219], v144 offset:35840
	ds_read_b128 v[220:223], v144 offset:36864
	ds_read_b128 v[224:227], v144 offset:37888
	ds_read_b128 v[228:231], v144 offset:38912
	ds_read_b128 v[232:235], v144 offset:39936
	global_load_lds_dwordx4 v198, s[14:15]
	s_mov_b32 m0, s33
	s_nop 0
	global_load_lds_dwordx4 v199, s[14:15]
	s_waitcnt lgkmcnt(8)
	s_barrier
	s_waitcnt lgkmcnt(0)
	s_setprio 1
	s_waitcnt lgkmcnt(0)
	v_mfma_f32_16x16x32_bf16 v[126:129], v[164:167], v[180:183], v[126:129]
	v_mfma_f32_16x16x32_bf16 v[122:125], v[172:175], v[180:183], v[122:125]
	v_mfma_f32_16x16x32_bf16 v[118:121], v[164:167], v[212:215], v[118:121]
	v_mfma_f32_16x16x32_bf16 v[114:117], v[172:175], v[212:215], v[114:117]
	v_mfma_f32_16x16x32_bf16 v[110:113], v[164:167], v[220:223], v[110:113]
	v_mfma_f32_16x16x32_bf16 v[106:109], v[172:175], v[220:223], v[106:109]
	v_mfma_f32_16x16x32_bf16 v[102:105], v[164:167], v[228:231], v[102:105]
	v_mfma_f32_16x16x32_bf16 v[98:101], v[172:175], v[228:231], v[98:101]
	v_mfma_f32_16x16x32_bf16 v[126:129], v[168:171], v[208:211], v[126:129]
	v_mfma_f32_16x16x32_bf16 v[122:125], v[176:179], v[208:211], v[122:125]
	v_mfma_f32_16x16x32_bf16 v[118:121], v[168:171], v[216:219], v[118:121]
	v_mfma_f32_16x16x32_bf16 v[114:117], v[176:179], v[216:219], v[114:117]
	v_mfma_f32_16x16x32_bf16 v[110:113], v[168:171], v[224:227], v[110:113]
	v_mfma_f32_16x16x32_bf16 v[106:109], v[176:179], v[224:227], v[106:109]
	v_mfma_f32_16x16x32_bf16 v[102:105], v[168:171], v[232:235], v[102:105]
	v_mfma_f32_16x16x32_bf16 v[98:101], v[176:179], v[232:235], v[98:101]
	s_setprio 0
	s_barrier
	s_mov_b32 m0, s35
	v_or_b32_e32 v159, 0x1c000, v143
	v_add_u32_e32 v161, 0x1c100, v143
	v_add_u32_e32 v163, 0x180, v196
	v_add_u32_e32 v160, 0x1c400, v143
	ds_read_b128 v[236:239], v159
	ds_read_b128 v[240:243], v160
	v_add_u32_e32 v162, 0x1c500, v143
	ds_read_b128 v[244:247], v161
	ds_read_b128 v[248:251], v162
	global_load_lds_dwordx4 v163, s[6:7]
	v_add_u32_e32 v196, 0x180, v197
	s_mov_b32 m0, s93
	s_nop 0
	global_load_lds_dwordx4 v196, s[6:7]
	s_barrier
; #define WAIT_V(n) asm volatile("s_waitcnt vmcnt(%0)" ::"n"(n) : "memory")
; #define WAIT_L(n) asm volatile("s_waitcnt lgkmcnt(%0)" ::"n"(n) : "memory")
; #define SBAR() __builtin_amdgcn_sched_barrier(0)
; #define STAGE(P, base, kt) do { _Pragma("unroll") for (int _i = 0; _i < 2; ++_i)                                        \
;       __builtin_amdgcn_global_load_lds((const unsigned*)((base) + (size_t)(sOff[_i] + (unsigned)(kt) * (BK * 2))),        \
;                                        (unsigned*)((P) + wid * 1024 + _i * 8192), 16, 0, 0); } while (0)
; #define LDA(dst, b, h) _Pragma("unroll") for (int m = 0; m < 4; ++m) _Pragma("unroll") for (int k = 0; k < 2; ++k) \
;       dst[m][k] = *(const bf16x8*)(SA(b, h) + aoff + (m * 2048 + k * 1024))
; #define BAR __builtin_amdgcn_s_barrier()
; template <int EPI, int N, int K>
; __device__ __forceinline__ void phase_gemm(const Params& p, const u16* __restrict__ A, const u16* __restrict__ Bt, int nM, char* shm,
;                            u16* __restrict__ outp, float* __restrict__ rowss) {
;     ...
;       BAR; WAIT_L(0); MMA(0, 1, At, B1); BAR;
;       LDA(At, 1, 1); STAGE(SA(1, 0), A0, t + 3);
;       BAR; WAIT_L(0); MMA(1, 0, At, B0); BAR; SBAR();
;       STAGE(SB(1, 1), B1p, t + 3);
;       WAIT_V(6); BAR; MMA(1, 1, At, B1); BAR;
;     }
	s_waitcnt lgkmcnt(0)
	s_setprio 1
	s_waitcnt lgkmcnt(0)
	v_mfma_f32_16x16x32_bf16 v[92:95], v[236:239], v[180:183], v[92:95]
	v_mfma_f32_16x16x32_bf16 v[88:91], v[244:247], v[180:183], v[88:91]
	v_mfma_f32_16x16x32_bf16 v[84:87], v[236:239], v[212:215], v[84:87]
	v_mfma_f32_16x16x32_bf16 v[80:83], v[244:247], v[212:215], v[80:83]
	v_mfma_f32_16x16x32_bf16 v[76:79], v[236:239], v[220:223], v[76:79]
	v_mfma_f32_16x16x32_bf16 v[72:75], v[244:247], v[220:223], v[72:75]
	v_mfma_f32_16x16x32_bf16 v[68:71], v[236:239], v[228:231], v[68:71]
	v_mfma_f32_16x16x32_bf16 v[64:67], v[244:247], v[228:231], v[64:67]
	v_mfma_f32_16x16x32_bf16 v[92:95], v[240:243], v[208:211], v[92:95]
	v_mfma_f32_16x16x32_bf16 v[88:91], v[248:251], v[208:211], v[88:91]
	v_mfma_f32_16x16x32_bf16 v[84:87], v[240:243], v[216:219], v[84:87]
	v_mfma_f32_16x16x32_bf16 v[80:83], v[248:251], v[216:219], v[80:83]
	v_mfma_f32_16x16x32_bf16 v[76:79], v[240:243], v[224:227], v[76:79]
	v_mfma_f32_16x16x32_bf16 v[72:75], v[248:251], v[224:227], v[72:75]
	v_mfma_f32_16x16x32_bf16 v[68:71], v[240:243], v[232:235], v[68:71]
	v_mfma_f32_16x16x32_bf16 v[64:67], v[248:251], v[232:235], v[64:67]
	s_setprio 0
	s_mov_b32 m0, s24
	s_barrier
	ds_read_b128 v[180:183], v144 offset:49152
	ds_read_b128 v[208:211], v144 offset:50176
	ds_read_b128 v[212:215], v144 offset:51200
	ds_read_b128 v[216:219], v144 offset:52224
	ds_read_b128 v[220:223], v144 offset:53248
	ds_read_b128 v[224:227], v144 offset:54272
	ds_read_b128 v[228:231], v144 offset:55296
	ds_read_b128 v[232:235], v144 offset:56320
	global_load_lds_dwordx4 v163, s[8:9]
	s_mov_b32 m0, s25
	s_nop 0
	global_load_lds_dwordx4 v196, s[8:9]
	s_barrier
	s_waitcnt lgkmcnt(0)
	s_setprio 1
	s_waitcnt lgkmcnt(0)
	v_mfma_f32_16x16x32_bf16 v[60:63], v[164:167], v[180:183], v[60:63]
	v_mfma_f32_16x16x32_bf16 v[56:59], v[172:175], v[180:183], v[56:59]
	v_mfma_f32_16x16x32_bf16 v[52:55], v[164:167], v[212:215], v[52:55]
	v_mfma_f32_16x16x32_bf16 v[48:51], v[172:175], v[212:215], v[48:51]
	v_mfma_f32_16x16x32_bf16 v[44:47], v[164:167], v[220:223], v[44:47]
	v_mfma_f32_16x16x32_bf16 v[40:43], v[172:175], v[220:223], v[40:43]
	v_mfma_f32_16x16x32_bf16 v[36:39], v[164:167], v[228:231], v[36:39]
	v_mfma_f32_16x16x32_bf16 v[32:35], v[172:175], v[228:231], v[32:35]
	v_mfma_f32_16x16x32_bf16 v[60:63], v[168:171], v[208:211], v[60:63]
	v_mfma_f32_16x16x32_bf16 v[56:59], v[176:179], v[208:211], v[56:59]
	v_mfma_f32_16x16x32_bf16 v[52:55], v[168:171], v[216:219], v[52:55]
	v_mfma_f32_16x16x32_bf16 v[48:51], v[176:179], v[216:219], v[48:51]
	v_mfma_f32_16x16x32_bf16 v[44:47], v[168:171], v[224:227], v[44:47]
	v_mfma_f32_16x16x32_bf16 v[40:43], v[176:179], v[224:227], v[40:43]
	v_mfma_f32_16x16x32_bf16 v[36:39], v[168:171], v[232:235], v[36:39]
	v_mfma_f32_16x16x32_bf16 v[32:35], v[176:179], v[232:235], v[32:35]
	s_setprio 0
	s_barrier
	s_mov_b32 m0, s26
	s_nop 0
	global_load_lds_dwordx4 v163, s[16:17]
	s_mov_b32 m0, s27
	s_nop 0
	global_load_lds_dwordx4 v196, s[16:17]
	s_waitcnt vmcnt(6)
	s_barrier
	s_setprio 1
	v_mfma_f32_16x16x32_bf16 v[28:31], v[236:239], v[180:183], v[28:31]
	v_mfma_f32_16x16x32_bf16 v[24:27], v[244:247], v[180:183], v[24:27]
	v_mfma_f32_16x16x32_bf16 v[20:23], v[236:239], v[212:215], v[20:23]
	v_mfma_f32_16x16x32_bf16 v[16:19], v[244:247], v[212:215], v[16:19]
	v_mfma_f32_16x16x32_bf16 v[12:15], v[236:239], v[220:223], v[12:15]
	v_mfma_f32_16x16x32_bf16 v[8:11], v[244:247], v[220:223], v[8:11]
	v_mfma_f32_16x16x32_bf16 v[4:7], v[236:239], v[228:231], v[4:7]
	v_mfma_f32_16x16x32_bf16 v[0:3], v[244:247], v[228:231], v[0:3]
	v_mfma_f32_16x16x32_bf16 v[28:31], v[240:243], v[208:211], v[28:31]
	v_mfma_f32_16x16x32_bf16 v[24:27], v[248:251], v[208:211], v[24:27]
	v_mfma_f32_16x16x32_bf16 v[20:23], v[240:243], v[216:219], v[20:23]
	v_mfma_f32_16x16x32_bf16 v[16:19], v[248:251], v[216:219], v[16:19]
	v_mfma_f32_16x16x32_bf16 v[12:15], v[240:243], v[224:227], v[12:15]
	v_mfma_f32_16x16x32_bf16 v[8:11], v[248:251], v[224:227], v[8:11]
	v_mfma_f32_16x16x32_bf16 v[4:7], v[240:243], v[232:235], v[4:7]
	v_mfma_f32_16x16x32_bf16 v[0:3], v[248:251], v[232:235], v[0:3]
	s_setprio 0
	s_add_i32 s53, s53, 2
	v_add_u32_e32 v141, 0x100, v141
	s_cmp_lt_u32 s53, 12
	v_add_u32_e32 v140, 0x100, v140
	s_barrier
